# plus lean 2-hop grid barrier (XCD-local arrive, leader wbl2 + global count polled by all) and hand-pipelined EpiGate epilogue (3 row units of loads in flight, counted vmcnt)
# speedup vs baseline: 1.0076x; 1.0049x over previous
; #define LAS __attribute__((address_space(3)))
; __device__ __forceinline__ unsigned xb_add(unsigned* p, unsigned v) { return __hip_atomic_fetch_add(p, v, __ATOMIC_RELAXED, __HIP_MEMORY_SCOPE_AGENT); }
; __device__ __forceinline__ unsigned xb_xcc_id() { return (unsigned)__builtin_amdgcn_s_getreg((3 << 11) | 20) & 0xFu; }
; __device__ __forceinline__ KP kparams() { unsigned long long k = (unsigned long long)__builtin_amdgcn_kernarg_segment_ptr(); asm volatile("" : "+s"(k)); return (KP)k; }
; __device__ __forceinline__ XcdBarrier xcd_barrier_post(unsigned* bar, volatile LAS unsigned* st) {
;     XcdBarrier b; b.bar = bar; b.x = xb_xcc_id(); b.st = st;
;     if (threadIdx.x == 0) (void)xb_add(&bar[XB_XCNT(b.x)], 1u);
;     return b;
; __global__ void __launch_bounds__(512, 2) fwd_megakernel(Params p_) {
;     extern __shared__ __attribute__((aligned(16))) unsigned char smem[];
;     cg::grid_group grid = cg::this_grid();
;     LAS unsigned char* lds = (LAS unsigned char*)smem;
;     const int G = gridDim.x, bid = blockIdx.x;
;     const int NGW = G * 8;
;     const size_t NGT = (size_t)G * 512;
;     volatile LAS unsigned* xst = (volatile LAS unsigned*)(lds + 131072 + 4000);
;     if (threadIdx.x < 2) xst[threadIdx.x] = 0u;
;     __syncthreads();
;     const XcdBarrier xbar = xcd_barrier_post((unsigned*)(kparams()->ws + OFF_BAR), xst);
_Z14fwd_megakernel6Params:
	s_mov_b32 s98, 0
	s_load_dwordx2 s[50:51], s[0:1], 0xe0
	s_load_dword s33, s[0:1], 0xe8
	s_add_u32 s16, s0, 0xe0
	v_writelane_b32 v253, s0, 0
	v_and_b32_e32 v246, 0x3ff, v0
	s_addc_u32 s17, s1, 0
	v_writelane_b32 v253, s1, 1
	v_cmp_gt_u32_e32 vcc, 2, v246
	s_and_saveexec_b64 s[6:7], vcc
	v_lshl_add_u32 v1, v246, 2, 0
	v_add_u32_e32 v1, 0x20fa0, v1
	v_mov_b32_e32 v2, 0
	ds_write_b32 v1, v2
	s_or_b64 exec, exec, s[6:7]
	v_readlane_b32 s4, v253, 0
	v_readlane_b32 s5, v253, 1
	s_waitcnt lgkmcnt(0)
	s_barrier
	s_load_dwordx2 s[6:7], s[4:5], 0xd0
	s_getreg_b32 s4, hwreg(HW_REG_XCC_ID, 0, 4)
	s_waitcnt lgkmcnt(0)
	s_add_u32 s0, s6, 0x4dd2a000
	s_addc_u32 s1, s7, 0
	v_writelane_b32 v253, s0, 2
	s_nop 1
	v_writelane_b32 v253, s1, 3
	s_and_b32 s0, s4, 15
	v_writelane_b32 v253, s0, 4
	v_cmp_eq_u32_e64 s[0:1], 0, v246
	s_nop 1
	v_writelane_b32 v253, s0, 5
	s_nop 1
	v_writelane_b32 v253, s1, 6
	s_and_saveexec_b64 s[8:9], s[0:1]
	s_cbranch_execz .LBB0_5
	s_mov_b64 s[4:5], exec
	v_mbcnt_lo_u32_b32 v1, s4, 0
	v_mbcnt_hi_u32_b32 v1, s5, v1
	v_cmp_eq_u32_e32 vcc, 0, v1
	s_and_b64 s[6:7], exec, vcc
	s_mov_b64 exec, s[6:7]
	s_cbranch_execz .LBB0_5
	v_readlane_b32 s0, v253, 4
	s_lshl_b32 s6, s0, 8
	s_bcnt1_i32_b64 s4, s[4:5]
	v_readlane_b32 s0, v253, 2
	v_mov_b32_e32 v1, s6
	v_mov_b32_e32 v2, s4
	v_readlane_b32 s1, v253, 3
	s_nop 4
	global_atomic_add v1, v2, s[0:1] offset:1024

; __device__ __forceinline__ unsigned xb_ld(unsigned* p)              { return __hip_atomic_load(p, __ATOMIC_RELAXED, __HIP_MEMORY_SCOPE_AGENT); }
; __device__ __forceinline__ unsigned xb_add(unsigned* p, unsigned v) { return __hip_atomic_fetch_add(p, v, __ATOMIC_RELAXED, __HIP_MEMORY_SCOPE_AGENT); }
; #define XB_SPIN(cond, bar) do { unsigned _sp = 0; while (cond) { __builtin_amdgcn_s_sleep(1); \
;     if ((++_sp & 255u) == 0u) { if (xb_ld(&(bar)[XB_TMO])) break; if (_sp > XB_SPIN_CAP) { atomicAdd(&(bar)[XB_TMO], 1u); break; } } } } while (0)
; __device__ __forceinline__ void xcd_barrier(const XcdBarrier& b) {
;     asm volatile("s_waitcnt vmcnt(0)" ::: "memory");
;     __syncthreads();
;     if (threadIdx.x == 0) {
;         unsigned long long bar_ = (unsigned long long)b.bar; unsigned bx = b.x;
;         asm volatile("" : "+s"(bar_), "+s"(bx));
;         unsigned* bar = (unsigned*)bar_;
;         __builtin_amdgcn_s_waitcnt(0);
;         unsigned nloc = b.st[0], nx = b.st[1];
;         if (nloc == 0u) { xcd_barrier_complete(bar, bx, nloc, nx); b.st[0] = nloc; b.st[1] = nx; }
;         const unsigned old = xb_add(&bar[XB_XSUB(bx)], 1u);
;         const unsigned gen = old / nloc;
;         if (old + 1u == (gen + 1u) * nloc) {
;             __builtin_amdgcn_fence(__ATOMIC_RELEASE, "agent");
;             asm volatile("s_waitcnt vmcnt(0)" ::: "memory");
;             const unsigned og = xb_add(&bar[XB_TOP], 1u);
;             const unsigned tg = og / nx;
;             if (og + 1u == (tg + 1u) * nx) xb_add(&bar[XB_TOPGEN], 1u);
;             else XB_SPIN(xb_ld(&bar[XB_TOPGEN]) == tg, bar);
;             __builtin_amdgcn_fence(__ATOMIC_ACQUIRE, "agent");
;             xb_add(&bar[XB_XGEN(bx)], 1u);
;             asm volatile("s_waitcnt vmcnt(0)" ::: "memory");
;         } else {
;             XB_SPIN(xb_ld(&bar[XB_XGEN(bx)]) == gen, bar);
;             __builtin_amdgcn_fence(__ATOMIC_ACQUIRE, "agent");
;             asm volatile("s_waitcnt vmcnt(0)" ::: "memory");
;         }
;     }
;     __syncthreads();
; }
.LBB0_152:
	s_waitcnt vmcnt(0)
	v_readlane_b32 s0, v253, 5
	v_readlane_b32 s1, v253, 6
	s_barrier
	s_and_saveexec_b64 s[4:5], s[0:1]
	s_cbranch_execz .LBB0_196
	s_add_i32 s98, s98, 1
	v_mov_b32_e32 v0, 0x20fa0
	ds_read_b64 v[2:3], v0
	v_readlane_b32 s10, v253, 2
	v_readlane_b32 s11, v253, 3
	v_readlane_b32 s12, v253, 4
	s_lshl_b32 s12, s12, 6
	s_add_i32 s12, s12, 0x3600
	s_add_u32 s14, s10, s12
	s_addc_u32 s15, s11, 0
	s_add_u32 s10, s10, 0x3b00
	s_addc_u32 s11, s11, 0
	v_mov_b64_e32 v[4:5], s[14:15]
	v_mov_b32_e32 v8, 1
	flat_atomic_add v6, v[4:5], v8 sc0
	s_waitcnt vmcnt(0) lgkmcnt(0)
	v_readfirstlane_b32 s12, v6
	v_readfirstlane_b32 s13, v2
	v_readfirstlane_b32 s14, v3
	s_mul_i32 s13, s13, s98
	s_mul_i32 s14, s14, s98
	s_add_i32 s12, s12, 1
	v_mov_b64_e32 v[4:5], s[10:11]
	s_cmp_lg_u32 s12, s13
	s_cbranch_scc1 .Lgb_poll_1
	buffer_wbl2 sc1
	s_waitcnt vmcnt(0) lgkmcnt(0)
	flat_atomic_add v7, v[4:5], v8 sc0
	s_waitcnt vmcnt(0) lgkmcnt(0)
.Lgb_poll_1:
	s_mov_b32 s16, 0
.Lgb_loop_1:
	flat_load_dword v6, v[4:5] sc1
	s_waitcnt vmcnt(0) lgkmcnt(0)
	v_readfirstlane_b32 s12, v6
	s_cmp_ge_u32 s12, s14
	s_cbranch_scc1 .Lgb_done_1
	s_sleep 1
	s_add_i32 s16, s16, 1
	s_cmp_lt_u32 s16, 0x4000
	s_cbranch_scc1 .Lgb_loop_1
.Lgb_done_1:
	buffer_inv sc1
	s_waitcnt vmcnt(0)
.LBB0_196:
	s_or_b64 exec, exec, s[4:5]
	v_readlane_b32 s8, v253, 7
	v_readlane_b32 s9, v253, 8
	s_cmpk_lt_i32 s8, 0x1500
	s_cselect_b64 s[2:3], -1, 0
	s_lshr_b32 s1, s9, 29
	s_add_i32 s1, s8, s1
	s_ashr_i32 s4, s1, 3
	s_and_b32 s1, s1, -8
	s_sub_i32 s1, s8, s1
	v_writelane_b32 v253, s2, 11
	s_cmpk_lt_i32 s8, 0x400
	s_mul_i32 s0, s51, s46
	v_writelane_b32 v253, s3, 12
	s_cselect_b64 s[2:3], -1, 0
	v_writelane_b32 v253, s2, 13
	s_cmpk_lt_i32 s8, 0x100
	s_movk_i32 s6, 0x2a1
	v_writelane_b32 v253, s3, 14
	s_cselect_b64 s[2:3], -1, 0
	v_writelane_b32 v253, s2, 15
	s_mul_i32 s0, s0, s33
	s_mul_i32 s5, s1, 33
	v_writelane_b32 v253, s3, 16
	s_lshl_b32 s2, s1, 7
	s_lshl_b32 s3, s1, 5
	s_cmp_lt_i32 s1, 0
	s_cselect_b32 s6, s6, 0x2a0
	v_writelane_b32 v253, s0, 17
	s_mul_i32 s0, s1, 0x81
	s_mul_i32 s1, s1, s6
	s_cselect_b32 s2, s0, s2
	s_cselect_b32 s5, s5, s3
	s_add_i32 s1, s1, s4
	s_mul_hi_i32 s0, s1, 0x30c30c31
	s_lshr_b32 s3, s0, 31
	s_ashr_i32 s0, s0, 5
	s_add_i32 s0, s0, s3
	s_mul_i32 s3, s0, 0xa8
	s_sub_i32 s1, s1, s3
	s_lshl_b32 s6, s0, 2
	s_bfe_u32 s0, s1, 0x2001d
	s_add_i32 s3, s1, s0
	s_sext_i32_i16 s7, s3
	s_and_b32 s3, s3, 0xfffc
	s_sub_i32 s1, s1, s3
	s_sext_i32_i16 s1, s1
	s_add_i32 s12, s6, s1
	s_add_i32 s1, s2, s4
	s_ashr_i32 s2, s1, 31
	s_lshr_b32 s2, s2, 27
	s_add_i32 s2, s1, s2
	s_ashr_i32 s3, s2, 5
	s_and_b32 s2, s2, 0xffe0
	s_sub_i32 s1, s1, s2
	s_bfe_i32 s2, s1, 0x80000
	s_bfe_u32 s2, s2, 0x2000d
	s_add_i32 s6, s1, s2
	s_bfe_i32 s2, s6, 0x80000
	s_and_b32 s6, s6, 0xfc
	s_sub_i32 s1, s1, s6
	s_lshl_b32 s3, s3, 2
	s_sext_i32_i8 s1, s1
	s_add_i32 s14, s3, s1
	s_lshr_b32 s0, s7, 2
	s_ashr_i32 s13, s7, 2
	s_sext_i32_i16 s7, s2
	s_ashr_i32 s15, s14, 31
	s_lshr_b32 s2, s7, 2
	s_ashr_i32 s16, s7, 2
	s_lshl_b64 s[6:7], s[14:15], 20
	s_add_i32 s1, s5, s4
	v_writelane_b32 v253, s6, 18
	s_bfe_i64 s[2:3], s[2:3], 0x100000
	s_ashr_i32 s4, s1, 31
	v_writelane_b32 v253, s7, 19
	s_lshl_b64 s[6:7], s[2:3], 19
	s_lshr_b32 s4, s4, 29
	v_writelane_b32 v253, s6, 20
	s_add_i32 s4, s1, s4
	s_ashr_i32 s5, s4, 3
	v_writelane_b32 v253, s7, 21
	s_lshl_b64 s[6:7], s[14:15], 19
	s_and_b32 s4, s4, 0xfff8
	v_writelane_b32 v253, s6, 22
	s_sub_i32 s1, s1, s4
	s_bfe_i32 s4, s1, 0x80000
	v_writelane_b32 v253, s7, 23
	s_lshl_b64 s[6:7], s[2:3], 18
	v_writelane_b32 v253, s6, 24
	s_bfe_u32 s4, s4, 0x2000d
	s_lshl_b32 s5, s5, 2
	v_writelane_b32 v253, s7, 25
	s_add_i32 s6, s1, s4
	s_bfe_i32 s4, s6, 0x80000
	s_and_b32 s6, s6, 0xfc
	s_sub_i32 s1, s1, s6
	s_sext_i32_i16 s7, s4
	s_sext_i32_i8 s1, s1
	s_add_i32 s18, s5, s1
	s_ashr_i32 s1, s7, 2
	v_writelane_b32 v253, s1, 26
	s_mov_b32 s6, s18
	s_lshr_b32 s4, s7, 2
	s_ashr_i32 s19, s18, 31
	v_writelane_b32 v253, s6, 27
	s_bfe_i64 s[4:5], s[4:5], 0x100000
	s_lshl_b64 s[4:5], s[4:5], 19
	v_writelane_b32 v253, s7, 28
	s_lshl_b64 s[6:7], s[18:19], 19
	v_writelane_b32 v253, s6, 29
	s_bfe_i64 s[0:1], s[0:1], 0x100000
	s_lshl_b64 s[0:1], s[0:1], 20
	v_writelane_b32 v253, s7, 30
	v_writelane_b32 v253, s4, 31
	s_mov_b32 s6, s12
	s_mul_hi_i32 s11, s46, 0x600
	v_writelane_b32 v253, s5, 32
	s_mov_b32 s4, s14
	v_writelane_b32 v253, s4, 33
	s_mul_i32 s10, s46, 0x600
	s_waitcnt lgkmcnt(0)
	v_writelane_b32 v253, s5, 34
	s_lshl_b64 s[4:5], s[14:15], 17
	v_writelane_b32 v253, s4, 35
	s_barrier
;     __device__ __forceinline__ void init(AccMut acc, const Unit& u, int wr, int wc, int fr, int fq) const { acc_bias(acc, bias + u.pn * 256 + wc * 32 + 8 * fq); }
;     __device__ __forceinline__ void init(AccMut acc, const Unit&, int, int, int, int) const { acc_zero(acc); }
;     __device__ __forceinline__ void init(AccMut acc, const Unit&, int, int, int, int) const { acc_zero(acc); }
;     __device__ __forceinline__ void init(AccMut acc, const Unit& u, int wr, int wc, int fr, int fq) const { acc_bias(acc, bias + u.pn * 256 + wc * 32 + 8 * fq); }
;     __device__ __forceinline__ void init(AccMut acc, const Unit&, int, int, int, int) const { acc_zero(acc); }
;     __device__ __forceinline__ void init(AccMut acc, const Unit&, int, int, int, int) const { acc_zero(acc); }
; __device__ __forceinline__ unsigned xb_ld(unsigned* p)              { return __hip_atomic_load(p, __ATOMIC_RELAXED, __HIP_MEMORY_SCOPE_AGENT); }
; __device__ __forceinline__ unsigned xb_add(unsigned* p, unsigned v) { return __hip_atomic_fetch_add(p, v, __ATOMIC_RELAXED, __HIP_MEMORY_SCOPE_AGENT); }
; #define XB_SPIN(cond, bar) do { unsigned _sp = 0; while (cond) { __builtin_amdgcn_s_sleep(1); \
;     if ((++_sp & 255u) == 0u) { if (xb_ld(&(bar)[XB_TMO])) break; if (_sp > XB_SPIN_CAP) { atomicAdd(&(bar)[XB_TMO], 1u); break; } } } } while (0)
; __device__ __forceinline__ void xcd_barrier(const XcdBarrier& b) {
;     ...
;             if (og + 1u == (tg + 1u) * nx) xb_add(&bar[XB_TOPGEN], 1u);
;             else XB_SPIN(xb_ld(&bar[XB_TOPGEN]) == tg, bar);
;             __builtin_amdgcn_fence(__ATOMIC_ACQUIRE, "agent");
;             xb_add(&bar[XB_XGEN(bx)], 1u);
;             asm volatile("s_waitcnt vmcnt(0)" ::: "memory");
; __global__ void __launch_bounds__(512, 2) fwd_megakernel(Params p_) {
;     ...
;     for (int l = 0; l < DEPTH; ++l) {
;         if (PHM & 4)
;         {
;             TID_VARS
;             KARGS
;             pg8::Gemm g{XB, wt + WT_IN, M_TOK, NIN, DM, DM, DM}; pg8::StaticOrder S; S.init(M_TOK, NIN, G, bid);
;             EpiIn E{H, BIASP + (size_t)l * NIN};
;             pg8::gemm_phase(lds, g, S, E, tid);
	s_nop 0
	v_writelane_b32 v253, s5, 36
	s_lshl_b64 s[4:5], s[2:3], 17
	v_writelane_b32 v253, s4, 37
	s_lshl_b64 s[2:3], s[2:3], 20
	s_mov_b32 s73, 0
	v_writelane_b32 v253, s5, 38
	v_writelane_b32 v253, s13, 39
	s_lshl_b32 s4, s13, 8
	s_ashr_i32 s13, s12, 31
	v_writelane_b32 v253, s6, 40
	s_ashr_i32 s5, s4, 31
	v_mov_b32_e32 v185, 0
	v_writelane_b32 v253, s7, 41
	s_lshl_b64 s[6:7], s[12:13], 20
	v_writelane_b32 v253, s6, 42
	v_mov_b32_e32 v247, 1
	v_mov_b32_e32 v248, 0x3727c5ac
	v_writelane_b32 v253, s7, 43
	v_writelane_b32 v253, s0, 44
	v_mov_b32_e32 v249, 0x260
	v_mbcnt_hi_u32_b32 v250, -1, v58
	v_writelane_b32 v253, s1, 45
	v_writelane_b32 v253, s16, 46
	v_writelane_b32 v253, s2, 47
	s_lshl_b32 s0, s16, 8
	s_ashr_i32 s1, s0, 31
	v_writelane_b32 v253, s3, 48
	s_lshl_b32 s2, s8, 5
	v_writelane_b32 v253, s2, 49
	s_lshl_b32 s2, s46, 5
	v_writelane_b32 v253, s2, 50
	s_lshl_b64 s[2:3], s[8:9], 11
	s_add_u32 s2, s2, 0x4dd3e000
	v_writelane_b32 v253, s2, 51
	s_addc_u32 s2, s3, 0
	v_writelane_b32 v253, s2, 52
	s_lshl_b64 s[2:3], s[46:47], 11
	v_writelane_b32 v253, s2, 53
	v_mov_b64_e32 v[188:189], 0x3ff
	v_mov_b64_e32 v[190:191], 0x400
	v_writelane_b32 v253, s3, 54
	s_lshl_b64 s[2:3], s[8:9], 13
	s_add_u32 s2, s2, 0x4cd2a000
	s_addc_u32 s3, s3, 0
	v_writelane_b32 v253, s2, 55
	v_mov_b64_e32 v[194:195], 0x100
	v_mov_b32_e32 v251, 0x3a800000
	v_writelane_b32 v253, s3, 56
	s_lshl_b64 s[2:3], s[46:47], 15
	v_writelane_b32 v253, s2, 57
	v_mov_b32_e32 v252, 0x3b000000
	s_mov_b32 s33, 0xf800000
	v_writelane_b32 v253, s3, 58
	s_lshl_b64 s[2:3], s[8:9], 14
	s_add_u32 s6, s2, 0xff000000
	v_writelane_b32 v253, s6, 59
	v_writelane_b32 v253, s2, 60
	s_mov_b64 s[80:81], 0x80
	s_mov_b32 s93, 0xbf3504f3
	v_writelane_b32 v253, s3, 61
	s_addc_u32 s2, s3, -1
	v_writelane_b32 v253, s2, 62
	s_lshl_b64 s[2:3], s[46:47], 16
	v_writelane_b32 v253, s2, 63
	s_brev_b32 s74, 1
	v_readlane_b32 s6, v253, 9
	v_writelane_b32 v254, s3, 0
	s_lshl_b64 s[2:3], s[8:9], 12
	v_writelane_b32 v254, s2, 1
	v_readlane_b32 s7, v253, 10
	s_mov_b32 s55, 0x3e47c5c2
	v_writelane_b32 v254, s3, 2
	s_lshl_b64 s[2:3], s[46:47], 14
	v_writelane_b32 v254, s2, 3
	s_mov_b32 s96, 0x3fd744fd
	s_nop 0
	v_writelane_b32 v254, s3, 4
	s_lshl_b64 s[2:3], s[46:47], 10
	s_add_u32 s2, s2, s6
	s_addc_u32 s3, s3, s7
	v_writelane_b32 v254, s2, 5
	s_nop 1
	v_writelane_b32 v254, s3, 6
	s_lshl_b64 s[2:3], s[46:47], 13
	v_writelane_b32 v254, s2, 7
	s_nop 1
	v_writelane_b32 v254, s3, 8
	s_add_u32 s2, s10, s6
	v_writelane_b32 v254, s10, 9
	s_addc_u32 s3, s11, s7
	s_nop 0
	v_writelane_b32 v254, s11, 10
	v_writelane_b32 v254, s2, 11
	s_nop 1
	v_writelane_b32 v254, s3, 12
	s_mul_hi_i32 s3, s46, 0x3000
	s_mul_i32 s2, s46, 0x3000
	v_writelane_b32 v254, s2, 13
	s_nop 1
	v_writelane_b32 v254, s3, 14
	s_add_u32 s2, s6, s52
	v_writelane_b32 v254, s52, 15
	s_addc_u32 s3, s7, s53
	s_lshl_b64 s[0:1], s[0:1], 2
	v_writelane_b32 v254, s53, 16
	v_writelane_b32 v254, s2, 17
	s_add_i32 s97, 0, 0x20000
	s_mov_b32 s6, s73
	v_writelane_b32 v254, s3, 18
	s_add_i32 s2, s8, s46
	v_writelane_b32 v254, s2, 19
	s_lshl_b64 s[2:3], s[4:5], 2
	v_writelane_b32 v254, s2, 20
	s_nop 1
	v_writelane_b32 v254, s3, 21
	s_add_i32 s2, 0, 0x20fa0
	v_writelane_b32 v254, s2, 22
	s_add_i32 s2, 0, 0x20fa4
	v_writelane_b32 v254, s2, 23
	s_add_i32 s2, 0, 0x20800
	v_writelane_b32 v254, s2, 24
	s_add_i32 s2, 0, 0x20810
	v_writelane_b32 v254, s2, 25
	s_add_i32 s2, 0, 0x20820
	v_writelane_b32 v254, s2, 26
	v_writelane_b32 v254, s0, 27
	s_mov_b64 s[2:3], 0
	s_nop 0
	v_writelane_b32 v254, s1, 28
	s_add_i32 s0, 0, 0x20830
	v_writelane_b32 v254, s0, 29
	s_add_i32 s0, 0, 0x20840
	v_writelane_b32 v254, s0, 30
	s_add_i32 s0, 0, 0x20850
	v_writelane_b32 v254, s0, 31
	s_add_i32 s0, 0, 0x20860
	v_writelane_b32 v254, s0, 32
	s_add_i32 s0, 0, 0x20870
	v_writelane_b32 v254, s0, 33
	s_add_i32 s0, 0, 0x20880
	v_writelane_b32 v254, s0, 34
	s_add_i32 s0, 0, 0x20890
	v_writelane_b32 v254, s0, 35
	s_add_i32 s0, 0, 0x208a0
	v_writelane_b32 v254, s0, 36
	s_add_i32 s0, 0, 0x208b0
	v_writelane_b32 v254, s0, 37
	s_add_i32 s0, 0, 0x208c0
	v_writelane_b32 v254, s0, 38
	s_add_i32 s0, 0, 0x208d0
	v_writelane_b32 v254, s0, 39
	s_add_i32 s0, 0, 0x208e0
	v_writelane_b32 v254, s0, 40
	s_add_i32 s0, 0, 0x208f0
	v_writelane_b32 v254, s0, 41
	s_lshl_b64 s[0:1], s[46:47], 12
	v_writelane_b32 v254, s0, 42
	s_nop 1
	v_writelane_b32 v254, s1, 43
	s_mov_b32 s1, 0xbe47c5c2
	v_writelane_b32 v254, s0, 44
	s_nop 1
	v_writelane_b32 v254, s1, 45
	s_mov_b32 s1, 0xbec3ef15
	v_writelane_b32 v254, s0, 46
	s_nop 1
	v_writelane_b32 v254, s1, 47
	s_mov_b32 s1, 0x3ec3ef15
	v_writelane_b32 v254, s0, 48
	s_nop 1
	v_writelane_b32 v254, s1, 49
	s_mov_b32 s1, 0x3f6c835e
	v_writelane_b32 v254, s0, 50
	s_nop 1
	v_writelane_b32 v254, s1, 51
	s_mov_b32 s1, 0xbf6c835e
	v_writelane_b32 v254, s0, 52
	s_nop 1
	v_writelane_b32 v254, s1, 53
	s_mov_b32 s1, 0x3f54db31
	v_writelane_b32 v254, s0, 54
	s_nop 1
	v_writelane_b32 v254, s1, 55
	s_mov_b32 s1, 0x3f0e39da
	v_writelane_b32 v254, s0, 56
	s_nop 1
	v_writelane_b32 v254, s1, 57
	s_mov_b32 s1, 0x3f7b14be
	v_writelane_b32 v254, s0, 58
	s_nop 1
	v_writelane_b32 v254, s1, 59
	s_mov_b32 s1, 0xbf0e39da
	v_writelane_b32 v254, s0, 60
	s_nop 1
	v_writelane_b32 v254, s1, 61
	s_mov_b32 s1, 0xbf54db31
	v_writelane_b32 v254, s0, 62
	s_nop 1
	v_writelane_b32 v254, s1, 63
	s_mov_b32 s1, 0xbf7b14be
	v_writelane_b32 v255, s0, 0
	s_nop 1
	v_writelane_b32 v255, s1, 1
	s_mov_b64 s[0:1], 0
	v_writelane_b32 v255, s0, 2
	s_nop 1
	v_writelane_b32 v255, s1, 3
	s_branch .LBB0_200
.LBB0_198:
	s_or_b64 exec, exec, s[38:39]
	s_waitcnt lgkmcnt(0)
	s_barrier

; __device__ __forceinline__ unsigned xb_ld(unsigned* p)              { return __hip_atomic_load(p, __ATOMIC_RELAXED, __HIP_MEMORY_SCOPE_AGENT); }
; __device__ __forceinline__ unsigned xb_add(unsigned* p, unsigned v) { return __hip_atomic_fetch_add(p, v, __ATOMIC_RELAXED, __HIP_MEMORY_SCOPE_AGENT); }
; #define XB_SPIN(cond, bar) do { unsigned _sp = 0; while (cond) { __builtin_amdgcn_s_sleep(1); \
;     if ((++_sp & 255u) == 0u) { if (xb_ld(&(bar)[XB_TMO])) break; if (_sp > XB_SPIN_CAP) { atomicAdd(&(bar)[XB_TMO], 1u); break; } } } } while (0)
; __device__ __forceinline__ void xcd_barrier(const XcdBarrier& b) {
;     asm volatile("s_waitcnt vmcnt(0)" ::: "memory");
;     __syncthreads();
;     if (threadIdx.x == 0) {
;         unsigned long long bar_ = (unsigned long long)b.bar; unsigned bx = b.x;
;         asm volatile("" : "+s"(bar_), "+s"(bx));
;         unsigned* bar = (unsigned*)bar_;
;         __builtin_amdgcn_s_waitcnt(0);
;         unsigned nloc = b.st[0], nx = b.st[1];
;         if (nloc == 0u) { xcd_barrier_complete(bar, bx, nloc, nx); b.st[0] = nloc; b.st[1] = nx; }
;         const unsigned old = xb_add(&bar[XB_XSUB(bx)], 1u);
;         const unsigned gen = old / nloc;
;         if (old + 1u == (gen + 1u) * nloc) {
;             __builtin_amdgcn_fence(__ATOMIC_RELEASE, "agent");
;             asm volatile("s_waitcnt vmcnt(0)" ::: "memory");
;             const unsigned og = xb_add(&bar[XB_TOP], 1u);
;             const unsigned tg = og / nx;
;             if (og + 1u == (tg + 1u) * nx) xb_add(&bar[XB_TOPGEN], 1u);
;             else XB_SPIN(xb_ld(&bar[XB_TOPGEN]) == tg, bar);
;             __builtin_amdgcn_fence(__ATOMIC_ACQUIRE, "agent");
;             xb_add(&bar[XB_XGEN(bx)], 1u);
;             asm volatile("s_waitcnt vmcnt(0)" ::: "memory");
;         } else {
;             XB_SPIN(xb_ld(&bar[XB_XGEN(bx)]) == gen, bar);
;             __builtin_amdgcn_fence(__ATOMIC_ACQUIRE, "agent");
;             asm volatile("s_waitcnt vmcnt(0)" ::: "memory");
;         }
;     }
;     __syncthreads();
; }
.LBB0_247:
	s_waitcnt vmcnt(0)
	s_waitcnt vmcnt(0) lgkmcnt(0)
	s_barrier
	s_mov_b64 s[38:39], exec
	v_readlane_b32 s2, v253, 5
	v_readlane_b32 s3, v253, 6
	s_and_b64 s[2:3], s[38:39], s[2:3]
	s_mov_b64 exec, s[2:3]
	s_cbranch_execz .LBB0_291
	s_add_i32 s98, s98, 1
	v_mov_b32_e32 v0, 0x20fa0
	ds_read_b64 v[2:3], v0
	v_readlane_b32 s10, v253, 2
	v_readlane_b32 s11, v253, 3
	v_readlane_b32 s12, v253, 4
	s_lshl_b32 s12, s12, 6
	s_add_i32 s12, s12, 0x3600
	s_add_u32 s14, s10, s12
	s_addc_u32 s15, s11, 0
	s_add_u32 s10, s10, 0x3b00
	s_addc_u32 s11, s11, 0
	v_mov_b64_e32 v[4:5], s[14:15]
	v_mov_b32_e32 v8, 1
	flat_atomic_add v6, v[4:5], v8 sc0
	s_waitcnt vmcnt(0) lgkmcnt(0)
	v_readfirstlane_b32 s12, v6
	v_readfirstlane_b32 s13, v2
	v_readfirstlane_b32 s14, v3
	s_mul_i32 s13, s13, s98
	s_mul_i32 s14, s14, s98
	s_add_i32 s12, s12, 1
	v_mov_b64_e32 v[4:5], s[10:11]
	s_cmp_lg_u32 s12, s13
	s_cbranch_scc1 .Lgb_poll_2
	buffer_wbl2 sc1
	s_waitcnt vmcnt(0) lgkmcnt(0)
	flat_atomic_add v7, v[4:5], v8 sc0
	s_waitcnt vmcnt(0) lgkmcnt(0)

; __device__ __forceinline__ unsigned xb_ld(unsigned* p)              { return __hip_atomic_load(p, __ATOMIC_RELAXED, __HIP_MEMORY_SCOPE_AGENT); }
; __device__ __forceinline__ unsigned xb_add(unsigned* p, unsigned v) { return __hip_atomic_fetch_add(p, v, __ATOMIC_RELAXED, __HIP_MEMORY_SCOPE_AGENT); }
; #define XB_SPIN(cond, bar) do { unsigned _sp = 0; while (cond) { __builtin_amdgcn_s_sleep(1); \
;     if ((++_sp & 255u) == 0u) { if (xb_ld(&(bar)[XB_TMO])) break; if (_sp > XB_SPIN_CAP) { atomicAdd(&(bar)[XB_TMO], 1u); break; } } } } while (0)
; __device__ __forceinline__ void xcd_barrier(const XcdBarrier& b) {
;     asm volatile("s_waitcnt vmcnt(0)" ::: "memory");
;     __syncthreads();
;     if (threadIdx.x == 0) {
;         unsigned long long bar_ = (unsigned long long)b.bar; unsigned bx = b.x;
;         asm volatile("" : "+s"(bar_), "+s"(bx));
;         unsigned* bar = (unsigned*)bar_;
;         __builtin_amdgcn_s_waitcnt(0);
;         unsigned nloc = b.st[0], nx = b.st[1];
;         if (nloc == 0u) { xcd_barrier_complete(bar, bx, nloc, nx); b.st[0] = nloc; b.st[1] = nx; }
;         const unsigned old = xb_add(&bar[XB_XSUB(bx)], 1u);
;         const unsigned gen = old / nloc;
;         if (old + 1u == (gen + 1u) * nloc) {
;             __builtin_amdgcn_fence(__ATOMIC_RELEASE, "agent");
;             asm volatile("s_waitcnt vmcnt(0)" ::: "memory");
;             const unsigned og = xb_add(&bar[XB_TOP], 1u);
;             const unsigned tg = og / nx;
;             if (og + 1u == (tg + 1u) * nx) xb_add(&bar[XB_TOPGEN], 1u);
;             else XB_SPIN(xb_ld(&bar[XB_TOPGEN]) == tg, bar);
;             __builtin_amdgcn_fence(__ATOMIC_ACQUIRE, "agent");
;             xb_add(&bar[XB_XGEN(bx)], 1u);
;             asm volatile("s_waitcnt vmcnt(0)" ::: "memory");
;         } else {
;             XB_SPIN(xb_ld(&bar[XB_XGEN(bx)]) == gen, bar);
;             __builtin_amdgcn_fence(__ATOMIC_ACQUIRE, "agent");
;             asm volatile("s_waitcnt vmcnt(0)" ::: "memory");
;         }
;     }
;     __syncthreads();
; }
.LBB0_514:
	s_mov_b64 s[68:69], 0x80000
	s_or_b64 exec, exec, s[4:5]
	s_waitcnt vmcnt(0)
	s_waitcnt lgkmcnt(0)
	s_barrier
	s_mov_b64 s[6:7], exec
	v_readlane_b32 s2, v253, 5
	v_readlane_b32 s3, v253, 6
	s_and_b64 s[2:3], s[6:7], s[2:3]
	s_mov_b64 exec, s[2:3]
	s_cbranch_execz .LBB0_558
	s_add_i32 s98, s98, 1
	v_mov_b32_e32 v0, 0x20fa0
	ds_read_b64 v[2:3], v0
	v_readlane_b32 s10, v253, 2
	v_readlane_b32 s11, v253, 3
	v_readlane_b32 s12, v253, 4
	s_lshl_b32 s12, s12, 6
	s_add_i32 s12, s12, 0x3600
	s_add_u32 s14, s10, s12
	s_addc_u32 s15, s11, 0
	s_add_u32 s10, s10, 0x3b00
	s_addc_u32 s11, s11, 0
	v_mov_b64_e32 v[4:5], s[14:15]
	v_mov_b32_e32 v8, 1
	flat_atomic_add v6, v[4:5], v8 sc0
	s_waitcnt vmcnt(0) lgkmcnt(0)
	v_readfirstlane_b32 s12, v6
	v_readfirstlane_b32 s13, v2
	v_readfirstlane_b32 s14, v3
	s_mul_i32 s13, s13, s98
	s_mul_i32 s14, s14, s98
	s_add_i32 s12, s12, 1
	v_mov_b64_e32 v[4:5], s[10:11]
	s_cmp_lg_u32 s12, s13
	s_cbranch_scc1 .Lgb_poll_3
	buffer_wbl2 sc1
	s_waitcnt vmcnt(0) lgkmcnt(0)
	flat_atomic_add v7, v[4:5], v8 sc0
	s_waitcnt vmcnt(0) lgkmcnt(0)

; __device__ __forceinline__ unsigned xb_ld(unsigned* p)              { return __hip_atomic_load(p, __ATOMIC_RELAXED, __HIP_MEMORY_SCOPE_AGENT); }
; __device__ __forceinline__ unsigned xb_add(unsigned* p, unsigned v) { return __hip_atomic_fetch_add(p, v, __ATOMIC_RELAXED, __HIP_MEMORY_SCOPE_AGENT); }
; #define XB_SPIN(cond, bar) do { unsigned _sp = 0; while (cond) { __builtin_amdgcn_s_sleep(1); \
;     if ((++_sp & 255u) == 0u) { if (xb_ld(&(bar)[XB_TMO])) break; if (_sp > XB_SPIN_CAP) { atomicAdd(&(bar)[XB_TMO], 1u); break; } } } } while (0)
; __device__ __forceinline__ void xcd_barrier(const XcdBarrier& b) {
;     asm volatile("s_waitcnt vmcnt(0)" ::: "memory");
;     __syncthreads();
;     if (threadIdx.x == 0) {
;         unsigned long long bar_ = (unsigned long long)b.bar; unsigned bx = b.x;
;         asm volatile("" : "+s"(bar_), "+s"(bx));
;         unsigned* bar = (unsigned*)bar_;
;         __builtin_amdgcn_s_waitcnt(0);
;         unsigned nloc = b.st[0], nx = b.st[1];
;         if (nloc == 0u) { xcd_barrier_complete(bar, bx, nloc, nx); b.st[0] = nloc; b.st[1] = nx; }
;         const unsigned old = xb_add(&bar[XB_XSUB(bx)], 1u);
;         const unsigned gen = old / nloc;
;         if (old + 1u == (gen + 1u) * nloc) {
;             __builtin_amdgcn_fence(__ATOMIC_RELEASE, "agent");
;             asm volatile("s_waitcnt vmcnt(0)" ::: "memory");
;             const unsigned og = xb_add(&bar[XB_TOP], 1u);
;             const unsigned tg = og / nx;
;             if (og + 1u == (tg + 1u) * nx) xb_add(&bar[XB_TOPGEN], 1u);
;             else XB_SPIN(xb_ld(&bar[XB_TOPGEN]) == tg, bar);
;             __builtin_amdgcn_fence(__ATOMIC_ACQUIRE, "agent");
;             xb_add(&bar[XB_XGEN(bx)], 1u);
;             asm volatile("s_waitcnt vmcnt(0)" ::: "memory");
;         } else {
;             XB_SPIN(xb_ld(&bar[XB_XGEN(bx)]) == gen, bar);
;             __builtin_amdgcn_fence(__ATOMIC_ACQUIRE, "agent");
;             asm volatile("s_waitcnt vmcnt(0)" ::: "memory");
;         }
;     }
;     __syncthreads();
; }
.LBB0_606:
	s_waitcnt vmcnt(0)
	s_waitcnt lgkmcnt(0)
	s_barrier
	s_mov_b64 s[42:43], exec
	v_readlane_b32 s2, v253, 5
	v_readlane_b32 s3, v253, 6
	s_and_b64 s[2:3], s[42:43], s[2:3]
	s_mov_b64 exec, s[2:3]
	s_cbranch_execz .LBB0_650
	s_add_i32 s98, s98, 1
	v_mov_b32_e32 v0, 0x20fa0
	ds_read_b64 v[2:3], v0
	v_readlane_b32 s10, v253, 2
	v_readlane_b32 s11, v253, 3
	v_readlane_b32 s12, v253, 4
	s_lshl_b32 s12, s12, 6
	s_add_i32 s12, s12, 0x3600
	s_add_u32 s14, s10, s12
	s_addc_u32 s15, s11, 0
	s_add_u32 s10, s10, 0x3b00
	s_addc_u32 s11, s11, 0
	v_mov_b64_e32 v[4:5], s[14:15]
	v_mov_b32_e32 v8, 1
	flat_atomic_add v6, v[4:5], v8 sc0
	s_waitcnt vmcnt(0) lgkmcnt(0)
	v_readfirstlane_b32 s12, v6
	v_readfirstlane_b32 s13, v2
	v_readfirstlane_b32 s14, v3
	s_mul_i32 s13, s13, s98
	s_mul_i32 s14, s14, s98
	s_add_i32 s12, s12, 1
	v_mov_b64_e32 v[4:5], s[10:11]
	s_cmp_lg_u32 s12, s13
	s_cbranch_scc1 .Lgb_poll_4
	buffer_wbl2 sc1
	s_waitcnt vmcnt(0) lgkmcnt(0)
	flat_atomic_add v7, v[4:5], v8 sc0
	s_waitcnt vmcnt(0) lgkmcnt(0)

; __device__ __forceinline__ unsigned xb_ld(unsigned* p)              { return __hip_atomic_load(p, __ATOMIC_RELAXED, __HIP_MEMORY_SCOPE_AGENT); }
; __device__ __forceinline__ unsigned xb_add(unsigned* p, unsigned v) { return __hip_atomic_fetch_add(p, v, __ATOMIC_RELAXED, __HIP_MEMORY_SCOPE_AGENT); }
; #define XB_SPIN(cond, bar) do { unsigned _sp = 0; while (cond) { __builtin_amdgcn_s_sleep(1); \
;     if ((++_sp & 255u) == 0u) { if (xb_ld(&(bar)[XB_TMO])) break; if (_sp > XB_SPIN_CAP) { atomicAdd(&(bar)[XB_TMO], 1u); break; } } } } while (0)
; __device__ __forceinline__ void xcd_barrier(const XcdBarrier& b) {
;     asm volatile("s_waitcnt vmcnt(0)" ::: "memory");
;     __syncthreads();
;     if (threadIdx.x == 0) {
;         unsigned long long bar_ = (unsigned long long)b.bar; unsigned bx = b.x;
;         asm volatile("" : "+s"(bar_), "+s"(bx));
;         unsigned* bar = (unsigned*)bar_;
;         __builtin_amdgcn_s_waitcnt(0);
;         unsigned nloc = b.st[0], nx = b.st[1];
;         if (nloc == 0u) { xcd_barrier_complete(bar, bx, nloc, nx); b.st[0] = nloc; b.st[1] = nx; }
;         const unsigned old = xb_add(&bar[XB_XSUB(bx)], 1u);
;         const unsigned gen = old / nloc;
;         if (old + 1u == (gen + 1u) * nloc) {
;             __builtin_amdgcn_fence(__ATOMIC_RELEASE, "agent");
;             asm volatile("s_waitcnt vmcnt(0)" ::: "memory");
;             const unsigned og = xb_add(&bar[XB_TOP], 1u);
;             const unsigned tg = og / nx;
;             if (og + 1u == (tg + 1u) * nx) xb_add(&bar[XB_TOPGEN], 1u);
;             else XB_SPIN(xb_ld(&bar[XB_TOPGEN]) == tg, bar);
;             __builtin_amdgcn_fence(__ATOMIC_ACQUIRE, "agent");
;             xb_add(&bar[XB_XGEN(bx)], 1u);
;             asm volatile("s_waitcnt vmcnt(0)" ::: "memory");
;         } else {
;             XB_SPIN(xb_ld(&bar[XB_XGEN(bx)]) == gen, bar);
;             __builtin_amdgcn_fence(__ATOMIC_ACQUIRE, "agent");
;             asm volatile("s_waitcnt vmcnt(0)" ::: "memory");
;         }
;     }
;     __syncthreads();
; }
.LBB0_666:
	s_waitcnt vmcnt(0)
	s_waitcnt lgkmcnt(0)
	s_barrier
	s_mov_b64 s[40:41], exec
	v_readlane_b32 s2, v253, 5
	v_readlane_b32 s3, v253, 6
	s_and_b64 s[2:3], s[40:41], s[2:3]
	s_mov_b64 exec, s[2:3]
	s_cbranch_execz .LBB0_710
	s_add_i32 s98, s98, 1
	v_mov_b32_e32 v0, 0x20fa0
	ds_read_b64 v[2:3], v0
	v_readlane_b32 s10, v253, 2
	v_readlane_b32 s11, v253, 3
	v_readlane_b32 s12, v253, 4
	s_lshl_b32 s12, s12, 6
	s_add_i32 s12, s12, 0x3600
	s_add_u32 s14, s10, s12
	s_addc_u32 s15, s11, 0
	s_add_u32 s10, s10, 0x3b00
	s_addc_u32 s11, s11, 0
	v_mov_b64_e32 v[4:5], s[14:15]
	v_mov_b32_e32 v8, 1
	flat_atomic_add v6, v[4:5], v8 sc0
	s_waitcnt vmcnt(0) lgkmcnt(0)
	v_readfirstlane_b32 s12, v6
	v_readfirstlane_b32 s13, v2
	v_readfirstlane_b32 s14, v3
	s_mul_i32 s13, s13, s98
	s_mul_i32 s14, s14, s98
	s_add_i32 s12, s12, 1
	v_mov_b64_e32 v[4:5], s[10:11]
	s_cmp_lg_u32 s12, s13
	s_cbranch_scc1 .Lgb_poll_5
	buffer_wbl2 sc1
	s_waitcnt vmcnt(0) lgkmcnt(0)
	flat_atomic_add v7, v[4:5], v8 sc0
	s_waitcnt vmcnt(0) lgkmcnt(0)

; __device__ __forceinline__ unsigned xb_ld(unsigned* p)              { return __hip_atomic_load(p, __ATOMIC_RELAXED, __HIP_MEMORY_SCOPE_AGENT); }
; __device__ __forceinline__ unsigned xb_add(unsigned* p, unsigned v) { return __hip_atomic_fetch_add(p, v, __ATOMIC_RELAXED, __HIP_MEMORY_SCOPE_AGENT); }
; #define XB_SPIN(cond, bar) do { unsigned _sp = 0; while (cond) { __builtin_amdgcn_s_sleep(1); \
;     if ((++_sp & 255u) == 0u) { if (xb_ld(&(bar)[XB_TMO])) break; if (_sp > XB_SPIN_CAP) { atomicAdd(&(bar)[XB_TMO], 1u); break; } } } } while (0)
; __device__ __forceinline__ void xcd_barrier(const XcdBarrier& b) {
;     asm volatile("s_waitcnt vmcnt(0)" ::: "memory");
;     __syncthreads();
;     if (threadIdx.x == 0) {
;         unsigned long long bar_ = (unsigned long long)b.bar; unsigned bx = b.x;
;         asm volatile("" : "+s"(bar_), "+s"(bx));
;         unsigned* bar = (unsigned*)bar_;
;         __builtin_amdgcn_s_waitcnt(0);
;         unsigned nloc = b.st[0], nx = b.st[1];
;         if (nloc == 0u) { xcd_barrier_complete(bar, bx, nloc, nx); b.st[0] = nloc; b.st[1] = nx; }
;         const unsigned old = xb_add(&bar[XB_XSUB(bx)], 1u);
;         const unsigned gen = old / nloc;
;         if (old + 1u == (gen + 1u) * nloc) {
;             __builtin_amdgcn_fence(__ATOMIC_RELEASE, "agent");
;             asm volatile("s_waitcnt vmcnt(0)" ::: "memory");
;             const unsigned og = xb_add(&bar[XB_TOP], 1u);
;             const unsigned tg = og / nx;
;             if (og + 1u == (tg + 1u) * nx) xb_add(&bar[XB_TOPGEN], 1u);
;             else XB_SPIN(xb_ld(&bar[XB_TOPGEN]) == tg, bar);
;             __builtin_amdgcn_fence(__ATOMIC_ACQUIRE, "agent");
;             xb_add(&bar[XB_XGEN(bx)], 1u);
;             asm volatile("s_waitcnt vmcnt(0)" ::: "memory");
;         } else {
;             XB_SPIN(xb_ld(&bar[XB_XGEN(bx)]) == gen, bar);
;             __builtin_amdgcn_fence(__ATOMIC_ACQUIRE, "agent");
;             asm volatile("s_waitcnt vmcnt(0)" ::: "memory");
;         }
;     }
;     __syncthreads();
; }
.LBB0_834:
	s_waitcnt vmcnt(0)
	s_waitcnt vmcnt(0) lgkmcnt(0)
	s_barrier
	s_mov_b64 s[42:43], exec
	v_readlane_b32 s2, v253, 5
	v_readlane_b32 s3, v253, 6
	s_and_b64 s[2:3], s[42:43], s[2:3]
	s_mov_b64 exec, s[2:3]
	s_cbranch_execz .LBB0_878
	s_add_i32 s98, s98, 1
	v_mov_b32_e32 v0, 0x20fa0
	ds_read_b64 v[2:3], v0
	v_readlane_b32 s10, v253, 2
	v_readlane_b32 s11, v253, 3
	v_readlane_b32 s12, v253, 4
	s_lshl_b32 s12, s12, 6
	s_add_i32 s12, s12, 0x3600
	s_add_u32 s14, s10, s12
	s_addc_u32 s15, s11, 0
	s_add_u32 s10, s10, 0x3b00
	s_addc_u32 s11, s11, 0
	v_mov_b64_e32 v[4:5], s[14:15]
	v_mov_b32_e32 v8, 1
	flat_atomic_add v6, v[4:5], v8 sc0
	s_waitcnt vmcnt(0) lgkmcnt(0)
	v_readfirstlane_b32 s12, v6
	v_readfirstlane_b32 s13, v2
	v_readfirstlane_b32 s14, v3
	s_mul_i32 s13, s13, s98
	s_mul_i32 s14, s14, s98
	s_add_i32 s12, s12, 1
	v_mov_b64_e32 v[4:5], s[10:11]
	s_cmp_lg_u32 s12, s13
	s_cbranch_scc1 .Lgb_poll_7
	buffer_wbl2 sc1
	s_waitcnt vmcnt(0) lgkmcnt(0)
	flat_atomic_add v7, v[4:5], v8 sc0
	s_waitcnt vmcnt(0) lgkmcnt(0)

; #define PG8_STAGE(bufoff, gbase, voff) do { _Pragma("unroll") for (int _i = 0; _i < 2; ++_i) \
;         __builtin_amdgcn_global_load_lds((const unsigned*)((const char*)(gbase) + (voff)[_i]), (LAS unsigned*)(lds + (bufoff) + ldsw + _i * 8192), 16, 0, 0); } while (0)
; #define PG8_LDA(dst, b, h) do { _Pragma("unroll") for (int m = 0; m < 4; ++m) _Pragma("unroll") for (int k = 0; k < 2; ++k) dst[m][k] = *(const LAS bf16x8*)(lds + PG8_SA(b, h) + aoff + m * 2048 + k * 1024); } while (0)
; #define PG8_LDB(dst, b, h) do { _Pragma("unroll") for (int n = 0; n < 2; ++n) _Pragma("unroll") for (int k = 0; k < 2; ++k) dst[n][k] = *(const LAS bf16x8*)(lds + PG8_SB(b, h) + boff + n * 2048 + k * 1024); } while (0)
; #define PG8_MMA(ai, bj, At, Bt) do { __builtin_amdgcn_s_setprio(1); _Pragma("unroll") for (int m = 0; m < 4; ++m) _Pragma("unroll") for (int n = 0; n < 2; ++n) _Pragma("unroll") for (int k = 0; k < 2; ++k) \
;         acc[ai][bj][m][n] = __builtin_amdgcn_mfma_f32_16x16x32_bf16(Bt[n][k], At[m][k], acc[ai][bj][m][n], 0, 0, 0); __builtin_amdgcn_s_setprio(0); } while (0)
; #define PG8_WAIT_V(n) asm volatile("s_waitcnt vmcnt(" #n ")" ::: "memory")
; #define PG8_WAIT_L(n) asm volatile("s_waitcnt lgkmcnt(" #n ")" ::: "memory")
; #define PG8_BAR __builtin_amdgcn_s_barrier()
; #define PG8_SCHED __builtin_amdgcn_sched_barrier(0)
; template <class Epi>
; __device__ __forceinline__ void gemm_phase(LAS unsigned char* lds, const Gemm g, const StaticOrder& S, const Epi& E, const int tid) {
;     ...
;             PG8_LDB(B0, 0, 0); PG8_SCHED; PG8_LDA(At, 0, 0); PG8_STAGE(PG8_SA(1, 1), a1 + hstepA, voffA);
;             PG8_WAIT_L(8); PG8_BAR; PG8_WAIT_L(0); PG8_MMA(0, 0, At, B0); PG8_BAR; PG8_SCHED;
;             PG8_LDB(B1, 0, 1); PG8_STAGE(PG8_SB(0, 0), b2, voffB);
;             PG8_BAR; PG8_WAIT_L(0); PG8_MMA(0, 1, At, B1); PG8_BAR;
;             PG8_LDA(At, 0, 1); PG8_STAGE(PG8_SA(0, 0), a2, voffA);
;             PG8_BAR; PG8_WAIT_L(0); PG8_MMA(1, 0, At, B0); PG8_BAR; PG8_SCHED;
;             PG8_STAGE(PG8_SB(0, 1), b2 + hstepB, voffB);
;             PG8_WAIT_V(6); PG8_BAR; PG8_MMA(1, 1, At, B1); PG8_BAR;
;             PG8_LDB(B0, 1, 0); PG8_SCHED; PG8_LDA(At, 1, 0); PG8_STAGE(PG8_SA(0, 1), a2 + hstepA, voffA);
.LBB0_890:
	s_add_u32 s10, s8, 0xfff80080
	s_addc_u32 s11, s9, -1
	s_add_i32 s49, 0, 0x10000
	v_add_u32_e32 v100, s49, v187
	ds_read_b128 v[88:91], v100
	ds_read_b128 v[92:95], v100 offset:1024
	ds_read_b128 v[96:99], v100 offset:2048
	ds_read_b128 v[100:103], v100 offset:3072
	s_cmp_eq_u32 s48, 28
	s_cselect_b32 s41, s4, s11
	s_cselect_b32 s40, s5, s10
	s_cselect_b32 s11, s31, s43
	s_cselect_b32 s10, s35, s42
	v_lshl_add_u64 v[182:183], s[8:9], 0, v[178:179]
	s_add_i32 m0, s56, 0xc000
	ds_read_b128 v[104:107], v193
	ds_read_b128 v[108:111], v193 offset:1024
	ds_read_b128 v[112:115], v193 offset:2048
	ds_read_b128 v[116:119], v193 offset:3072
	ds_read_b128 v[160:163], v193 offset:4096
	ds_read_b128 v[164:167], v193 offset:5120
	ds_read_b128 v[168:171], v193 offset:6144
	ds_read_b128 v[196:199], v193 offset:7168
	global_load_lds_dwordx4 v[182:183], off
	v_lshl_add_u64 v[182:183], s[8:9], 0, v[180:181]
	s_add_i32 m0, s56, 0xe000
	s_nop 0
	global_load_lds_dwordx4 v[182:183], off
	s_waitcnt lgkmcnt(8)
	s_barrier
	s_waitcnt lgkmcnt(0)
	s_setprio 1
	s_waitcnt lgkmcnt(0)
	v_mfma_f32_16x16x32_bf16 v[156:159], v[88:91], v[104:107], v[156:159]
	v_mfma_f32_16x16x32_bf16 v[152:155], v[96:99], v[104:107], v[152:155]
	v_mfma_f32_16x16x32_bf16 v[148:151], v[88:91], v[112:115], v[148:151]
	v_mfma_f32_16x16x32_bf16 v[144:147], v[96:99], v[112:115], v[144:147]
	v_mfma_f32_16x16x32_bf16 v[140:143], v[88:91], v[160:163], v[140:143]
	v_mfma_f32_16x16x32_bf16 v[136:139], v[96:99], v[160:163], v[136:139]
	v_mfma_f32_16x16x32_bf16 v[132:135], v[88:91], v[168:171], v[132:135]
	v_mfma_f32_16x16x32_bf16 v[128:131], v[96:99], v[168:171], v[128:131]
	v_mfma_f32_16x16x32_bf16 v[156:159], v[92:95], v[108:111], v[156:159]
	v_mfma_f32_16x16x32_bf16 v[152:155], v[100:103], v[108:111], v[152:155]
	v_mfma_f32_16x16x32_bf16 v[148:151], v[92:95], v[116:119], v[148:151]
	v_mfma_f32_16x16x32_bf16 v[144:147], v[100:103], v[116:119], v[144:147]
	v_mfma_f32_16x16x32_bf16 v[140:143], v[92:95], v[164:167], v[140:143]
	v_mfma_f32_16x16x32_bf16 v[136:139], v[100:103], v[164:167], v[136:139]
	v_mfma_f32_16x16x32_bf16 v[132:135], v[92:95], v[196:199], v[132:135]
	v_mfma_f32_16x16x32_bf16 v[128:131], v[100:103], v[196:199], v[128:131]
	s_setprio 0
	s_barrier
	s_add_i32 s67, 0, 0x14000
	v_add_u32_e32 v182, s67, v187
	s_add_i32 s49, s49, s54
	ds_read_b128 v[200:203], v182
	ds_read_b128 v[204:207], v182 offset:1024
	ds_read_b128 v[208:211], v182 offset:2048
	ds_read_b128 v[212:215], v182 offset:3072
	v_lshl_add_u64 v[182:183], s[10:11], 0, v[184:185]
	s_mov_b32 m0, s49
	v_lshl_add_u64 v[216:217], s[10:11], 0, v[172:173]
	global_load_lds_dwordx4 v[182:183], off
	s_add_i32 m0, s49, 0x2000
	s_nop 0
	global_load_lds_dwordx4 v[216:217], off
	s_barrier
	s_waitcnt lgkmcnt(0)
	s_setprio 1
	s_waitcnt lgkmcnt(0)
	v_mfma_f32_16x16x32_bf16 v[60:63], v[200:203], v[104:107], v[60:63]
	v_mfma_f32_16x16x32_bf16 v[56:59], v[208:211], v[104:107], v[56:59]
	v_mfma_f32_16x16x32_bf16 v[52:55], v[200:203], v[112:115], v[52:55]
	v_mfma_f32_16x16x32_bf16 v[48:51], v[208:211], v[112:115], v[48:51]
	v_mfma_f32_16x16x32_bf16 v[44:47], v[200:203], v[160:163], v[44:47]
	v_mfma_f32_16x16x32_bf16 v[40:43], v[208:211], v[160:163], v[40:43]
	v_mfma_f32_16x16x32_bf16 v[36:39], v[200:203], v[168:171], v[36:39]
	v_mfma_f32_16x16x32_bf16 v[32:35], v[208:211], v[168:171], v[32:35]
	v_mfma_f32_16x16x32_bf16 v[60:63], v[204:207], v[108:111], v[60:63]
	v_mfma_f32_16x16x32_bf16 v[56:59], v[212:215], v[108:111], v[56:59]
	v_mfma_f32_16x16x32_bf16 v[52:55], v[204:207], v[116:119], v[52:55]
	v_mfma_f32_16x16x32_bf16 v[48:51], v[212:215], v[116:119], v[48:51]
	v_mfma_f32_16x16x32_bf16 v[44:47], v[204:207], v[164:167], v[44:47]
	v_mfma_f32_16x16x32_bf16 v[40:43], v[212:215], v[164:167], v[40:43]
	v_mfma_f32_16x16x32_bf16 v[36:39], v[204:207], v[196:199], v[36:39]
	v_mfma_f32_16x16x32_bf16 v[32:35], v[212:215], v[196:199], v[32:35]
	s_setprio 0
	s_mov_b32 m0, s56
	v_lshl_add_u64 v[218:219], s[40:41], 0, v[176:177]
	s_barrier
	ds_read_b128 v[104:107], v193 offset:16384
	ds_read_b128 v[108:111], v193 offset:17408
	ds_read_b128 v[112:115], v193 offset:18432
	ds_read_b128 v[116:119], v193 offset:19456
	ds_read_b128 v[160:163], v193 offset:20480
	ds_read_b128 v[164:167], v193 offset:21504
	ds_read_b128 v[168:171], v193 offset:22528
	ds_read_b128 v[196:199], v193 offset:23552
	global_load_lds_dwordx4 v[218:219], off
	v_lshl_add_u64 v[220:221], s[40:41], 0, v[174:175]
	s_mov_b32 m0, s57
	s_nop 0
	global_load_lds_dwordx4 v[220:221], off
	s_barrier
	s_waitcnt lgkmcnt(0)
	s_setprio 1
	s_waitcnt lgkmcnt(0)
	v_mfma_f32_16x16x32_bf16 v[124:127], v[88:91], v[104:107], v[124:127]
	v_mfma_f32_16x16x32_bf16 v[120:123], v[96:99], v[104:107], v[120:123]
	v_mfma_f32_16x16x32_bf16 v[84:87], v[88:91], v[112:115], v[84:87]
	v_mfma_f32_16x16x32_bf16 v[80:83], v[96:99], v[112:115], v[80:83]
	v_mfma_f32_16x16x32_bf16 v[76:79], v[88:91], v[160:163], v[76:79]
	v_mfma_f32_16x16x32_bf16 v[72:75], v[96:99], v[160:163], v[72:75]
	v_mfma_f32_16x16x32_bf16 v[68:71], v[88:91], v[168:171], v[68:71]
	v_mfma_f32_16x16x32_bf16 v[64:67], v[96:99], v[168:171], v[64:67]
	v_mfma_f32_16x16x32_bf16 v[124:127], v[92:95], v[108:111], v[124:127]
	v_mfma_f32_16x16x32_bf16 v[120:123], v[100:103], v[108:111], v[120:123]
	v_mfma_f32_16x16x32_bf16 v[84:87], v[92:95], v[116:119], v[84:87]
	v_mfma_f32_16x16x32_bf16 v[80:83], v[100:103], v[116:119], v[80:83]
	v_mfma_f32_16x16x32_bf16 v[76:79], v[92:95], v[164:167], v[76:79]
	v_mfma_f32_16x16x32_bf16 v[72:75], v[100:103], v[164:167], v[72:75]
	v_mfma_f32_16x16x32_bf16 v[68:71], v[92:95], v[196:199], v[68:71]
	v_mfma_f32_16x16x32_bf16 v[64:67], v[100:103], v[196:199], v[64:67]
	s_setprio 0
	s_barrier
; #define PG8_STAGE(bufoff, gbase, voff) do { _Pragma("unroll") for (int _i = 0; _i < 2; ++_i) \
;         __builtin_amdgcn_global_load_lds((const unsigned*)((const char*)(gbase) + (voff)[_i]), (LAS unsigned*)(lds + (bufoff) + ldsw + _i * 8192), 16, 0, 0); } while (0)
; #define PG8_LDA(dst, b, h) do { _Pragma("unroll") for (int m = 0; m < 4; ++m) _Pragma("unroll") for (int k = 0; k < 2; ++k) dst[m][k] = *(const LAS bf16x8*)(lds + PG8_SA(b, h) + aoff + m * 2048 + k * 1024); } while (0)
; #define PG8_LDB(dst, b, h) do { _Pragma("unroll") for (int n = 0; n < 2; ++n) _Pragma("unroll") for (int k = 0; k < 2; ++k) dst[n][k] = *(const LAS bf16x8*)(lds + PG8_SB(b, h) + boff + n * 2048 + k * 1024); } while (0)
; #define PG8_MMA(ai, bj, At, Bt) do { __builtin_amdgcn_s_setprio(1); _Pragma("unroll") for (int m = 0; m < 4; ++m) _Pragma("unroll") for (int n = 0; n < 2; ++n) _Pragma("unroll") for (int k = 0; k < 2; ++k) \
;         acc[ai][bj][m][n] = __builtin_amdgcn_mfma_f32_16x16x32_bf16(Bt[n][k], At[m][k], acc[ai][bj][m][n], 0, 0, 0); __builtin_amdgcn_s_setprio(0); } while (0)
; #define PG8_WAIT_V(n) asm volatile("s_waitcnt vmcnt(" #n ")" ::: "memory")
; #define PG8_WAIT_L(n) asm volatile("s_waitcnt lgkmcnt(" #n ")" ::: "memory")
; #define PG8_BAR __builtin_amdgcn_s_barrier()
; #define PG8_SCHED __builtin_amdgcn_sched_barrier(0)
; template <class Epi>
; __device__ __forceinline__ void gemm_phase(LAS unsigned char* lds, const Gemm g, const StaticOrder& S, const Epi& E, const int tid) {
;     ...
;             PG8_STAGE(PG8_SB(0, 1), b2 + hstepB, voffB);
;             PG8_WAIT_V(6); PG8_BAR; PG8_MMA(1, 1, At, B1); PG8_BAR;
;             PG8_LDB(B0, 1, 0); PG8_SCHED; PG8_LDA(At, 1, 0); PG8_STAGE(PG8_SA(0, 1), a2 + hstepA, voffA);
;             PG8_WAIT_L(8); PG8_BAR; PG8_WAIT_L(0); PG8_MMA(0, 0, At, B0); PG8_BAR; PG8_SCHED;
;             PG8_LDB(B1, 1, 1); PG8_STAGE(PG8_SB(1, 0), b3, voffB);
;             PG8_BAR; PG8_WAIT_L(0); PG8_MMA(0, 1, At, B1); PG8_BAR;
;             PG8_LDA(At, 1, 1); PG8_STAGE(PG8_SA(1, 0), a3, voffA);
;             PG8_BAR; PG8_WAIT_L(0); PG8_MMA(1, 0, At, B0); PG8_BAR; PG8_SCHED;
	s_add_u32 s68, s10, 0x80000
	s_addc_u32 s69, s11, 0
	s_add_i32 s49, s67, s54
	v_lshl_add_u64 v[88:89], s[68:69], 0, v[184:185]
	s_mov_b32 m0, s49
	s_nop 0
	global_load_lds_dwordx4 v[88:89], off
	v_lshl_add_u64 v[88:89], s[68:69], 0, v[172:173]
	s_add_i32 m0, s49, 0x2000
	s_nop 0
	global_load_lds_dwordx4 v[88:89], off
	s_waitcnt vmcnt(6)
	s_barrier
	s_setprio 1
	v_mfma_f32_16x16x32_bf16 v[28:31], v[200:203], v[104:107], v[28:31]
	v_mfma_f32_16x16x32_bf16 v[24:27], v[208:211], v[104:107], v[24:27]
	v_mfma_f32_16x16x32_bf16 v[20:23], v[200:203], v[112:115], v[20:23]
	v_mfma_f32_16x16x32_bf16 v[16:19], v[208:211], v[112:115], v[16:19]
	v_mfma_f32_16x16x32_bf16 v[12:15], v[200:203], v[160:163], v[12:15]
	v_mfma_f32_16x16x32_bf16 v[8:11], v[208:211], v[160:163], v[8:11]
	v_mfma_f32_16x16x32_bf16 v[4:7], v[200:203], v[168:171], v[4:7]
	v_mfma_f32_16x16x32_bf16 v[0:3], v[208:211], v[168:171], v[0:3]
	v_mfma_f32_16x16x32_bf16 v[28:31], v[204:207], v[108:111], v[28:31]
	v_mfma_f32_16x16x32_bf16 v[24:27], v[212:215], v[108:111], v[24:27]
	v_mfma_f32_16x16x32_bf16 v[20:23], v[204:207], v[116:119], v[20:23]
	v_mfma_f32_16x16x32_bf16 v[16:19], v[212:215], v[116:119], v[16:19]
	v_mfma_f32_16x16x32_bf16 v[12:15], v[204:207], v[164:167], v[12:15]
	v_mfma_f32_16x16x32_bf16 v[8:11], v[212:215], v[164:167], v[8:11]
	v_mfma_f32_16x16x32_bf16 v[4:7], v[204:207], v[196:199], v[4:7]
	v_mfma_f32_16x16x32_bf16 v[0:3], v[212:215], v[196:199], v[0:3]
	s_setprio 0
	s_add_i32 s49, 0, 0x18000
	v_add_u32_e32 v100, s49, v187
	s_barrier
	ds_read_b128 v[88:91], v100
	ds_read_b128 v[92:95], v100 offset:1024
	ds_read_b128 v[96:99], v100 offset:2048
	ds_read_b128 v[100:103], v100 offset:3072
	s_add_u32 s40, s40, 0x80000
	s_addc_u32 s41, s41, 0
	s_mov_b32 m0, s58
	v_lshl_add_u64 v[200:201], s[40:41], 0, v[176:177]
	ds_read_b128 v[104:107], v193 offset:32768
	ds_read_b128 v[108:111], v193 offset:33792
	ds_read_b128 v[112:115], v193 offset:34816
	ds_read_b128 v[116:119], v193 offset:35840
	ds_read_b128 v[160:163], v193 offset:36864
	ds_read_b128 v[164:167], v193 offset:37888
	ds_read_b128 v[168:171], v193 offset:38912
	ds_read_b128 v[196:199], v193 offset:39936
	global_load_lds_dwordx4 v[200:201], off
	v_lshl_add_u64 v[200:201], s[40:41], 0, v[174:175]
	s_mov_b32 m0, s59
	s_nop 0
	global_load_lds_dwordx4 v[200:201], off
	s_waitcnt lgkmcnt(8)
	s_barrier
	s_waitcnt lgkmcnt(0)
	s_setprio 1
	s_waitcnt lgkmcnt(0)
	v_mfma_f32_16x16x32_bf16 v[156:159], v[88:91], v[104:107], v[156:159]
	v_mfma_f32_16x16x32_bf16 v[152:155], v[96:99], v[104:107], v[152:155]
	v_mfma_f32_16x16x32_bf16 v[148:151], v[88:91], v[112:115], v[148:151]
	v_mfma_f32_16x16x32_bf16 v[144:147], v[96:99], v[112:115], v[144:147]
	v_mfma_f32_16x16x32_bf16 v[140:143], v[88:91], v[160:163], v[140:143]
	v_mfma_f32_16x16x32_bf16 v[136:139], v[96:99], v[160:163], v[136:139]
	v_mfma_f32_16x16x32_bf16 v[132:135], v[88:91], v[168:171], v[132:135]
	v_mfma_f32_16x16x32_bf16 v[128:131], v[96:99], v[168:171], v[128:131]
	v_mfma_f32_16x16x32_bf16 v[156:159], v[92:95], v[108:111], v[156:159]
	v_mfma_f32_16x16x32_bf16 v[152:155], v[100:103], v[108:111], v[152:155]
	v_mfma_f32_16x16x32_bf16 v[148:151], v[92:95], v[116:119], v[148:151]
	v_mfma_f32_16x16x32_bf16 v[144:147], v[100:103], v[116:119], v[144:147]
	v_mfma_f32_16x16x32_bf16 v[140:143], v[92:95], v[164:167], v[140:143]
	v_mfma_f32_16x16x32_bf16 v[136:139], v[100:103], v[164:167], v[136:139]
	v_mfma_f32_16x16x32_bf16 v[132:135], v[92:95], v[196:199], v[132:135]
	v_mfma_f32_16x16x32_bf16 v[128:131], v[100:103], v[196:199], v[128:131]
	s_setprio 0
	s_barrier
	s_add_i32 s40, 0, 0x1c000
	s_add_i32 s41, s49, s54
	v_add_u32_e32 v212, s40, v187
	v_lshl_add_u64 v[182:183], v[182:183], 0, s[80:81]
	s_mov_b32 m0, s41
	ds_read_b128 v[200:203], v212
	ds_read_b128 v[204:207], v212 offset:1024
	ds_read_b128 v[208:211], v212 offset:2048
	ds_read_b128 v[212:215], v212 offset:3072
	global_load_lds_dwordx4 v[182:183], off
	v_lshl_add_u64 v[182:183], v[216:217], 0, s[80:81]
	s_add_i32 m0, s41, 0x2000
	s_nop 0
	global_load_lds_dwordx4 v[182:183], off
	s_barrier
	s_waitcnt lgkmcnt(0)
	s_setprio 1
	s_waitcnt lgkmcnt(0)
	v_mfma_f32_16x16x32_bf16 v[60:63], v[200:203], v[104:107], v[60:63]
	v_mfma_f32_16x16x32_bf16 v[56:59], v[208:211], v[104:107], v[56:59]
	v_mfma_f32_16x16x32_bf16 v[52:55], v[200:203], v[112:115], v[52:55]
	v_mfma_f32_16x16x32_bf16 v[48:51], v[208:211], v[112:115], v[48:51]
	v_mfma_f32_16x16x32_bf16 v[44:47], v[200:203], v[160:163], v[44:47]
	v_mfma_f32_16x16x32_bf16 v[40:43], v[208:211], v[160:163], v[40:43]
	v_mfma_f32_16x16x32_bf16 v[36:39], v[200:203], v[168:171], v[36:39]
	v_mfma_f32_16x16x32_bf16 v[32:35], v[208:211], v[168:171], v[32:35]
	v_mfma_f32_16x16x32_bf16 v[60:63], v[204:207], v[108:111], v[60:63]
	v_mfma_f32_16x16x32_bf16 v[56:59], v[212:215], v[108:111], v[56:59]
	v_mfma_f32_16x16x32_bf16 v[52:55], v[204:207], v[116:119], v[52:55]
	v_mfma_f32_16x16x32_bf16 v[48:51], v[212:215], v[116:119], v[48:51]
	v_mfma_f32_16x16x32_bf16 v[44:47], v[204:207], v[164:167], v[44:47]
	v_mfma_f32_16x16x32_bf16 v[40:43], v[212:215], v[164:167], v[40:43]
	v_mfma_f32_16x16x32_bf16 v[36:39], v[204:207], v[196:199], v[36:39]
	v_mfma_f32_16x16x32_bf16 v[32:35], v[212:215], v[196:199], v[32:35]
	s_setprio 0
	s_mov_b32 m0, s60
	v_lshl_add_u64 v[182:183], v[218:219], 0, s[80:81]
	s_barrier
	ds_read_b128 v[104:107], v193 offset:49152
	ds_read_b128 v[108:111], v193 offset:50176
	ds_read_b128 v[112:115], v193 offset:51200
	ds_read_b128 v[116:119], v193 offset:52224
	ds_read_b128 v[160:163], v193 offset:53248
	ds_read_b128 v[164:167], v193 offset:54272
	ds_read_b128 v[168:171], v193 offset:55296
	ds_read_b128 v[196:199], v193 offset:56320
	global_load_lds_dwordx4 v[182:183], off
	v_lshl_add_u64 v[182:183], v[220:221], 0, s[80:81]
	s_mov_b32 m0, s62
	s_nop 0
	global_load_lds_dwordx4 v[182:183], off
	s_barrier
; #define PG8_STAGE(bufoff, gbase, voff) do { _Pragma("unroll") for (int _i = 0; _i < 2; ++_i) \
;         __builtin_amdgcn_global_load_lds((const unsigned*)((const char*)(gbase) + (voff)[_i]), (LAS unsigned*)(lds + (bufoff) + ldsw + _i * 8192), 16, 0, 0); } while (0)
; #define PG8_MMA(ai, bj, At, Bt) do { __builtin_amdgcn_s_setprio(1); _Pragma("unroll") for (int m = 0; m < 4; ++m) _Pragma("unroll") for (int n = 0; n < 2; ++n) _Pragma("unroll") for (int k = 0; k < 2; ++k) \
;         acc[ai][bj][m][n] = __builtin_amdgcn_mfma_f32_16x16x32_bf16(Bt[n][k], At[m][k], acc[ai][bj][m][n], 0, 0, 0); __builtin_amdgcn_s_setprio(0); } while (0)
; #define PG8_WAIT_V(n) asm volatile("s_waitcnt vmcnt(" #n ")" ::: "memory")
; #define PG8_WAIT_L(n) asm volatile("s_waitcnt lgkmcnt(" #n ")" ::: "memory")
; template <class Epi>
; __device__ __forceinline__ void gemm_phase(LAS unsigned char* lds, const Gemm g, const StaticOrder& S, const Epi& E, const int tid) {
;     ...
;             PG8_BAR; PG8_WAIT_L(0); PG8_MMA(1, 0, At, B0); PG8_BAR; PG8_SCHED;
;             PG8_STAGE(PG8_SB(1, 1), b3 + hstepB, voffB);
;             PG8_WAIT_V(6); PG8_BAR; PG8_MMA(1, 1, At, B1); PG8_BAR;
;     __device__ __forceinline__ void operator()(AccRef acc, const Unit& u, int wr, int wc, int fr, int fq) const {
;         const int row0 = u.pm * 256 + wr * 64 + fr, c0 = u.pn * 256 + wc * 32 + 8 * fq;
; #pragma unroll
;         for (int bj = 0; bj < 2; ++bj) {
;             const f32x4 g0 = *(const f32x4*)(lng + c0 + bj * 128), g1 = *(const f32x4*)(lng + c0 + bj * 128 + 4), b0 = *(const f32x4*)(lnb + c0 + bj * 128), b1 = *(const f32x4*)(lnb + c0 + bj * 128 + 4);
;             const f32x4 cg0 = *(const f32x4*)(cg + c0 + bj * 128), cg1 = *(const f32x4*)(cg + c0 + bj * 128 + 4), cb0 = *(const f32x4*)(cb + c0 + bj * 128), cb1 = *(const f32x4*)(cb + c0 + bj * 128 + 4);
; #pragma unroll
;             for (int ai = 0; ai < 2; ++ai)
; #pragma unroll
;             for (int mh = 0; mh < 4; mh += 2) {
;                 u32x4 pw[4]; f32x4 yv[4][2]; f32x2 st[4];
; #pragma unroll
;                 for (int m = mh; m < mh + 2; ++m) { const int row = row0 + ai * 128 + m * 16; const size_t ro = (size_t)row * DM + c0 + bj * 128;
;                     pw[m] = *(const u32x4*)(PLEB + ro); yv[m][0] = *(const f32x4*)(X + ro); yv[m][1] = *(const f32x4*)(X + ro + 4); st[m] = *(const f32x2*)(stats + 2 * row); }
	s_waitcnt lgkmcnt(0)
	s_setprio 1
	s_waitcnt lgkmcnt(0)
	v_mfma_f32_16x16x32_bf16 v[124:127], v[88:91], v[104:107], v[124:127]
	v_mfma_f32_16x16x32_bf16 v[120:123], v[96:99], v[104:107], v[120:123]
	v_mfma_f32_16x16x32_bf16 v[84:87], v[88:91], v[112:115], v[84:87]
	v_mfma_f32_16x16x32_bf16 v[80:83], v[96:99], v[112:115], v[80:83]
	v_mfma_f32_16x16x32_bf16 v[76:79], v[88:91], v[160:163], v[76:79]
	v_mfma_f32_16x16x32_bf16 v[72:75], v[96:99], v[160:163], v[72:75]
	v_mfma_f32_16x16x32_bf16 v[68:71], v[88:91], v[168:171], v[68:71]
	v_mfma_f32_16x16x32_bf16 v[64:67], v[96:99], v[168:171], v[64:67]
	v_mfma_f32_16x16x32_bf16 v[124:127], v[92:95], v[108:111], v[124:127]
	v_mfma_f32_16x16x32_bf16 v[120:123], v[100:103], v[108:111], v[120:123]
	v_mfma_f32_16x16x32_bf16 v[84:87], v[92:95], v[116:119], v[84:87]
	v_mfma_f32_16x16x32_bf16 v[80:83], v[100:103], v[116:119], v[80:83]
	v_mfma_f32_16x16x32_bf16 v[76:79], v[92:95], v[164:167], v[76:79]
	v_mfma_f32_16x16x32_bf16 v[72:75], v[100:103], v[164:167], v[72:75]
	v_mfma_f32_16x16x32_bf16 v[68:71], v[92:95], v[196:199], v[68:71]
	v_mfma_f32_16x16x32_bf16 v[64:67], v[100:103], v[196:199], v[64:67]
	s_setprio 0
	s_barrier
	s_add_u32 s10, s10, 0x80080
	s_addc_u32 s11, s11, 0
	s_add_i32 s40, s40, s54
	v_lshl_add_u64 v[88:89], s[10:11], 0, v[184:185]
	s_mov_b32 m0, s40
	s_nop 0
	global_load_lds_dwordx4 v[88:89], off
	v_lshl_add_u64 v[88:89], s[10:11], 0, v[172:173]
	s_add_i32 m0, s40, 0x2000
	s_nop 0
	global_load_lds_dwordx4 v[88:89], off
	s_waitcnt vmcnt(6)
	s_barrier
	s_setprio 1
	v_mfma_f32_16x16x32_bf16 v[28:31], v[200:203], v[104:107], v[28:31]
	v_mfma_f32_16x16x32_bf16 v[24:27], v[208:211], v[104:107], v[24:27]
	v_mfma_f32_16x16x32_bf16 v[20:23], v[200:203], v[112:115], v[20:23]
	v_mfma_f32_16x16x32_bf16 v[16:19], v[208:211], v[112:115], v[16:19]
	v_mfma_f32_16x16x32_bf16 v[12:15], v[200:203], v[160:163], v[12:15]
	v_mfma_f32_16x16x32_bf16 v[8:11], v[208:211], v[160:163], v[8:11]
	v_mfma_f32_16x16x32_bf16 v[4:7], v[200:203], v[168:171], v[4:7]
	v_mfma_f32_16x16x32_bf16 v[0:3], v[208:211], v[168:171], v[0:3]
	v_mfma_f32_16x16x32_bf16 v[28:31], v[204:207], v[108:111], v[28:31]
	v_mfma_f32_16x16x32_bf16 v[24:27], v[212:215], v[108:111], v[24:27]
	v_mfma_f32_16x16x32_bf16 v[20:23], v[204:207], v[116:119], v[20:23]
	v_mfma_f32_16x16x32_bf16 v[16:19], v[212:215], v[116:119], v[16:19]
	v_mfma_f32_16x16x32_bf16 v[12:15], v[204:207], v[164:167], v[12:15]
	v_mfma_f32_16x16x32_bf16 v[8:11], v[212:215], v[164:167], v[8:11]
	v_mfma_f32_16x16x32_bf16 v[4:7], v[204:207], v[196:199], v[4:7]
	v_mfma_f32_16x16x32_bf16 v[0:3], v[212:215], v[196:199], v[0:3]
	s_setprio 0
	s_add_i32 s48, s48, 2
	s_add_u32 s8, s8, 0x100
	s_addc_u32 s9, s9, 0
	s_add_u32 s42, s42, 0x100
	s_addc_u32 s43, s43, 0
	s_cmp_gt_u32 s48, 29
	s_barrier
	s_cbranch_scc0 .LBB0_890
	v_lshl_add_u32 v243, s64, 8, v186
	v_lshl_or_b32 v244, s3, 8, v192
	v_lshlrev_b32_e32 v243, 13, v243
	v_lshl_add_u32 v242, v244, 2, v243
	v_lshl_or_b32 v244, s3, 8, v192
	v_lshlrev_b32_e32 v244, 2, v244
	global_load_dwordx4 v[88:91], v244, s[26:27]
	global_load_dwordx4 v[92:95], v244, s[26:27] offset:16
	global_load_dwordx4 v[96:99], v244, s[28:29]
	global_load_dwordx4 v[100:103], v244, s[28:29] offset:16
	global_load_dwordx4 v[104:107], v244, s[14:15]
	global_load_dwordx4 v[108:111], v244, s[14:15] offset:16
	global_load_dwordx4 v[112:115], v244, s[24:25]
	global_load_dwordx4 v[116:119], v244, s[24:25] offset:16
	v_mov_b32_e32 v243, v242
	global_load_dwordx4 v[200:203], v243, s[12:13]
	global_load_dwordx4 v[204:207], v243, s[12:13] offset:16
	v_lshrrev_b32_e32 v244, 1, v243
	global_load_dwordx4 v[196:199], v244, s[20:21]
	v_lshrrev_b32_e32 v244, 10, v243
	v_and_b32_e32 v244, -8, v244
	global_load_dwordx2 v[208:209], v244, s[22:23]
	v_add_u32_e32 v243, 0x20000, v242
	global_load_dwordx4 v[214:217], v243, s[12:13]
	global_load_dwordx4 v[218:221], v243, s[12:13] offset:16
	v_lshrrev_b32_e32 v244, 1, v243
	global_load_dwordx4 v[210:213], v244, s[20:21]
	v_lshrrev_b32_e32 v244, 10, v243
	v_and_b32_e32 v244, -8, v244
	global_load_dwordx2 v[222:223], v244, s[22:23]
	v_add_u32_e32 v243, 0x40000, v242
	global_load_dwordx4 v[228:231], v243, s[12:13]
	global_load_dwordx4 v[232:235], v243, s[12:13] offset:16
	v_lshrrev_b32_e32 v244, 1, v243
	global_load_dwordx4 v[224:227], v244, s[20:21]
	v_lshrrev_b32_e32 v244, 10, v243
	v_and_b32_e32 v244, -8, v244
	global_load_dwordx2 v[236:237], v244, s[22:23]
	s_waitcnt vmcnt(8)
; __device__ __forceinline__ f32x4 sig4(f32x4 v) { return (f32x4){sigmoidf_(v[0]), sigmoidf_(v[1]), sigmoidf_(v[2]), sigmoidf_(v[3])}; }
; __device__ __forceinline__ void unpack8(u32x4 w, f32x4& a, f32x4& b) { a = (f32x4){bf_lo(w.x), bf_hi(w.x), bf_lo(w.y), bf_hi(w.y)}; b = (f32x4){bf_lo(w.z), bf_hi(w.z), bf_lo(w.w), bf_hi(w.w)}; }
; __device__ __forceinline__ u32x4 pack8(f32x4 a, f32x4 b) { u32x4 w; w.x = cvt_pk_bf16(a[0], a[1]); w.y = cvt_pk_bf16(a[2], a[3]); w.z = cvt_pk_bf16(b[0], b[1]); w.w = cvt_pk_bf16(b[2], b[3]); return w; }
;     __device__ __forceinline__ void operator()(AccRef acc, const Unit& u, int wr, int wc, int fr, int fq) const {
;     ...
;                 for (int m = mh; m < mh + 2; ++m) { const int row = row0 + ai * 128 + m * 16; const size_t ro = (size_t)row * DM + c0 + bj * 128;
;                     const float mu = st[m].x * (1.f / DM), var = st[m].y * (1.f / DM) - mu * mu, r = 1.f / sqrtf(var + LN_EPS);
;                     f32x4 p0, p1; unpack8(pw[m], p0, p1);
;                     const f32x4 x0 = (yv[m][0] - mu) * r * g0 + b0, x1 = (yv[m][1] - mu) * r * g1 + b1;
;                     const f32x4 o0 = x0 + sig4((acc[ai][bj][m][0] - mu * cg0) * r + cb0) * p0, o1 = x1 + sig4((acc[ai][bj][m][1] - mu * cg1) * r + cb1) * p1;
;                     *(f32x4*)(X + ro) = o0; *(f32x4*)(X + ro + 4) = o1; if (XB) *(u32x4*)(XB + ro) = pack8(o0, o1); }
	v_mul_f32_e32 v168, 0x3a000000, v208
	v_mul_f32_e32 v171, 0x3a000000, v209
	v_fma_f32 v170, -v168, v168, v171
	v_add_f32_e32 v170, 0x3727c5ac, v170
	v_cmp_gt_f32_e32 vcc, s33, v170
	v_mul_f32_e32 v171, 0x4f800000, v170
	s_nop 0
	v_cndmask_b32_e32 v170, v170, v171, vcc
	v_sqrt_f32_e32 v171, v170
	v_lshlrev_b32_e32 v160, 16, v196
	v_and_b32_e32 v161, 0xffff0000, v196
	v_lshlrev_b32_e32 v162, 16, v197
	v_and_b32_e32 v163, 0xffff0000, v197
	v_lshlrev_b32_e32 v164, 16, v198
	v_and_b32_e32 v165, 0xffff0000, v198
	v_lshlrev_b32_e32 v166, 16, v199
	v_and_b32_e32 v167, 0xffff0000, v199
	v_add_u32_e32 v238, -1, v171
	v_fma_f32 v239, -v238, v171, v170
	v_cmp_ge_f32_e64 s[8:9], 0, v239
	v_add_u32_e32 v239, 1, v171
	s_nop 0
	v_cndmask_b32_e64 v238, v171, v238, s[8:9]
	v_fma_f32 v171, -v239, v171, v170
	v_cmp_lt_f32_e64 s[8:9], 0, v171
	s_nop 1
	v_cndmask_b32_e64 v171, v238, v239, s[8:9]
	v_mul_f32_e32 v238, 0x37800000, v171
	v_cndmask_b32_e32 v171, v171, v238, vcc
	v_cmp_class_f32_e32 vcc, v170, v249
	s_nop 1
	v_cndmask_b32_e32 v170, v171, v170, vcc
	v_div_scale_f32 v171, s[4:5], v170, v170, 1.0
	v_rcp_f32_e32 v238, v171
	s_nop 0
	v_fma_f32 v239, -v171, v238, 1.0
	v_fmac_f32_e32 v238, v239, v238
	v_div_scale_f32 v239, vcc, 1.0, v170, 1.0
	v_mul_f32_e32 v240, v239, v238
	v_fma_f32 v241, -v171, v240, v239
	v_fmac_f32_e32 v240, v241, v238
	v_fma_f32 v171, -v171, v240, v239
	v_div_fmas_f32 v171, v171, v238, v240
	v_div_fixup_f32 v169, v171, v170, 1.0
	v_fma_f32 v156, -v104, v168, v156
	v_fma_f32 v157, -v105, v168, v157
	v_fma_f32 v158, -v106, v168, v158
	v_fma_f32 v159, -v107, v168, v159
	v_fma_f32 v152, -v108, v168, v152
	v_fma_f32 v153, -v109, v168, v153
	v_fma_f32 v154, -v110, v168, v154
	v_fma_f32 v155, -v111, v168, v155
	v_sub_f32_e32 v200, v200, v168
	v_sub_f32_e32 v201, v201, v168
	v_sub_f32_e32 v202, v202, v168
	v_sub_f32_e32 v203, v203, v168
	v_sub_f32_e32 v204, v204, v168
	v_sub_f32_e32 v205, v205, v168
	v_sub_f32_e32 v206, v206, v168
	v_sub_f32_e32 v207, v207, v168
	v_fma_f32 v156, v156, v169, v112
	v_fma_f32 v157, v157, v169, v113
	v_fma_f32 v158, v158, v169, v114
	v_fma_f32 v159, v159, v169, v115
	v_fma_f32 v152, v152, v169, v116
	v_fma_f32 v153, v153, v169, v117
	v_fma_f32 v154, v154, v169, v118
	v_fma_f32 v155, v155, v169, v119
	v_mul_f32_e32 v200, v200, v169
	v_mul_f32_e32 v201, v201, v169
	v_mul_f32_e32 v202, v202, v169
	v_mul_f32_e32 v203, v203, v169
	v_mul_f32_e32 v204, v204, v169
	v_mul_f32_e32 v205, v205, v169
	v_mul_f32_e32 v206, v206, v169
	v_mul_f32_e32 v207, v207, v169
	v_mul_f32_e32 v156, 0xbfb8aa3b, v156
	v_mul_f32_e32 v157, 0xbfb8aa3b, v157
	v_mul_f32_e32 v158, 0xbfb8aa3b, v158
	v_mul_f32_e32 v159, 0xbfb8aa3b, v159
	v_mul_f32_e32 v152, 0xbfb8aa3b, v152
	v_mul_f32_e32 v153, 0xbfb8aa3b, v153
	v_mul_f32_e32 v154, 0xbfb8aa3b, v154
	v_mul_f32_e32 v155, 0xbfb8aa3b, v155
	v_fma_f32 v200, v88, v200, v96
	v_fma_f32 v201, v89, v201, v97
	v_fma_f32 v202, v90, v202, v98
	v_fma_f32 v203, v91, v203, v99
	v_fma_f32 v204, v92, v204, v100
	v_fma_f32 v205, v93, v205, v101
	v_fma_f32 v206, v94, v206, v102
	v_fma_f32 v207, v95, v207, v103
	v_exp_f32_e32 v156, v156
	v_exp_f32_e32 v157, v157
	v_exp_f32_e32 v158, v158
	v_exp_f32_e32 v159, v159
	v_exp_f32_e32 v152, v152
	v_exp_f32_e32 v153, v153
	v_exp_f32_e32 v154, v154
	v_exp_f32_e32 v155, v155
	v_add_f32_e32 v156, 1.0, v156
	v_add_f32_e32 v157, 1.0, v157
	v_add_f32_e32 v158, 1.0, v158
	v_add_f32_e32 v159, 1.0, v159
	v_add_f32_e32 v152, 1.0, v152
	v_add_f32_e32 v153, 1.0, v153
	v_add_f32_e32 v154, 1.0, v154
	v_add_f32_e32 v155, 1.0, v155
	v_rcp_f32_e32 v156, v156
	v_rcp_f32_e32 v157, v157
	v_rcp_f32_e32 v158, v158
	v_rcp_f32_e32 v159, v159
	v_rcp_f32_e32 v152, v152
	v_rcp_f32_e32 v153, v153
	v_rcp_f32_e32 v154, v154
	v_rcp_f32_e32 v155, v155
	v_fma_f32 v200, v156, v160, v200
	v_fma_f32 v201, v157, v161, v201
	v_fma_f32 v202, v158, v162, v202
	v_fma_f32 v203, v159, v163, v203
	v_fma_f32 v204, v152, v164, v204
	v_fma_f32 v205, v153, v165, v205
	v_fma_f32 v206, v154, v166, v206
	v_fma_f32 v207, v155, v167, v207
	v_mov_b32_e32 v243, v242
	global_store_dwordx4 v243, v[200:203], s[12:13]
	global_store_dwordx4 v243, v[204:207], s[12:13] offset:16
	s_and_b64 s[4:5], exec, s[16:17]
	s_cbranch_scc0 .Leg_noxb_0
	v_cvt_pk_bf16_f32 v196, v200, v201
	v_cvt_pk_bf16_f32 v197, v202, v203
	v_cvt_pk_bf16_f32 v198, v204, v205
	v_cvt_pk_bf16_f32 v199, v206, v207
	v_lshrrev_b32_e32 v244, 1, v243
	global_store_dwordx4 v244, v[196:199], s[18:19]
; __device__ __forceinline__ f32x4 sig4(f32x4 v) { return (f32x4){sigmoidf_(v[0]), sigmoidf_(v[1]), sigmoidf_(v[2]), sigmoidf_(v[3])}; }
; __device__ __forceinline__ void unpack8(u32x4 w, f32x4& a, f32x4& b) { a = (f32x4){bf_lo(w.x), bf_hi(w.x), bf_lo(w.y), bf_hi(w.y)}; b = (f32x4){bf_lo(w.z), bf_hi(w.z), bf_lo(w.w), bf_hi(w.w)}; }
; __device__ __forceinline__ u32x4 pack8(f32x4 a, f32x4 b) { u32x4 w; w.x = cvt_pk_bf16(a[0], a[1]); w.y = cvt_pk_bf16(a[2], a[3]); w.z = cvt_pk_bf16(b[0], b[1]); w.w = cvt_pk_bf16(b[2], b[3]); return w; }
;     __device__ __forceinline__ void operator()(AccRef acc, const Unit& u, int wr, int wc, int fr, int fq) const {
;     ...
;                 for (int m = mh; m < mh + 2; ++m) { const int row = row0 + ai * 128 + m * 16; const size_t ro = (size_t)row * DM + c0 + bj * 128;
;                     pw[m] = *(const u32x4*)(PLEB + ro); yv[m][0] = *(const f32x4*)(X + ro); yv[m][1] = *(const f32x4*)(X + ro + 4); st[m] = *(const f32x2*)(stats + 2 * row); }
; #pragma unroll
;                 for (int m = mh; m < mh + 2; ++m) { const int row = row0 + ai * 128 + m * 16; const size_t ro = (size_t)row * DM + c0 + bj * 128;
;                     const float mu = st[m].x * (1.f / DM), var = st[m].y * (1.f / DM) - mu * mu, r = 1.f / sqrtf(var + LN_EPS);
;                     f32x4 p0, p1; unpack8(pw[m], p0, p1);
;                     const f32x4 x0 = (yv[m][0] - mu) * r * g0 + b0, x1 = (yv[m][1] - mu) * r * g1 + b1;
;                     const f32x4 o0 = x0 + sig4((acc[ai][bj][m][0] - mu * cg0) * r + cb0) * p0, o1 = x1 + sig4((acc[ai][bj][m][1] - mu * cg1) * r + cb1) * p1;
;                     *(f32x4*)(X + ro) = o0; *(f32x4*)(X + ro + 4) = o1; if (XB) *(u32x4*)(XB + ro) = pack8(o0, o1); }
.Leg_noxb_0:
	v_add_u32_e32 v243, 0x60000, v242
	global_load_dwordx4 v[200:203], v243, s[12:13]
	global_load_dwordx4 v[204:207], v243, s[12:13] offset:16
	v_lshrrev_b32_e32 v244, 1, v243
	global_load_dwordx4 v[196:199], v244, s[20:21]
	v_lshrrev_b32_e32 v244, 10, v243
	v_and_b32_e32 v244, -8, v244
	global_load_dwordx2 v[208:209], v244, s[22:23]
	s_waitcnt vmcnt(10)
	v_mul_f32_e32 v168, 0x3a000000, v222
	v_mul_f32_e32 v171, 0x3a000000, v223
	v_fma_f32 v170, -v168, v168, v171
	v_add_f32_e32 v170, 0x3727c5ac, v170
	v_cmp_gt_f32_e32 vcc, s33, v170
	v_mul_f32_e32 v171, 0x4f800000, v170
	s_nop 0
	v_cndmask_b32_e32 v170, v170, v171, vcc
	v_sqrt_f32_e32 v171, v170
	v_lshlrev_b32_e32 v160, 16, v210
	v_and_b32_e32 v161, 0xffff0000, v210
	v_lshlrev_b32_e32 v162, 16, v211
	v_and_b32_e32 v163, 0xffff0000, v211
	v_lshlrev_b32_e32 v164, 16, v212
	v_and_b32_e32 v165, 0xffff0000, v212
	v_lshlrev_b32_e32 v166, 16, v213
	v_and_b32_e32 v167, 0xffff0000, v213
	v_add_u32_e32 v238, -1, v171
	v_fma_f32 v239, -v238, v171, v170
	v_cmp_ge_f32_e64 s[8:9], 0, v239
	v_add_u32_e32 v239, 1, v171
	s_nop 0
	v_cndmask_b32_e64 v238, v171, v238, s[8:9]
	v_fma_f32 v171, -v239, v171, v170
	v_cmp_lt_f32_e64 s[8:9], 0, v171
	s_nop 1
	v_cndmask_b32_e64 v171, v238, v239, s[8:9]
	v_mul_f32_e32 v238, 0x37800000, v171
	v_cndmask_b32_e32 v171, v171, v238, vcc
	v_cmp_class_f32_e32 vcc, v170, v249
	s_nop 1
	v_cndmask_b32_e32 v170, v171, v170, vcc
	v_div_scale_f32 v171, s[4:5], v170, v170, 1.0
	v_rcp_f32_e32 v238, v171
	s_nop 0
	v_fma_f32 v239, -v171, v238, 1.0
	v_fmac_f32_e32 v238, v239, v238
	v_div_scale_f32 v239, vcc, 1.0, v170, 1.0
	v_mul_f32_e32 v240, v239, v238
	v_fma_f32 v241, -v171, v240, v239
	v_fmac_f32_e32 v240, v241, v238
	v_fma_f32 v171, -v171, v240, v239
	v_div_fmas_f32 v171, v171, v238, v240
	v_div_fixup_f32 v169, v171, v170, 1.0
	v_fma_f32 v148, -v104, v168, v148
	v_fma_f32 v149, -v105, v168, v149
	v_fma_f32 v150, -v106, v168, v150
	v_fma_f32 v151, -v107, v168, v151
	v_fma_f32 v144, -v108, v168, v144
	v_fma_f32 v145, -v109, v168, v145
	v_fma_f32 v146, -v110, v168, v146
	v_fma_f32 v147, -v111, v168, v147
	v_sub_f32_e32 v214, v214, v168
	v_sub_f32_e32 v215, v215, v168
	v_sub_f32_e32 v216, v216, v168
	v_sub_f32_e32 v217, v217, v168
	v_sub_f32_e32 v218, v218, v168
	v_sub_f32_e32 v219, v219, v168
	v_sub_f32_e32 v220, v220, v168
	v_sub_f32_e32 v221, v221, v168
	v_fma_f32 v148, v148, v169, v112
	v_fma_f32 v149, v149, v169, v113
	v_fma_f32 v150, v150, v169, v114
	v_fma_f32 v151, v151, v169, v115
	v_fma_f32 v144, v144, v169, v116
	v_fma_f32 v145, v145, v169, v117
	v_fma_f32 v146, v146, v169, v118
	v_fma_f32 v147, v147, v169, v119
	v_mul_f32_e32 v214, v214, v169
	v_mul_f32_e32 v215, v215, v169
	v_mul_f32_e32 v216, v216, v169
	v_mul_f32_e32 v217, v217, v169
	v_mul_f32_e32 v218, v218, v169
	v_mul_f32_e32 v219, v219, v169
	v_mul_f32_e32 v220, v220, v169
	v_mul_f32_e32 v221, v221, v169
	v_mul_f32_e32 v148, 0xbfb8aa3b, v148
	v_mul_f32_e32 v149, 0xbfb8aa3b, v149
	v_mul_f32_e32 v150, 0xbfb8aa3b, v150
	v_mul_f32_e32 v151, 0xbfb8aa3b, v151
	v_mul_f32_e32 v144, 0xbfb8aa3b, v144
	v_mul_f32_e32 v145, 0xbfb8aa3b, v145
	v_mul_f32_e32 v146, 0xbfb8aa3b, v146
	v_mul_f32_e32 v147, 0xbfb8aa3b, v147
	v_fma_f32 v214, v88, v214, v96
	v_fma_f32 v215, v89, v215, v97
	v_fma_f32 v216, v90, v216, v98
	v_fma_f32 v217, v91, v217, v99
	v_fma_f32 v218, v92, v218, v100
	v_fma_f32 v219, v93, v219, v101
	v_fma_f32 v220, v94, v220, v102
	v_fma_f32 v221, v95, v221, v103
	v_exp_f32_e32 v148, v148
	v_exp_f32_e32 v149, v149
	v_exp_f32_e32 v150, v150
	v_exp_f32_e32 v151, v151
	v_exp_f32_e32 v144, v144
	v_exp_f32_e32 v145, v145
	v_exp_f32_e32 v146, v146
	v_exp_f32_e32 v147, v147
	v_add_f32_e32 v148, 1.0, v148
	v_add_f32_e32 v149, 1.0, v149
	v_add_f32_e32 v150, 1.0, v150
	v_add_f32_e32 v151, 1.0, v151
	v_add_f32_e32 v144, 1.0, v144
	v_add_f32_e32 v145, 1.0, v145
	v_add_f32_e32 v146, 1.0, v146
	v_add_f32_e32 v147, 1.0, v147
	v_rcp_f32_e32 v148, v148
	v_rcp_f32_e32 v149, v149
	v_rcp_f32_e32 v150, v150
	v_rcp_f32_e32 v151, v151
	v_rcp_f32_e32 v144, v144
	v_rcp_f32_e32 v145, v145
	v_rcp_f32_e32 v146, v146
	v_rcp_f32_e32 v147, v147
	v_fma_f32 v214, v148, v160, v214
	v_fma_f32 v215, v149, v161, v215
	v_fma_f32 v216, v150, v162, v216
	v_fma_f32 v217, v151, v163, v217
	v_fma_f32 v218, v144, v164, v218
	v_fma_f32 v219, v145, v165, v219
	v_fma_f32 v220, v146, v166, v220
	v_fma_f32 v221, v147, v167, v221
	v_add_u32_e32 v243, 0x20000, v242
	global_store_dwordx4 v243, v[214:217], s[12:13]
	global_store_dwordx4 v243, v[218:221], s[12:13] offset:16
	s_and_b64 s[4:5], exec, s[16:17]
	s_cbranch_scc0 .Leg_noxb_1
	v_cvt_pk_bf16_f32 v210, v214, v215
	v_cvt_pk_bf16_f32 v211, v216, v217
	v_cvt_pk_bf16_f32 v212, v218, v219
	v_cvt_pk_bf16_f32 v213, v220, v221
	v_lshrrev_b32_e32 v244, 1, v243
	global_store_dwordx4 v244, v[210:213], s[18:19]
; __device__ __forceinline__ f32x4 sig4(f32x4 v) { return (f32x4){sigmoidf_(v[0]), sigmoidf_(v[1]), sigmoidf_(v[2]), sigmoidf_(v[3])}; }
; __device__ __forceinline__ void unpack8(u32x4 w, f32x4& a, f32x4& b) { a = (f32x4){bf_lo(w.x), bf_hi(w.x), bf_lo(w.y), bf_hi(w.y)}; b = (f32x4){bf_lo(w.z), bf_hi(w.z), bf_lo(w.w), bf_hi(w.w)}; }
; __device__ __forceinline__ u32x4 pack8(f32x4 a, f32x4 b) { u32x4 w; w.x = cvt_pk_bf16(a[0], a[1]); w.y = cvt_pk_bf16(a[2], a[3]); w.z = cvt_pk_bf16(b[0], b[1]); w.w = cvt_pk_bf16(b[2], b[3]); return w; }
;     __device__ __forceinline__ void operator()(AccRef acc, const Unit& u, int wr, int wc, int fr, int fq) const {
;     ...
;                 for (int m = mh; m < mh + 2; ++m) { const int row = row0 + ai * 128 + m * 16; const size_t ro = (size_t)row * DM + c0 + bj * 128;
;                     pw[m] = *(const u32x4*)(PLEB + ro); yv[m][0] = *(const f32x4*)(X + ro); yv[m][1] = *(const f32x4*)(X + ro + 4); st[m] = *(const f32x2*)(stats + 2 * row); }
; #pragma unroll
;                 for (int m = mh; m < mh + 2; ++m) { const int row = row0 + ai * 128 + m * 16; const size_t ro = (size_t)row * DM + c0 + bj * 128;
;                     const float mu = st[m].x * (1.f / DM), var = st[m].y * (1.f / DM) - mu * mu, r = 1.f / sqrtf(var + LN_EPS);
;                     f32x4 p0, p1; unpack8(pw[m], p0, p1);
;                     const f32x4 x0 = (yv[m][0] - mu) * r * g0 + b0, x1 = (yv[m][1] - mu) * r * g1 + b1;
;                     const f32x4 o0 = x0 + sig4((acc[ai][bj][m][0] - mu * cg0) * r + cb0) * p0, o1 = x1 + sig4((acc[ai][bj][m][1] - mu * cg1) * r + cb1) * p1;
;                     *(f32x4*)(X + ro) = o0; *(f32x4*)(X + ro + 4) = o1; if (XB) *(u32x4*)(XB + ro) = pack8(o0, o1); }
.Leg_noxb_1:
	v_add_u32_e32 v243, 0x100000, v242
	global_load_dwordx4 v[214:217], v243, s[12:13]
	global_load_dwordx4 v[218:221], v243, s[12:13] offset:16
	v_lshrrev_b32_e32 v244, 1, v243
	global_load_dwordx4 v[210:213], v244, s[20:21]
	v_lshrrev_b32_e32 v244, 10, v243
	v_and_b32_e32 v244, -8, v244
	global_load_dwordx2 v[222:223], v244, s[22:23]
	s_waitcnt vmcnt(12)
	v_mul_f32_e32 v168, 0x3a000000, v236
	v_mul_f32_e32 v171, 0x3a000000, v237
	v_fma_f32 v170, -v168, v168, v171
	v_add_f32_e32 v170, 0x3727c5ac, v170
	v_cmp_gt_f32_e32 vcc, s33, v170
	v_mul_f32_e32 v171, 0x4f800000, v170
	s_nop 0
	v_cndmask_b32_e32 v170, v170, v171, vcc
	v_sqrt_f32_e32 v171, v170
	v_lshlrev_b32_e32 v160, 16, v224
	v_and_b32_e32 v161, 0xffff0000, v224
	v_lshlrev_b32_e32 v162, 16, v225
	v_and_b32_e32 v163, 0xffff0000, v225
	v_lshlrev_b32_e32 v164, 16, v226
	v_and_b32_e32 v165, 0xffff0000, v226
	v_lshlrev_b32_e32 v166, 16, v227
	v_and_b32_e32 v167, 0xffff0000, v227
	v_add_u32_e32 v238, -1, v171
	v_fma_f32 v239, -v238, v171, v170
	v_cmp_ge_f32_e64 s[8:9], 0, v239
	v_add_u32_e32 v239, 1, v171
	s_nop 0
	v_cndmask_b32_e64 v238, v171, v238, s[8:9]
	v_fma_f32 v171, -v239, v171, v170
	v_cmp_lt_f32_e64 s[8:9], 0, v171
	s_nop 1
	v_cndmask_b32_e64 v171, v238, v239, s[8:9]
	v_mul_f32_e32 v238, 0x37800000, v171
	v_cndmask_b32_e32 v171, v171, v238, vcc
	v_cmp_class_f32_e32 vcc, v170, v249
	s_nop 1
	v_cndmask_b32_e32 v170, v171, v170, vcc
	v_div_scale_f32 v171, s[4:5], v170, v170, 1.0
	v_rcp_f32_e32 v238, v171
	s_nop 0
	v_fma_f32 v239, -v171, v238, 1.0
	v_fmac_f32_e32 v238, v239, v238
	v_div_scale_f32 v239, vcc, 1.0, v170, 1.0
	v_mul_f32_e32 v240, v239, v238
	v_fma_f32 v241, -v171, v240, v239
	v_fmac_f32_e32 v240, v241, v238
	v_fma_f32 v171, -v171, v240, v239
	v_div_fmas_f32 v171, v171, v238, v240
	v_div_fixup_f32 v169, v171, v170, 1.0
	v_fma_f32 v140, -v104, v168, v140
	v_fma_f32 v141, -v105, v168, v141
	v_fma_f32 v142, -v106, v168, v142
	v_fma_f32 v143, -v107, v168, v143
	v_fma_f32 v136, -v108, v168, v136
	v_fma_f32 v137, -v109, v168, v137
	v_fma_f32 v138, -v110, v168, v138
	v_fma_f32 v139, -v111, v168, v139
	v_sub_f32_e32 v228, v228, v168
	v_sub_f32_e32 v229, v229, v168
	v_sub_f32_e32 v230, v230, v168
	v_sub_f32_e32 v231, v231, v168
	v_sub_f32_e32 v232, v232, v168
	v_sub_f32_e32 v233, v233, v168
	v_sub_f32_e32 v234, v234, v168
	v_sub_f32_e32 v235, v235, v168
	v_fma_f32 v140, v140, v169, v112
	v_fma_f32 v141, v141, v169, v113
	v_fma_f32 v142, v142, v169, v114
	v_fma_f32 v143, v143, v169, v115
	v_fma_f32 v136, v136, v169, v116
	v_fma_f32 v137, v137, v169, v117
	v_fma_f32 v138, v138, v169, v118
	v_fma_f32 v139, v139, v169, v119
	v_mul_f32_e32 v228, v228, v169
	v_mul_f32_e32 v229, v229, v169
	v_mul_f32_e32 v230, v230, v169
	v_mul_f32_e32 v231, v231, v169
	v_mul_f32_e32 v232, v232, v169
	v_mul_f32_e32 v233, v233, v169
	v_mul_f32_e32 v234, v234, v169
	v_mul_f32_e32 v235, v235, v169
	v_mul_f32_e32 v140, 0xbfb8aa3b, v140
	v_mul_f32_e32 v141, 0xbfb8aa3b, v141
	v_mul_f32_e32 v142, 0xbfb8aa3b, v142
	v_mul_f32_e32 v143, 0xbfb8aa3b, v143
	v_mul_f32_e32 v136, 0xbfb8aa3b, v136
	v_mul_f32_e32 v137, 0xbfb8aa3b, v137
	v_mul_f32_e32 v138, 0xbfb8aa3b, v138
	v_mul_f32_e32 v139, 0xbfb8aa3b, v139
	v_fma_f32 v228, v88, v228, v96
	v_fma_f32 v229, v89, v229, v97
	v_fma_f32 v230, v90, v230, v98
	v_fma_f32 v231, v91, v231, v99
	v_fma_f32 v232, v92, v232, v100
	v_fma_f32 v233, v93, v233, v101
	v_fma_f32 v234, v94, v234, v102
	v_fma_f32 v235, v95, v235, v103
	v_exp_f32_e32 v140, v140
	v_exp_f32_e32 v141, v141
	v_exp_f32_e32 v142, v142
	v_exp_f32_e32 v143, v143
	v_exp_f32_e32 v136, v136
	v_exp_f32_e32 v137, v137
	v_exp_f32_e32 v138, v138
	v_exp_f32_e32 v139, v139
	v_add_f32_e32 v140, 1.0, v140
	v_add_f32_e32 v141, 1.0, v141
	v_add_f32_e32 v142, 1.0, v142
	v_add_f32_e32 v143, 1.0, v143
	v_add_f32_e32 v136, 1.0, v136
	v_add_f32_e32 v137, 1.0, v137
	v_add_f32_e32 v138, 1.0, v138
	v_add_f32_e32 v139, 1.0, v139
	v_rcp_f32_e32 v140, v140
	v_rcp_f32_e32 v141, v141
	v_rcp_f32_e32 v142, v142
	v_rcp_f32_e32 v143, v143
	v_rcp_f32_e32 v136, v136
	v_rcp_f32_e32 v137, v137
	v_rcp_f32_e32 v138, v138
	v_rcp_f32_e32 v139, v139
	v_fma_f32 v228, v140, v160, v228
	v_fma_f32 v229, v141, v161, v229
	v_fma_f32 v230, v142, v162, v230
	v_fma_f32 v231, v143, v163, v231
	v_fma_f32 v232, v136, v164, v232
	v_fma_f32 v233, v137, v165, v233
	v_fma_f32 v234, v138, v166, v234
	v_fma_f32 v235, v139, v167, v235
	v_add_u32_e32 v243, 0x40000, v242
	global_store_dwordx4 v243, v[228:231], s[12:13]
	global_store_dwordx4 v243, v[232:235], s[12:13] offset:16
	s_and_b64 s[4:5], exec, s[16:17]
	s_cbranch_scc0 .Leg_noxb_2
	v_cvt_pk_bf16_f32 v224, v228, v229
	v_cvt_pk_bf16_f32 v225, v230, v231
	v_cvt_pk_bf16_f32 v226, v232, v233
	v_cvt_pk_bf16_f32 v227, v234, v235
	v_lshrrev_b32_e32 v244, 1, v243
	global_store_dwordx4 v244, v[224:227], s[18:19]
; __device__ __forceinline__ f32x4 sig4(f32x4 v) { return (f32x4){sigmoidf_(v[0]), sigmoidf_(v[1]), sigmoidf_(v[2]), sigmoidf_(v[3])}; }
; __device__ __forceinline__ void unpack8(u32x4 w, f32x4& a, f32x4& b) { a = (f32x4){bf_lo(w.x), bf_hi(w.x), bf_lo(w.y), bf_hi(w.y)}; b = (f32x4){bf_lo(w.z), bf_hi(w.z), bf_lo(w.w), bf_hi(w.w)}; }
; __device__ __forceinline__ u32x4 pack8(f32x4 a, f32x4 b) { u32x4 w; w.x = cvt_pk_bf16(a[0], a[1]); w.y = cvt_pk_bf16(a[2], a[3]); w.z = cvt_pk_bf16(b[0], b[1]); w.w = cvt_pk_bf16(b[2], b[3]); return w; }
;     __device__ __forceinline__ void operator()(AccRef acc, const Unit& u, int wr, int wc, int fr, int fq) const {
;     ...
;                 for (int m = mh; m < mh + 2; ++m) { const int row = row0 + ai * 128 + m * 16; const size_t ro = (size_t)row * DM + c0 + bj * 128;
;                     pw[m] = *(const u32x4*)(PLEB + ro); yv[m][0] = *(const f32x4*)(X + ro); yv[m][1] = *(const f32x4*)(X + ro + 4); st[m] = *(const f32x2*)(stats + 2 * row); }
; #pragma unroll
;                 for (int m = mh; m < mh + 2; ++m) { const int row = row0 + ai * 128 + m * 16; const size_t ro = (size_t)row * DM + c0 + bj * 128;
;                     const float mu = st[m].x * (1.f / DM), var = st[m].y * (1.f / DM) - mu * mu, r = 1.f / sqrtf(var + LN_EPS);
;                     f32x4 p0, p1; unpack8(pw[m], p0, p1);
;                     const f32x4 x0 = (yv[m][0] - mu) * r * g0 + b0, x1 = (yv[m][1] - mu) * r * g1 + b1;
;                     const f32x4 o0 = x0 + sig4((acc[ai][bj][m][0] - mu * cg0) * r + cb0) * p0, o1 = x1 + sig4((acc[ai][bj][m][1] - mu * cg1) * r + cb1) * p1;
;                     *(f32x4*)(X + ro) = o0; *(f32x4*)(X + ro + 4) = o1; if (XB) *(u32x4*)(XB + ro) = pack8(o0, o1); }
.Leg_noxb_2:
	v_add_u32_e32 v243, 0x120000, v242
	global_load_dwordx4 v[228:231], v243, s[12:13]
	global_load_dwordx4 v[232:235], v243, s[12:13] offset:16
	v_lshrrev_b32_e32 v244, 1, v243
	global_load_dwordx4 v[224:227], v244, s[20:21]
	v_lshrrev_b32_e32 v244, 10, v243
	v_and_b32_e32 v244, -8, v244
	global_load_dwordx2 v[236:237], v244, s[22:23]
	s_waitcnt vmcnt(12)
	v_mul_f32_e32 v168, 0x3a000000, v208
	v_mul_f32_e32 v171, 0x3a000000, v209
	v_fma_f32 v170, -v168, v168, v171
	v_add_f32_e32 v170, 0x3727c5ac, v170
	v_cmp_gt_f32_e32 vcc, s33, v170
	v_mul_f32_e32 v171, 0x4f800000, v170
	s_nop 0
	v_cndmask_b32_e32 v170, v170, v171, vcc
	v_sqrt_f32_e32 v171, v170
	v_lshlrev_b32_e32 v160, 16, v196
	v_and_b32_e32 v161, 0xffff0000, v196
	v_lshlrev_b32_e32 v162, 16, v197
	v_and_b32_e32 v163, 0xffff0000, v197
	v_lshlrev_b32_e32 v164, 16, v198
	v_and_b32_e32 v165, 0xffff0000, v198
	v_lshlrev_b32_e32 v166, 16, v199
	v_and_b32_e32 v167, 0xffff0000, v199
	v_add_u32_e32 v238, -1, v171
	v_fma_f32 v239, -v238, v171, v170
	v_cmp_ge_f32_e64 s[8:9], 0, v239
	v_add_u32_e32 v239, 1, v171
	s_nop 0
	v_cndmask_b32_e64 v238, v171, v238, s[8:9]
	v_fma_f32 v171, -v239, v171, v170
	v_cmp_lt_f32_e64 s[8:9], 0, v171
	s_nop 1
	v_cndmask_b32_e64 v171, v238, v239, s[8:9]
	v_mul_f32_e32 v238, 0x37800000, v171
	v_cndmask_b32_e32 v171, v171, v238, vcc
	v_cmp_class_f32_e32 vcc, v170, v249
	s_nop 1
	v_cndmask_b32_e32 v170, v171, v170, vcc
	v_div_scale_f32 v171, s[4:5], v170, v170, 1.0
	v_rcp_f32_e32 v238, v171
	s_nop 0
	v_fma_f32 v239, -v171, v238, 1.0
	v_fmac_f32_e32 v238, v239, v238
	v_div_scale_f32 v239, vcc, 1.0, v170, 1.0
	v_mul_f32_e32 v240, v239, v238
	v_fma_f32 v241, -v171, v240, v239
	v_fmac_f32_e32 v240, v241, v238
	v_fma_f32 v171, -v171, v240, v239
	v_div_fmas_f32 v171, v171, v238, v240
	v_div_fixup_f32 v169, v171, v170, 1.0
	v_fma_f32 v132, -v104, v168, v132
	v_fma_f32 v133, -v105, v168, v133
	v_fma_f32 v134, -v106, v168, v134
	v_fma_f32 v135, -v107, v168, v135
	v_fma_f32 v128, -v108, v168, v128
	v_fma_f32 v129, -v109, v168, v129
	v_fma_f32 v130, -v110, v168, v130
	v_fma_f32 v131, -v111, v168, v131
	v_sub_f32_e32 v200, v200, v168
	v_sub_f32_e32 v201, v201, v168
	v_sub_f32_e32 v202, v202, v168
	v_sub_f32_e32 v203, v203, v168
	v_sub_f32_e32 v204, v204, v168
	v_sub_f32_e32 v205, v205, v168
	v_sub_f32_e32 v206, v206, v168
	v_sub_f32_e32 v207, v207, v168
	v_fma_f32 v132, v132, v169, v112
	v_fma_f32 v133, v133, v169, v113
	v_fma_f32 v134, v134, v169, v114
	v_fma_f32 v135, v135, v169, v115
	v_fma_f32 v128, v128, v169, v116
	v_fma_f32 v129, v129, v169, v117
	v_fma_f32 v130, v130, v169, v118
	v_fma_f32 v131, v131, v169, v119
	v_mul_f32_e32 v200, v200, v169
	v_mul_f32_e32 v201, v201, v169
	v_mul_f32_e32 v202, v202, v169
	v_mul_f32_e32 v203, v203, v169
	v_mul_f32_e32 v204, v204, v169
	v_mul_f32_e32 v205, v205, v169
	v_mul_f32_e32 v206, v206, v169
	v_mul_f32_e32 v207, v207, v169
	v_mul_f32_e32 v132, 0xbfb8aa3b, v132
	v_mul_f32_e32 v133, 0xbfb8aa3b, v133
	v_mul_f32_e32 v134, 0xbfb8aa3b, v134
	v_mul_f32_e32 v135, 0xbfb8aa3b, v135
	v_mul_f32_e32 v128, 0xbfb8aa3b, v128
	v_mul_f32_e32 v129, 0xbfb8aa3b, v129
	v_mul_f32_e32 v130, 0xbfb8aa3b, v130
	v_mul_f32_e32 v131, 0xbfb8aa3b, v131
	v_fma_f32 v200, v88, v200, v96
	v_fma_f32 v201, v89, v201, v97
	v_fma_f32 v202, v90, v202, v98
	v_fma_f32 v203, v91, v203, v99
	v_fma_f32 v204, v92, v204, v100
	v_fma_f32 v205, v93, v205, v101
	v_fma_f32 v206, v94, v206, v102
	v_fma_f32 v207, v95, v207, v103
	v_exp_f32_e32 v132, v132
	v_exp_f32_e32 v133, v133
	v_exp_f32_e32 v134, v134
	v_exp_f32_e32 v135, v135
	v_exp_f32_e32 v128, v128
	v_exp_f32_e32 v129, v129
	v_exp_f32_e32 v130, v130
	v_exp_f32_e32 v131, v131
	v_add_f32_e32 v132, 1.0, v132
	v_add_f32_e32 v133, 1.0, v133
	v_add_f32_e32 v134, 1.0, v134
	v_add_f32_e32 v135, 1.0, v135
	v_add_f32_e32 v128, 1.0, v128
	v_add_f32_e32 v129, 1.0, v129
	v_add_f32_e32 v130, 1.0, v130
	v_add_f32_e32 v131, 1.0, v131
	v_rcp_f32_e32 v132, v132
	v_rcp_f32_e32 v133, v133
	v_rcp_f32_e32 v134, v134
	v_rcp_f32_e32 v135, v135
	v_rcp_f32_e32 v128, v128
	v_rcp_f32_e32 v129, v129
	v_rcp_f32_e32 v130, v130
	v_rcp_f32_e32 v131, v131
	v_fma_f32 v200, v132, v160, v200
	v_fma_f32 v201, v133, v161, v201
	v_fma_f32 v202, v134, v162, v202
	v_fma_f32 v203, v135, v163, v203
	v_fma_f32 v204, v128, v164, v204
	v_fma_f32 v205, v129, v165, v205
	v_fma_f32 v206, v130, v166, v206
	v_fma_f32 v207, v131, v167, v207
	v_add_u32_e32 v243, 0x60000, v242
	global_store_dwordx4 v243, v[200:203], s[12:13]
	global_store_dwordx4 v243, v[204:207], s[12:13] offset:16
	s_and_b64 s[4:5], exec, s[16:17]
	s_cbranch_scc0 .Leg_noxb_3
	v_cvt_pk_bf16_f32 v196, v200, v201
	v_cvt_pk_bf16_f32 v197, v202, v203
	v_cvt_pk_bf16_f32 v198, v204, v205
	v_cvt_pk_bf16_f32 v199, v206, v207
	v_lshrrev_b32_e32 v244, 1, v243
	global_store_dwordx4 v244, v[196:199], s[18:19]
; __device__ __forceinline__ f32x4 sig4(f32x4 v) { return (f32x4){sigmoidf_(v[0]), sigmoidf_(v[1]), sigmoidf_(v[2]), sigmoidf_(v[3])}; }
; __device__ __forceinline__ void unpack8(u32x4 w, f32x4& a, f32x4& b) { a = (f32x4){bf_lo(w.x), bf_hi(w.x), bf_lo(w.y), bf_hi(w.y)}; b = (f32x4){bf_lo(w.z), bf_hi(w.z), bf_lo(w.w), bf_hi(w.w)}; }
; __device__ __forceinline__ u32x4 pack8(f32x4 a, f32x4 b) { u32x4 w; w.x = cvt_pk_bf16(a[0], a[1]); w.y = cvt_pk_bf16(a[2], a[3]); w.z = cvt_pk_bf16(b[0], b[1]); w.w = cvt_pk_bf16(b[2], b[3]); return w; }
;     __device__ __forceinline__ void operator()(AccRef acc, const Unit& u, int wr, int wc, int fr, int fq) const {
;     ...
;             const f32x4 g0 = *(const f32x4*)(lng + c0 + bj * 128), g1 = *(const f32x4*)(lng + c0 + bj * 128 + 4), b0 = *(const f32x4*)(lnb + c0 + bj * 128), b1 = *(const f32x4*)(lnb + c0 + bj * 128 + 4);
;             const f32x4 cg0 = *(const f32x4*)(cg + c0 + bj * 128), cg1 = *(const f32x4*)(cg + c0 + bj * 128 + 4), cb0 = *(const f32x4*)(cb + c0 + bj * 128), cb1 = *(const f32x4*)(cb + c0 + bj * 128 + 4);
; #pragma unroll
;             for (int ai = 0; ai < 2; ++ai)
; #pragma unroll
;             for (int mh = 0; mh < 4; mh += 2) {
;                 u32x4 pw[4]; f32x4 yv[4][2]; f32x2 st[4];
; #pragma unroll
;                 for (int m = mh; m < mh + 2; ++m) { const int row = row0 + ai * 128 + m * 16; const size_t ro = (size_t)row * DM + c0 + bj * 128;
;                     pw[m] = *(const u32x4*)(PLEB + ro); yv[m][0] = *(const f32x4*)(X + ro); yv[m][1] = *(const f32x4*)(X + ro + 4); st[m] = *(const f32x2*)(stats + 2 * row); }
; #pragma unroll
;                 for (int m = mh; m < mh + 2; ++m) { const int row = row0 + ai * 128 + m * 16; const size_t ro = (size_t)row * DM + c0 + bj * 128;
;                     const float mu = st[m].x * (1.f / DM), var = st[m].y * (1.f / DM) - mu * mu, r = 1.f / sqrtf(var + LN_EPS);
;                     f32x4 p0, p1; unpack8(pw[m], p0, p1);
;                     const f32x4 x0 = (yv[m][0] - mu) * r * g0 + b0, x1 = (yv[m][1] - mu) * r * g1 + b1;
;                     const f32x4 o0 = x0 + sig4((acc[ai][bj][m][0] - mu * cg0) * r + cb0) * p0, o1 = x1 + sig4((acc[ai][bj][m][1] - mu * cg1) * r + cb1) * p1;
;                     *(f32x4*)(X + ro) = o0; *(f32x4*)(X + ro + 4) = o1; if (XB) *(u32x4*)(XB + ro) = pack8(o0, o1); }
.Leg_noxb_3:
	v_lshl_or_b32 v244, s3, 8, v192
	v_lshlrev_b32_e32 v244, 2, v244
	global_load_dwordx4 v[128:131], v244, s[26:27] offset:512
	global_load_dwordx4 v[132:135], v244, s[26:27] offset:528
	global_load_dwordx4 v[136:139], v244, s[28:29] offset:512
	global_load_dwordx4 v[140:143], v244, s[28:29] offset:528
	global_load_dwordx4 v[144:147], v244, s[14:15] offset:512
	global_load_dwordx4 v[148:151], v244, s[14:15] offset:528
	global_load_dwordx4 v[152:155], v244, s[24:25] offset:512
	global_load_dwordx4 v[156:159], v244, s[24:25] offset:528
	v_add_u32_e32 v243, 0x140000, v242
	global_load_dwordx4 v[200:203], v243, s[12:13]
	global_load_dwordx4 v[204:207], v243, s[12:13] offset:16
	v_lshrrev_b32_e32 v244, 1, v243
	global_load_dwordx4 v[196:199], v244, s[20:21]
	v_lshrrev_b32_e32 v244, 10, v243
	v_and_b32_e32 v244, -8, v244
	global_load_dwordx2 v[208:209], v244, s[22:23]
	s_waitcnt vmcnt(20)
	v_mul_f32_e32 v168, 0x3a000000, v222
	v_mul_f32_e32 v171, 0x3a000000, v223
	v_fma_f32 v170, -v168, v168, v171
	v_add_f32_e32 v170, 0x3727c5ac, v170
	v_cmp_gt_f32_e32 vcc, s33, v170
	v_mul_f32_e32 v171, 0x4f800000, v170
	s_nop 0
	v_cndmask_b32_e32 v170, v170, v171, vcc
	v_sqrt_f32_e32 v171, v170
	v_lshlrev_b32_e32 v160, 16, v210
	v_and_b32_e32 v161, 0xffff0000, v210
	v_lshlrev_b32_e32 v162, 16, v211
	v_and_b32_e32 v163, 0xffff0000, v211
	v_lshlrev_b32_e32 v164, 16, v212
	v_and_b32_e32 v165, 0xffff0000, v212
	v_lshlrev_b32_e32 v166, 16, v213
	v_and_b32_e32 v167, 0xffff0000, v213
	v_add_u32_e32 v238, -1, v171
	v_fma_f32 v239, -v238, v171, v170
	v_cmp_ge_f32_e64 s[8:9], 0, v239
	v_add_u32_e32 v239, 1, v171
	s_nop 0
	v_cndmask_b32_e64 v238, v171, v238, s[8:9]
	v_fma_f32 v171, -v239, v171, v170
	v_cmp_lt_f32_e64 s[8:9], 0, v171
	s_nop 1
	v_cndmask_b32_e64 v171, v238, v239, s[8:9]
	v_mul_f32_e32 v238, 0x37800000, v171
	v_cndmask_b32_e32 v171, v171, v238, vcc
	v_cmp_class_f32_e32 vcc, v170, v249
	s_nop 1
	v_cndmask_b32_e32 v170, v171, v170, vcc
	v_div_scale_f32 v171, s[4:5], v170, v170, 1.0
	v_rcp_f32_e32 v238, v171
	s_nop 0
	v_fma_f32 v239, -v171, v238, 1.0
	v_fmac_f32_e32 v238, v239, v238
	v_div_scale_f32 v239, vcc, 1.0, v170, 1.0
	v_mul_f32_e32 v240, v239, v238
	v_fma_f32 v241, -v171, v240, v239
	v_fmac_f32_e32 v240, v241, v238
	v_fma_f32 v171, -v171, v240, v239
	v_div_fmas_f32 v171, v171, v238, v240
	v_div_fixup_f32 v169, v171, v170, 1.0
	v_fma_f32 v124, -v104, v168, v124
	v_fma_f32 v125, -v105, v168, v125
	v_fma_f32 v126, -v106, v168, v126
	v_fma_f32 v127, -v107, v168, v127
	v_fma_f32 v120, -v108, v168, v120
	v_fma_f32 v121, -v109, v168, v121
	v_fma_f32 v122, -v110, v168, v122
	v_fma_f32 v123, -v111, v168, v123
	v_sub_f32_e32 v214, v214, v168
	v_sub_f32_e32 v215, v215, v168
	v_sub_f32_e32 v216, v216, v168
	v_sub_f32_e32 v217, v217, v168
	v_sub_f32_e32 v218, v218, v168
	v_sub_f32_e32 v219, v219, v168
	v_sub_f32_e32 v220, v220, v168
	v_sub_f32_e32 v221, v221, v168
	v_fma_f32 v124, v124, v169, v112
	v_fma_f32 v125, v125, v169, v113
	v_fma_f32 v126, v126, v169, v114
	v_fma_f32 v127, v127, v169, v115
	v_fma_f32 v120, v120, v169, v116
	v_fma_f32 v121, v121, v169, v117
	v_fma_f32 v122, v122, v169, v118
	v_fma_f32 v123, v123, v169, v119
	v_mul_f32_e32 v214, v214, v169
	v_mul_f32_e32 v215, v215, v169
	v_mul_f32_e32 v216, v216, v169
	v_mul_f32_e32 v217, v217, v169
	v_mul_f32_e32 v218, v218, v169
	v_mul_f32_e32 v219, v219, v169
	v_mul_f32_e32 v220, v220, v169
	v_mul_f32_e32 v221, v221, v169
	v_mul_f32_e32 v124, 0xbfb8aa3b, v124
	v_mul_f32_e32 v125, 0xbfb8aa3b, v125
	v_mul_f32_e32 v126, 0xbfb8aa3b, v126
	v_mul_f32_e32 v127, 0xbfb8aa3b, v127
	v_mul_f32_e32 v120, 0xbfb8aa3b, v120
	v_mul_f32_e32 v121, 0xbfb8aa3b, v121
	v_mul_f32_e32 v122, 0xbfb8aa3b, v122
	v_mul_f32_e32 v123, 0xbfb8aa3b, v123
	v_fma_f32 v214, v88, v214, v96
	v_fma_f32 v215, v89, v215, v97
	v_fma_f32 v216, v90, v216, v98
	v_fma_f32 v217, v91, v217, v99
	v_fma_f32 v218, v92, v218, v100
	v_fma_f32 v219, v93, v219, v101
	v_fma_f32 v220, v94, v220, v102
	v_fma_f32 v221, v95, v221, v103
	v_exp_f32_e32 v124, v124
	v_exp_f32_e32 v125, v125
	v_exp_f32_e32 v126, v126
	v_exp_f32_e32 v127, v127
	v_exp_f32_e32 v120, v120
	v_exp_f32_e32 v121, v121
	v_exp_f32_e32 v122, v122
	v_exp_f32_e32 v123, v123
	v_add_f32_e32 v124, 1.0, v124
	v_add_f32_e32 v125, 1.0, v125
	v_add_f32_e32 v126, 1.0, v126
	v_add_f32_e32 v127, 1.0, v127
	v_add_f32_e32 v120, 1.0, v120
	v_add_f32_e32 v121, 1.0, v121
	v_add_f32_e32 v122, 1.0, v122
	v_add_f32_e32 v123, 1.0, v123
	v_rcp_f32_e32 v124, v124
	v_rcp_f32_e32 v125, v125
	v_rcp_f32_e32 v126, v126
	v_rcp_f32_e32 v127, v127
	v_rcp_f32_e32 v120, v120
	v_rcp_f32_e32 v121, v121
	v_rcp_f32_e32 v122, v122
	v_rcp_f32_e32 v123, v123
	v_fma_f32 v214, v124, v160, v214
	v_fma_f32 v215, v125, v161, v215
	v_fma_f32 v216, v126, v162, v216
	v_fma_f32 v217, v127, v163, v217
	v_fma_f32 v218, v120, v164, v218
	v_fma_f32 v219, v121, v165, v219
	v_fma_f32 v220, v122, v166, v220
	v_fma_f32 v221, v123, v167, v221
	v_add_u32_e32 v243, 0x100000, v242
	global_store_dwordx4 v243, v[214:217], s[12:13]
	global_store_dwordx4 v243, v[218:221], s[12:13] offset:16
	s_and_b64 s[4:5], exec, s[16:17]
	s_cbranch_scc0 .Leg_noxb_4
	v_cvt_pk_bf16_f32 v210, v214, v215
	v_cvt_pk_bf16_f32 v211, v216, v217
	v_cvt_pk_bf16_f32 v212, v218, v219
	v_cvt_pk_bf16_f32 v213, v220, v221
	v_lshrrev_b32_e32 v244, 1, v243
	global_store_dwordx4 v244, v[210:213], s[18:19]
; __device__ __forceinline__ f32x4 sig4(f32x4 v) { return (f32x4){sigmoidf_(v[0]), sigmoidf_(v[1]), sigmoidf_(v[2]), sigmoidf_(v[3])}; }
; __device__ __forceinline__ void unpack8(u32x4 w, f32x4& a, f32x4& b) { a = (f32x4){bf_lo(w.x), bf_hi(w.x), bf_lo(w.y), bf_hi(w.y)}; b = (f32x4){bf_lo(w.z), bf_hi(w.z), bf_lo(w.w), bf_hi(w.w)}; }
; __device__ __forceinline__ u32x4 pack8(f32x4 a, f32x4 b) { u32x4 w; w.x = cvt_pk_bf16(a[0], a[1]); w.y = cvt_pk_bf16(a[2], a[3]); w.z = cvt_pk_bf16(b[0], b[1]); w.w = cvt_pk_bf16(b[2], b[3]); return w; }
;     __device__ __forceinline__ void operator()(AccRef acc, const Unit& u, int wr, int wc, int fr, int fq) const {
;     ...
;                 for (int m = mh; m < mh + 2; ++m) { const int row = row0 + ai * 128 + m * 16; const size_t ro = (size_t)row * DM + c0 + bj * 128;
;                     pw[m] = *(const u32x4*)(PLEB + ro); yv[m][0] = *(const f32x4*)(X + ro); yv[m][1] = *(const f32x4*)(X + ro + 4); st[m] = *(const f32x2*)(stats + 2 * row); }
; #pragma unroll
;                 for (int m = mh; m < mh + 2; ++m) { const int row = row0 + ai * 128 + m * 16; const size_t ro = (size_t)row * DM + c0 + bj * 128;
;                     const float mu = st[m].x * (1.f / DM), var = st[m].y * (1.f / DM) - mu * mu, r = 1.f / sqrtf(var + LN_EPS);
;                     f32x4 p0, p1; unpack8(pw[m], p0, p1);
;                     const f32x4 x0 = (yv[m][0] - mu) * r * g0 + b0, x1 = (yv[m][1] - mu) * r * g1 + b1;
;                     const f32x4 o0 = x0 + sig4((acc[ai][bj][m][0] - mu * cg0) * r + cb0) * p0, o1 = x1 + sig4((acc[ai][bj][m][1] - mu * cg1) * r + cb1) * p1;
;                     *(f32x4*)(X + ro) = o0; *(f32x4*)(X + ro + 4) = o1; if (XB) *(u32x4*)(XB + ro) = pack8(o0, o1); }
.Leg_noxb_4:
	v_add_u32_e32 v243, 0x160000, v242
	global_load_dwordx4 v[214:217], v243, s[12:13]
	global_load_dwordx4 v[218:221], v243, s[12:13] offset:16
	v_lshrrev_b32_e32 v244, 1, v243
	global_load_dwordx4 v[210:213], v244, s[20:21]
	v_lshrrev_b32_e32 v244, 10, v243
	v_and_b32_e32 v244, -8, v244
	global_load_dwordx2 v[222:223], v244, s[22:23]
	s_waitcnt vmcnt(20)
	v_mul_f32_e32 v168, 0x3a000000, v236
	v_mul_f32_e32 v171, 0x3a000000, v237
	v_fma_f32 v170, -v168, v168, v171
	v_add_f32_e32 v170, 0x3727c5ac, v170
	v_cmp_gt_f32_e32 vcc, s33, v170
	v_mul_f32_e32 v171, 0x4f800000, v170
	s_nop 0
	v_cndmask_b32_e32 v170, v170, v171, vcc
	v_sqrt_f32_e32 v171, v170
	v_lshlrev_b32_e32 v160, 16, v224
	v_and_b32_e32 v161, 0xffff0000, v224
	v_lshlrev_b32_e32 v162, 16, v225
	v_and_b32_e32 v163, 0xffff0000, v225
	v_lshlrev_b32_e32 v164, 16, v226
	v_and_b32_e32 v165, 0xffff0000, v226
	v_lshlrev_b32_e32 v166, 16, v227
	v_and_b32_e32 v167, 0xffff0000, v227
	v_add_u32_e32 v238, -1, v171
	v_fma_f32 v239, -v238, v171, v170
	v_cmp_ge_f32_e64 s[8:9], 0, v239
	v_add_u32_e32 v239, 1, v171
	s_nop 0
	v_cndmask_b32_e64 v238, v171, v238, s[8:9]
	v_fma_f32 v171, -v239, v171, v170
	v_cmp_lt_f32_e64 s[8:9], 0, v171
	s_nop 1
	v_cndmask_b32_e64 v171, v238, v239, s[8:9]
	v_mul_f32_e32 v238, 0x37800000, v171
	v_cndmask_b32_e32 v171, v171, v238, vcc
	v_cmp_class_f32_e32 vcc, v170, v249
	s_nop 1
	v_cndmask_b32_e32 v170, v171, v170, vcc
	v_div_scale_f32 v171, s[4:5], v170, v170, 1.0
	v_rcp_f32_e32 v238, v171
	s_nop 0
	v_fma_f32 v239, -v171, v238, 1.0
	v_fmac_f32_e32 v238, v239, v238
	v_div_scale_f32 v239, vcc, 1.0, v170, 1.0
	v_mul_f32_e32 v240, v239, v238
	v_fma_f32 v241, -v171, v240, v239
	v_fmac_f32_e32 v240, v241, v238
	v_fma_f32 v171, -v171, v240, v239
	v_div_fmas_f32 v171, v171, v238, v240
	v_div_fixup_f32 v169, v171, v170, 1.0
	v_fma_f32 v84, -v104, v168, v84
	v_fma_f32 v85, -v105, v168, v85
	v_fma_f32 v86, -v106, v168, v86
	v_fma_f32 v87, -v107, v168, v87
	v_fma_f32 v80, -v108, v168, v80
	v_fma_f32 v81, -v109, v168, v81
	v_fma_f32 v82, -v110, v168, v82
	v_fma_f32 v83, -v111, v168, v83
	v_sub_f32_e32 v228, v228, v168
	v_sub_f32_e32 v229, v229, v168
	v_sub_f32_e32 v230, v230, v168
	v_sub_f32_e32 v231, v231, v168
	v_sub_f32_e32 v232, v232, v168
	v_sub_f32_e32 v233, v233, v168
	v_sub_f32_e32 v234, v234, v168
	v_sub_f32_e32 v235, v235, v168
	v_fma_f32 v84, v84, v169, v112
	v_fma_f32 v85, v85, v169, v113
	v_fma_f32 v86, v86, v169, v114
	v_fma_f32 v87, v87, v169, v115
	v_fma_f32 v80, v80, v169, v116
	v_fma_f32 v81, v81, v169, v117
	v_fma_f32 v82, v82, v169, v118
	v_fma_f32 v83, v83, v169, v119
	v_mul_f32_e32 v228, v228, v169
	v_mul_f32_e32 v229, v229, v169
	v_mul_f32_e32 v230, v230, v169
	v_mul_f32_e32 v231, v231, v169
	v_mul_f32_e32 v232, v232, v169
	v_mul_f32_e32 v233, v233, v169
	v_mul_f32_e32 v234, v234, v169
	v_mul_f32_e32 v235, v235, v169
	v_mul_f32_e32 v84, 0xbfb8aa3b, v84
	v_mul_f32_e32 v85, 0xbfb8aa3b, v85
	v_mul_f32_e32 v86, 0xbfb8aa3b, v86
	v_mul_f32_e32 v87, 0xbfb8aa3b, v87
	v_mul_f32_e32 v80, 0xbfb8aa3b, v80
	v_mul_f32_e32 v81, 0xbfb8aa3b, v81
	v_mul_f32_e32 v82, 0xbfb8aa3b, v82
	v_mul_f32_e32 v83, 0xbfb8aa3b, v83
	v_fma_f32 v228, v88, v228, v96
	v_fma_f32 v229, v89, v229, v97
	v_fma_f32 v230, v90, v230, v98
	v_fma_f32 v231, v91, v231, v99
	v_fma_f32 v232, v92, v232, v100
	v_fma_f32 v233, v93, v233, v101
	v_fma_f32 v234, v94, v234, v102
	v_fma_f32 v235, v95, v235, v103
	v_exp_f32_e32 v84, v84
	v_exp_f32_e32 v85, v85
	v_exp_f32_e32 v86, v86
	v_exp_f32_e32 v87, v87
	v_exp_f32_e32 v80, v80
	v_exp_f32_e32 v81, v81
	v_exp_f32_e32 v82, v82
	v_exp_f32_e32 v83, v83
	v_add_f32_e32 v84, 1.0, v84
	v_add_f32_e32 v85, 1.0, v85
	v_add_f32_e32 v86, 1.0, v86
	v_add_f32_e32 v87, 1.0, v87
	v_add_f32_e32 v80, 1.0, v80
	v_add_f32_e32 v81, 1.0, v81
	v_add_f32_e32 v82, 1.0, v82
	v_add_f32_e32 v83, 1.0, v83
	v_rcp_f32_e32 v84, v84
	v_rcp_f32_e32 v85, v85
	v_rcp_f32_e32 v86, v86
	v_rcp_f32_e32 v87, v87
	v_rcp_f32_e32 v80, v80
	v_rcp_f32_e32 v81, v81
	v_rcp_f32_e32 v82, v82
	v_rcp_f32_e32 v83, v83
	v_fma_f32 v228, v84, v160, v228
	v_fma_f32 v229, v85, v161, v229
	v_fma_f32 v230, v86, v162, v230
	v_fma_f32 v231, v87, v163, v231
	v_fma_f32 v232, v80, v164, v232
	v_fma_f32 v233, v81, v165, v233
	v_fma_f32 v234, v82, v166, v234
	v_fma_f32 v235, v83, v167, v235
	v_add_u32_e32 v243, 0x120000, v242
	global_store_dwordx4 v243, v[228:231], s[12:13]
	global_store_dwordx4 v243, v[232:235], s[12:13] offset:16
	s_and_b64 s[4:5], exec, s[16:17]
	s_cbranch_scc0 .Leg_noxb_5
	v_cvt_pk_bf16_f32 v224, v228, v229
	v_cvt_pk_bf16_f32 v225, v230, v231
	v_cvt_pk_bf16_f32 v226, v232, v233
	v_cvt_pk_bf16_f32 v227, v234, v235
	v_lshrrev_b32_e32 v244, 1, v243
	global_store_dwordx4 v244, v[224:227], s[18:19]
; __device__ __forceinline__ f32x4 sig4(f32x4 v) { return (f32x4){sigmoidf_(v[0]), sigmoidf_(v[1]), sigmoidf_(v[2]), sigmoidf_(v[3])}; }
; __device__ __forceinline__ void unpack8(u32x4 w, f32x4& a, f32x4& b) { a = (f32x4){bf_lo(w.x), bf_hi(w.x), bf_lo(w.y), bf_hi(w.y)}; b = (f32x4){bf_lo(w.z), bf_hi(w.z), bf_lo(w.w), bf_hi(w.w)}; }
; __device__ __forceinline__ u32x4 pack8(f32x4 a, f32x4 b) { u32x4 w; w.x = cvt_pk_bf16(a[0], a[1]); w.y = cvt_pk_bf16(a[2], a[3]); w.z = cvt_pk_bf16(b[0], b[1]); w.w = cvt_pk_bf16(b[2], b[3]); return w; }
;     __device__ __forceinline__ void operator()(AccRef acc, const Unit& u, int wr, int wc, int fr, int fq) const {
;     ...
;                 u32x4 pw[4]; f32x4 yv[4][2]; f32x2 st[4];
; #pragma unroll
;                 for (int m = mh; m < mh + 2; ++m) { const int row = row0 + ai * 128 + m * 16; const size_t ro = (size_t)row * DM + c0 + bj * 128;
;                     pw[m] = *(const u32x4*)(PLEB + ro); yv[m][0] = *(const f32x4*)(X + ro); yv[m][1] = *(const f32x4*)(X + ro + 4); st[m] = *(const f32x2*)(stats + 2 * row); }
; #pragma unroll
;                 for (int m = mh; m < mh + 2; ++m) { const int row = row0 + ai * 128 + m * 16; const size_t ro = (size_t)row * DM + c0 + bj * 128;
;                     const float mu = st[m].x * (1.f / DM), var = st[m].y * (1.f / DM) - mu * mu, r = 1.f / sqrtf(var + LN_EPS);
;                     f32x4 p0, p1; unpack8(pw[m], p0, p1);
;                     const f32x4 x0 = (yv[m][0] - mu) * r * g0 + b0, x1 = (yv[m][1] - mu) * r * g1 + b1;
;                     const f32x4 o0 = x0 + sig4((acc[ai][bj][m][0] - mu * cg0) * r + cb0) * p0, o1 = x1 + sig4((acc[ai][bj][m][1] - mu * cg1) * r + cb1) * p1;
;                     *(f32x4*)(X + ro) = o0; *(f32x4*)(X + ro + 4) = o1; if (XB) *(u32x4*)(XB + ro) = pack8(o0, o1); }
;                 asm volatile("" ::: "memory");
.Leg_noxb_5:
	v_add_u32_e32 v243, 0x200, v242
	global_load_dwordx4 v[228:231], v243, s[12:13]
	global_load_dwordx4 v[232:235], v243, s[12:13] offset:16
	v_lshrrev_b32_e32 v244, 1, v243
	global_load_dwordx4 v[224:227], v244, s[20:21]
	v_lshrrev_b32_e32 v244, 10, v243
	v_and_b32_e32 v244, -8, v244
	global_load_dwordx2 v[236:237], v244, s[22:23]
	s_waitcnt vmcnt(12)
	v_mul_f32_e32 v168, 0x3a000000, v208
	v_mul_f32_e32 v171, 0x3a000000, v209
	v_fma_f32 v170, -v168, v168, v171
	v_add_f32_e32 v170, 0x3727c5ac, v170
	v_cmp_gt_f32_e32 vcc, s33, v170
	v_mul_f32_e32 v171, 0x4f800000, v170
	s_nop 0
	v_cndmask_b32_e32 v170, v170, v171, vcc
	v_sqrt_f32_e32 v171, v170
	v_lshlrev_b32_e32 v160, 16, v196
	v_and_b32_e32 v161, 0xffff0000, v196
	v_lshlrev_b32_e32 v162, 16, v197
	v_and_b32_e32 v163, 0xffff0000, v197
	v_lshlrev_b32_e32 v164, 16, v198
	v_and_b32_e32 v165, 0xffff0000, v198
	v_lshlrev_b32_e32 v166, 16, v199
	v_and_b32_e32 v167, 0xffff0000, v199
	v_add_u32_e32 v238, -1, v171
	v_fma_f32 v239, -v238, v171, v170
	v_cmp_ge_f32_e64 s[8:9], 0, v239
	v_add_u32_e32 v239, 1, v171
	s_nop 0
	v_cndmask_b32_e64 v238, v171, v238, s[8:9]
	v_fma_f32 v171, -v239, v171, v170
	v_cmp_lt_f32_e64 s[8:9], 0, v171
	s_nop 1
	v_cndmask_b32_e64 v171, v238, v239, s[8:9]
	v_mul_f32_e32 v238, 0x37800000, v171
	v_cndmask_b32_e32 v171, v171, v238, vcc
	v_cmp_class_f32_e32 vcc, v170, v249
	s_nop 1
	v_cndmask_b32_e32 v170, v171, v170, vcc
	v_div_scale_f32 v171, s[4:5], v170, v170, 1.0
	v_rcp_f32_e32 v238, v171
	s_nop 0
	v_fma_f32 v239, -v171, v238, 1.0
	v_fmac_f32_e32 v238, v239, v238
	v_div_scale_f32 v239, vcc, 1.0, v170, 1.0
	v_mul_f32_e32 v240, v239, v238
	v_fma_f32 v241, -v171, v240, v239
	v_fmac_f32_e32 v240, v241, v238
	v_fma_f32 v171, -v171, v240, v239
	v_div_fmas_f32 v171, v171, v238, v240
	v_div_fixup_f32 v169, v171, v170, 1.0
	v_fma_f32 v76, -v104, v168, v76
	v_fma_f32 v77, -v105, v168, v77
	v_fma_f32 v78, -v106, v168, v78
	v_fma_f32 v79, -v107, v168, v79
	v_fma_f32 v72, -v108, v168, v72
	v_fma_f32 v73, -v109, v168, v73
	v_fma_f32 v74, -v110, v168, v74
	v_fma_f32 v75, -v111, v168, v75
	v_sub_f32_e32 v200, v200, v168
	v_sub_f32_e32 v201, v201, v168
	v_sub_f32_e32 v202, v202, v168
	v_sub_f32_e32 v203, v203, v168
	v_sub_f32_e32 v204, v204, v168
	v_sub_f32_e32 v205, v205, v168
	v_sub_f32_e32 v206, v206, v168
	v_sub_f32_e32 v207, v207, v168
	v_fma_f32 v76, v76, v169, v112
	v_fma_f32 v77, v77, v169, v113
	v_fma_f32 v78, v78, v169, v114
	v_fma_f32 v79, v79, v169, v115
	v_fma_f32 v72, v72, v169, v116
	v_fma_f32 v73, v73, v169, v117
	v_fma_f32 v74, v74, v169, v118
	v_fma_f32 v75, v75, v169, v119
	v_mul_f32_e32 v200, v200, v169
	v_mul_f32_e32 v201, v201, v169
	v_mul_f32_e32 v202, v202, v169
	v_mul_f32_e32 v203, v203, v169
	v_mul_f32_e32 v204, v204, v169
	v_mul_f32_e32 v205, v205, v169
	v_mul_f32_e32 v206, v206, v169
	v_mul_f32_e32 v207, v207, v169
	v_mul_f32_e32 v76, 0xbfb8aa3b, v76
	v_mul_f32_e32 v77, 0xbfb8aa3b, v77
	v_mul_f32_e32 v78, 0xbfb8aa3b, v78
	v_mul_f32_e32 v79, 0xbfb8aa3b, v79
	v_mul_f32_e32 v72, 0xbfb8aa3b, v72
	v_mul_f32_e32 v73, 0xbfb8aa3b, v73
	v_mul_f32_e32 v74, 0xbfb8aa3b, v74
	v_mul_f32_e32 v75, 0xbfb8aa3b, v75
	v_fma_f32 v200, v88, v200, v96
	v_fma_f32 v201, v89, v201, v97
	v_fma_f32 v202, v90, v202, v98
	v_fma_f32 v203, v91, v203, v99
	v_fma_f32 v204, v92, v204, v100
	v_fma_f32 v205, v93, v205, v101
	v_fma_f32 v206, v94, v206, v102
	v_fma_f32 v207, v95, v207, v103
	v_exp_f32_e32 v76, v76
	v_exp_f32_e32 v77, v77
	v_exp_f32_e32 v78, v78
	v_exp_f32_e32 v79, v79
	v_exp_f32_e32 v72, v72
	v_exp_f32_e32 v73, v73
	v_exp_f32_e32 v74, v74
	v_exp_f32_e32 v75, v75
	v_add_f32_e32 v76, 1.0, v76
	v_add_f32_e32 v77, 1.0, v77
	v_add_f32_e32 v78, 1.0, v78
	v_add_f32_e32 v79, 1.0, v79
	v_add_f32_e32 v72, 1.0, v72
	v_add_f32_e32 v73, 1.0, v73
	v_add_f32_e32 v74, 1.0, v74
	v_add_f32_e32 v75, 1.0, v75
	v_rcp_f32_e32 v76, v76
	v_rcp_f32_e32 v77, v77
	v_rcp_f32_e32 v78, v78
	v_rcp_f32_e32 v79, v79
	v_rcp_f32_e32 v72, v72
	v_rcp_f32_e32 v73, v73
	v_rcp_f32_e32 v74, v74
	v_rcp_f32_e32 v75, v75
	v_fma_f32 v200, v76, v160, v200
	v_fma_f32 v201, v77, v161, v201
	v_fma_f32 v202, v78, v162, v202
	v_fma_f32 v203, v79, v163, v203
	v_fma_f32 v204, v72, v164, v204
	v_fma_f32 v205, v73, v165, v205
	v_fma_f32 v206, v74, v166, v206
	v_fma_f32 v207, v75, v167, v207
	v_add_u32_e32 v243, 0x140000, v242
	global_store_dwordx4 v243, v[200:203], s[12:13]
	global_store_dwordx4 v243, v[204:207], s[12:13] offset:16
	s_and_b64 s[4:5], exec, s[16:17]
	s_cbranch_scc0 .Leg_noxb_6
	v_cvt_pk_bf16_f32 v196, v200, v201
	v_cvt_pk_bf16_f32 v197, v202, v203
	v_cvt_pk_bf16_f32 v198, v204, v205
	v_cvt_pk_bf16_f32 v199, v206, v207
	v_lshrrev_b32_e32 v244, 1, v243
	global_store_dwordx4 v244, v[196:199], s[18:19]
; __device__ __forceinline__ f32x4 sig4(f32x4 v) { return (f32x4){sigmoidf_(v[0]), sigmoidf_(v[1]), sigmoidf_(v[2]), sigmoidf_(v[3])}; }
; __device__ __forceinline__ void unpack8(u32x4 w, f32x4& a, f32x4& b) { a = (f32x4){bf_lo(w.x), bf_hi(w.x), bf_lo(w.y), bf_hi(w.y)}; b = (f32x4){bf_lo(w.z), bf_hi(w.z), bf_lo(w.w), bf_hi(w.w)}; }
; __device__ __forceinline__ u32x4 pack8(f32x4 a, f32x4 b) { u32x4 w; w.x = cvt_pk_bf16(a[0], a[1]); w.y = cvt_pk_bf16(a[2], a[3]); w.z = cvt_pk_bf16(b[0], b[1]); w.w = cvt_pk_bf16(b[2], b[3]); return w; }
;     __device__ __forceinline__ void operator()(AccRef acc, const Unit& u, int wr, int wc, int fr, int fq) const {
;     ...
;                 u32x4 pw[4]; f32x4 yv[4][2]; f32x2 st[4];
; #pragma unroll
;                 for (int m = mh; m < mh + 2; ++m) { const int row = row0 + ai * 128 + m * 16; const size_t ro = (size_t)row * DM + c0 + bj * 128;
;                     pw[m] = *(const u32x4*)(PLEB + ro); yv[m][0] = *(const f32x4*)(X + ro); yv[m][1] = *(const f32x4*)(X + ro + 4); st[m] = *(const f32x2*)(stats + 2 * row); }
; #pragma unroll
;                 for (int m = mh; m < mh + 2; ++m) { const int row = row0 + ai * 128 + m * 16; const size_t ro = (size_t)row * DM + c0 + bj * 128;
;                     const float mu = st[m].x * (1.f / DM), var = st[m].y * (1.f / DM) - mu * mu, r = 1.f / sqrtf(var + LN_EPS);
;                     f32x4 p0, p1; unpack8(pw[m], p0, p1);
;                     const f32x4 x0 = (yv[m][0] - mu) * r * g0 + b0, x1 = (yv[m][1] - mu) * r * g1 + b1;
;                     const f32x4 o0 = x0 + sig4((acc[ai][bj][m][0] - mu * cg0) * r + cb0) * p0, o1 = x1 + sig4((acc[ai][bj][m][1] - mu * cg1) * r + cb1) * p1;
;                     *(f32x4*)(X + ro) = o0; *(f32x4*)(X + ro + 4) = o1; if (XB) *(u32x4*)(XB + ro) = pack8(o0, o1); }
;                 asm volatile("" ::: "memory");
.Leg_noxb_6:
	v_add_u32_e32 v243, 0x20200, v242
	global_load_dwordx4 v[200:203], v243, s[12:13]
	global_load_dwordx4 v[204:207], v243, s[12:13] offset:16
	v_lshrrev_b32_e32 v244, 1, v243
	global_load_dwordx4 v[196:199], v244, s[20:21]
	v_lshrrev_b32_e32 v244, 10, v243
	v_and_b32_e32 v244, -8, v244
	global_load_dwordx2 v[208:209], v244, s[22:23]
	s_waitcnt vmcnt(12)
	v_mul_f32_e32 v168, 0x3a000000, v222
	v_mul_f32_e32 v171, 0x3a000000, v223
	v_fma_f32 v170, -v168, v168, v171
	v_add_f32_e32 v170, 0x3727c5ac, v170
	v_cmp_gt_f32_e32 vcc, s33, v170
	v_mul_f32_e32 v171, 0x4f800000, v170
	s_nop 0
	v_cndmask_b32_e32 v170, v170, v171, vcc
	v_sqrt_f32_e32 v171, v170
	v_lshlrev_b32_e32 v160, 16, v210
	v_and_b32_e32 v161, 0xffff0000, v210
	v_lshlrev_b32_e32 v162, 16, v211
	v_and_b32_e32 v163, 0xffff0000, v211
	v_lshlrev_b32_e32 v164, 16, v212
	v_and_b32_e32 v165, 0xffff0000, v212
	v_lshlrev_b32_e32 v166, 16, v213
	v_and_b32_e32 v167, 0xffff0000, v213
	v_add_u32_e32 v238, -1, v171
	v_fma_f32 v239, -v238, v171, v170
	v_cmp_ge_f32_e64 s[8:9], 0, v239
	v_add_u32_e32 v239, 1, v171
	s_nop 0
	v_cndmask_b32_e64 v238, v171, v238, s[8:9]
	v_fma_f32 v171, -v239, v171, v170
	v_cmp_lt_f32_e64 s[8:9], 0, v171
	s_nop 1
	v_cndmask_b32_e64 v171, v238, v239, s[8:9]
	v_mul_f32_e32 v238, 0x37800000, v171
	v_cndmask_b32_e32 v171, v171, v238, vcc
	v_cmp_class_f32_e32 vcc, v170, v249
	s_nop 1
	v_cndmask_b32_e32 v170, v171, v170, vcc
	v_div_scale_f32 v171, s[4:5], v170, v170, 1.0
	v_rcp_f32_e32 v238, v171
	s_nop 0
	v_fma_f32 v239, -v171, v238, 1.0
	v_fmac_f32_e32 v238, v239, v238
	v_div_scale_f32 v239, vcc, 1.0, v170, 1.0
	v_mul_f32_e32 v240, v239, v238
	v_fma_f32 v241, -v171, v240, v239
	v_fmac_f32_e32 v240, v241, v238
	v_fma_f32 v171, -v171, v240, v239
	v_div_fmas_f32 v171, v171, v238, v240
	v_div_fixup_f32 v169, v171, v170, 1.0
	v_fma_f32 v68, -v104, v168, v68
	v_fma_f32 v69, -v105, v168, v69
	v_fma_f32 v70, -v106, v168, v70
	v_fma_f32 v71, -v107, v168, v71
	v_fma_f32 v64, -v108, v168, v64
	v_fma_f32 v65, -v109, v168, v65
	v_fma_f32 v66, -v110, v168, v66
	v_fma_f32 v67, -v111, v168, v67
	v_sub_f32_e32 v214, v214, v168
	v_sub_f32_e32 v215, v215, v168
	v_sub_f32_e32 v216, v216, v168
	v_sub_f32_e32 v217, v217, v168
	v_sub_f32_e32 v218, v218, v168
	v_sub_f32_e32 v219, v219, v168
	v_sub_f32_e32 v220, v220, v168
	v_sub_f32_e32 v221, v221, v168
	v_fma_f32 v68, v68, v169, v112
	v_fma_f32 v69, v69, v169, v113
	v_fma_f32 v70, v70, v169, v114
	v_fma_f32 v71, v71, v169, v115
	v_fma_f32 v64, v64, v169, v116
	v_fma_f32 v65, v65, v169, v117
	v_fma_f32 v66, v66, v169, v118
	v_fma_f32 v67, v67, v169, v119
	v_mul_f32_e32 v214, v214, v169
	v_mul_f32_e32 v215, v215, v169
	v_mul_f32_e32 v216, v216, v169
	v_mul_f32_e32 v217, v217, v169
	v_mul_f32_e32 v218, v218, v169
	v_mul_f32_e32 v219, v219, v169
	v_mul_f32_e32 v220, v220, v169
	v_mul_f32_e32 v221, v221, v169
	v_mul_f32_e32 v68, 0xbfb8aa3b, v68
	v_mul_f32_e32 v69, 0xbfb8aa3b, v69
	v_mul_f32_e32 v70, 0xbfb8aa3b, v70
	v_mul_f32_e32 v71, 0xbfb8aa3b, v71
	v_mul_f32_e32 v64, 0xbfb8aa3b, v64
	v_mul_f32_e32 v65, 0xbfb8aa3b, v65
	v_mul_f32_e32 v66, 0xbfb8aa3b, v66
	v_mul_f32_e32 v67, 0xbfb8aa3b, v67
	v_fma_f32 v214, v88, v214, v96
	v_fma_f32 v215, v89, v215, v97
	v_fma_f32 v216, v90, v216, v98
	v_fma_f32 v217, v91, v217, v99
	v_fma_f32 v218, v92, v218, v100
	v_fma_f32 v219, v93, v219, v101
	v_fma_f32 v220, v94, v220, v102
	v_fma_f32 v221, v95, v221, v103
	v_exp_f32_e32 v68, v68
	v_exp_f32_e32 v69, v69
	v_exp_f32_e32 v70, v70
	v_exp_f32_e32 v71, v71
	v_exp_f32_e32 v64, v64
	v_exp_f32_e32 v65, v65
	v_exp_f32_e32 v66, v66
	v_exp_f32_e32 v67, v67
	v_add_f32_e32 v68, 1.0, v68
	v_add_f32_e32 v69, 1.0, v69
	v_add_f32_e32 v70, 1.0, v70
	v_add_f32_e32 v71, 1.0, v71
	v_add_f32_e32 v64, 1.0, v64
	v_add_f32_e32 v65, 1.0, v65
	v_add_f32_e32 v66, 1.0, v66
	v_add_f32_e32 v67, 1.0, v67
	v_rcp_f32_e32 v68, v68
	v_rcp_f32_e32 v69, v69
	v_rcp_f32_e32 v70, v70
	v_rcp_f32_e32 v71, v71
	v_rcp_f32_e32 v64, v64
	v_rcp_f32_e32 v65, v65
	v_rcp_f32_e32 v66, v66
	v_rcp_f32_e32 v67, v67
	v_fma_f32 v214, v68, v160, v214
	v_fma_f32 v215, v69, v161, v215
	v_fma_f32 v216, v70, v162, v216
	v_fma_f32 v217, v71, v163, v217
	v_fma_f32 v218, v64, v164, v218
	v_fma_f32 v219, v65, v165, v219
	v_fma_f32 v220, v66, v166, v220
	v_fma_f32 v221, v67, v167, v221
	v_add_u32_e32 v243, 0x160000, v242
	global_store_dwordx4 v243, v[214:217], s[12:13]
	global_store_dwordx4 v243, v[218:221], s[12:13] offset:16
	s_and_b64 s[4:5], exec, s[16:17]
	s_cbranch_scc0 .Leg_noxb_7
	v_cvt_pk_bf16_f32 v210, v214, v215
	v_cvt_pk_bf16_f32 v211, v216, v217
	v_cvt_pk_bf16_f32 v212, v218, v219
	v_cvt_pk_bf16_f32 v213, v220, v221
	v_lshrrev_b32_e32 v244, 1, v243
	global_store_dwordx4 v244, v[210:213], s[18:19]
; __device__ __forceinline__ f32x4 sig4(f32x4 v) { return (f32x4){sigmoidf_(v[0]), sigmoidf_(v[1]), sigmoidf_(v[2]), sigmoidf_(v[3])}; }
; __device__ __forceinline__ void unpack8(u32x4 w, f32x4& a, f32x4& b) { a = (f32x4){bf_lo(w.x), bf_hi(w.x), bf_lo(w.y), bf_hi(w.y)}; b = (f32x4){bf_lo(w.z), bf_hi(w.z), bf_lo(w.w), bf_hi(w.w)}; }
;     __device__ __forceinline__ void operator()(AccRef acc, const Unit& u, int wr, int wc, int fr, int fq) const {
;         const int row0 = u.pm * 256 + wr * 64 + fr, c0 = u.pn * 256 + wc * 32 + 8 * fq;
; #pragma unroll
;         for (int bj = 0; bj < 2; ++bj) {
;             const f32x4 g0 = *(const f32x4*)(lng + c0 + bj * 128), g1 = *(const f32x4*)(lng + c0 + bj * 128 + 4), b0 = *(const f32x4*)(lnb + c0 + bj * 128), b1 = *(const f32x4*)(lnb + c0 + bj * 128 + 4);
;             const f32x4 cg0 = *(const f32x4*)(cg + c0 + bj * 128), cg1 = *(const f32x4*)(cg + c0 + bj * 128 + 4), cb0 = *(const f32x4*)(cb + c0 + bj * 128), cb1 = *(const f32x4*)(cb + c0 + bj * 128 + 4);
; #pragma unroll
;             for (int ai = 0; ai < 2; ++ai)
; #pragma unroll
;             for (int mh = 0; mh < 4; mh += 2) {
;                 u32x4 pw[4]; f32x4 yv[4][2]; f32x2 st[4];
; #pragma unroll
;                 for (int m = mh; m < mh + 2; ++m) { const int row = row0 + ai * 128 + m * 16; const size_t ro = (size_t)row * DM + c0 + bj * 128;
;                     pw[m] = *(const u32x4*)(PLEB + ro); yv[m][0] = *(const f32x4*)(X + ro); yv[m][1] = *(const f32x4*)(X + ro + 4); st[m] = *(const f32x2*)(stats + 2 * row); }
; #pragma unroll
;                 for (int m = mh; m < mh + 2; ++m) { const int row = row0 + ai * 128 + m * 16; const size_t ro = (size_t)row * DM + c0 + bj * 128;
;                     const float mu = st[m].x * (1.f / DM), var = st[m].y * (1.f / DM) - mu * mu, r = 1.f / sqrtf(var + LN_EPS);
;                     f32x4 p0, p1; unpack8(pw[m], p0, p1);
;                     const f32x4 x0 = (yv[m][0] - mu) * r * g0 + b0, x1 = (yv[m][1] - mu) * r * g1 + b1;
;                     const f32x4 o0 = x0 + sig4((acc[ai][bj][m][0] - mu * cg0) * r + cb0) * p0, o1 = x1 + sig4((acc[ai][bj][m][1] - mu * cg1) * r + cb1) * p1;
;                     *(f32x4*)(X + ro) = o0; *(f32x4*)(X + ro + 4) = o1; if (XB) *(u32x4*)(XB + ro) = pack8(o0, o1); }
;                 asm volatile("" ::: "memory");
.Leg_noxb_7:
	v_add_u32_e32 v243, 0x40200, v242
	global_load_dwordx4 v[214:217], v243, s[12:13]
	global_load_dwordx4 v[218:221], v243, s[12:13] offset:16
	v_lshrrev_b32_e32 v244, 1, v243
	global_load_dwordx4 v[210:213], v244, s[20:21]
	v_lshrrev_b32_e32 v244, 10, v243
	v_and_b32_e32 v244, -8, v244
	global_load_dwordx2 v[222:223], v244, s[22:23]
	s_waitcnt vmcnt(12)
	v_mul_f32_e32 v168, 0x3a000000, v236
	v_mul_f32_e32 v171, 0x3a000000, v237
	v_fma_f32 v170, -v168, v168, v171
	v_add_f32_e32 v170, 0x3727c5ac, v170
	v_cmp_gt_f32_e32 vcc, s33, v170
	v_mul_f32_e32 v171, 0x4f800000, v170
	s_nop 0
	v_cndmask_b32_e32 v170, v170, v171, vcc
	v_sqrt_f32_e32 v171, v170
	v_lshlrev_b32_e32 v160, 16, v224
	v_and_b32_e32 v161, 0xffff0000, v224
	v_lshlrev_b32_e32 v162, 16, v225
	v_and_b32_e32 v163, 0xffff0000, v225
	v_lshlrev_b32_e32 v164, 16, v226
	v_and_b32_e32 v165, 0xffff0000, v226
	v_lshlrev_b32_e32 v166, 16, v227
	v_and_b32_e32 v167, 0xffff0000, v227
	v_add_u32_e32 v238, -1, v171
	v_fma_f32 v239, -v238, v171, v170
	v_cmp_ge_f32_e64 s[8:9], 0, v239
	v_add_u32_e32 v239, 1, v171
	s_nop 0
	v_cndmask_b32_e64 v238, v171, v238, s[8:9]
	v_fma_f32 v171, -v239, v171, v170
	v_cmp_lt_f32_e64 s[8:9], 0, v171
	s_nop 1
	v_cndmask_b32_e64 v171, v238, v239, s[8:9]
	v_mul_f32_e32 v238, 0x37800000, v171
	v_cndmask_b32_e32 v171, v171, v238, vcc
	v_cmp_class_f32_e32 vcc, v170, v249
	s_nop 1
	v_cndmask_b32_e32 v170, v171, v170, vcc
	v_div_scale_f32 v171, s[4:5], v170, v170, 1.0
	v_rcp_f32_e32 v238, v171
	s_nop 0
	v_fma_f32 v239, -v171, v238, 1.0
	v_fmac_f32_e32 v238, v239, v238
	v_div_scale_f32 v239, vcc, 1.0, v170, 1.0
	v_mul_f32_e32 v240, v239, v238
	v_fma_f32 v241, -v171, v240, v239
	v_fmac_f32_e32 v240, v241, v238
	v_fma_f32 v171, -v171, v240, v239
	v_div_fmas_f32 v171, v171, v238, v240
	v_div_fixup_f32 v169, v171, v170, 1.0
	v_fma_f32 v60, -v144, v168, v60
	v_fma_f32 v61, -v145, v168, v61
	v_fma_f32 v62, -v146, v168, v62
	v_fma_f32 v63, -v147, v168, v63
	v_fma_f32 v56, -v148, v168, v56
	v_fma_f32 v57, -v149, v168, v57
	v_fma_f32 v58, -v150, v168, v58
	v_fma_f32 v59, -v151, v168, v59
	v_sub_f32_e32 v228, v228, v168
	v_sub_f32_e32 v229, v229, v168
	v_sub_f32_e32 v230, v230, v168
	v_sub_f32_e32 v231, v231, v168
	v_sub_f32_e32 v232, v232, v168
	v_sub_f32_e32 v233, v233, v168
	v_sub_f32_e32 v234, v234, v168
	v_sub_f32_e32 v235, v235, v168
	v_fma_f32 v60, v60, v169, v152
	v_fma_f32 v61, v61, v169, v153
	v_fma_f32 v62, v62, v169, v154
	v_fma_f32 v63, v63, v169, v155
	v_fma_f32 v56, v56, v169, v156
	v_fma_f32 v57, v57, v169, v157
	v_fma_f32 v58, v58, v169, v158
	v_fma_f32 v59, v59, v169, v159
	v_mul_f32_e32 v228, v228, v169
	v_mul_f32_e32 v229, v229, v169
	v_mul_f32_e32 v230, v230, v169
	v_mul_f32_e32 v231, v231, v169
	v_mul_f32_e32 v232, v232, v169
	v_mul_f32_e32 v233, v233, v169
	v_mul_f32_e32 v234, v234, v169
	v_mul_f32_e32 v235, v235, v169
	v_mul_f32_e32 v60, 0xbfb8aa3b, v60
	v_mul_f32_e32 v61, 0xbfb8aa3b, v61
	v_mul_f32_e32 v62, 0xbfb8aa3b, v62
	v_mul_f32_e32 v63, 0xbfb8aa3b, v63
	v_mul_f32_e32 v56, 0xbfb8aa3b, v56
	v_mul_f32_e32 v57, 0xbfb8aa3b, v57
	v_mul_f32_e32 v58, 0xbfb8aa3b, v58
	v_mul_f32_e32 v59, 0xbfb8aa3b, v59
	v_fma_f32 v228, v128, v228, v136
	v_fma_f32 v229, v129, v229, v137
	v_fma_f32 v230, v130, v230, v138
	v_fma_f32 v231, v131, v231, v139
	v_fma_f32 v232, v132, v232, v140
	v_fma_f32 v233, v133, v233, v141
	v_fma_f32 v234, v134, v234, v142
	v_fma_f32 v235, v135, v235, v143
	v_exp_f32_e32 v60, v60
	v_exp_f32_e32 v61, v61
	v_exp_f32_e32 v62, v62
	v_exp_f32_e32 v63, v63
	v_exp_f32_e32 v56, v56
	v_exp_f32_e32 v57, v57
	v_exp_f32_e32 v58, v58
	v_exp_f32_e32 v59, v59
	v_add_f32_e32 v60, 1.0, v60
	v_add_f32_e32 v61, 1.0, v61
	v_add_f32_e32 v62, 1.0, v62
	v_add_f32_e32 v63, 1.0, v63
	v_add_f32_e32 v56, 1.0, v56
	v_add_f32_e32 v57, 1.0, v57
	v_add_f32_e32 v58, 1.0, v58
	v_add_f32_e32 v59, 1.0, v59
	v_rcp_f32_e32 v60, v60
	v_rcp_f32_e32 v61, v61
	v_rcp_f32_e32 v62, v62
	v_rcp_f32_e32 v63, v63
	v_rcp_f32_e32 v56, v56
	v_rcp_f32_e32 v57, v57
	v_rcp_f32_e32 v58, v58
	v_rcp_f32_e32 v59, v59
	v_fma_f32 v228, v60, v160, v228
	v_fma_f32 v229, v61, v161, v229
	v_fma_f32 v230, v62, v162, v230
	v_fma_f32 v231, v63, v163, v231
	v_fma_f32 v232, v56, v164, v232
	v_fma_f32 v233, v57, v165, v233
	v_fma_f32 v234, v58, v166, v234
	v_fma_f32 v235, v59, v167, v235
	v_add_u32_e32 v243, 0x200, v242
	global_store_dwordx4 v243, v[228:231], s[12:13]
	global_store_dwordx4 v243, v[232:235], s[12:13] offset:16
	s_and_b64 s[4:5], exec, s[16:17]
	s_cbranch_scc0 .Leg_noxb_8
	v_cvt_pk_bf16_f32 v224, v228, v229
	v_cvt_pk_bf16_f32 v225, v230, v231
	v_cvt_pk_bf16_f32 v226, v232, v233
	v_cvt_pk_bf16_f32 v227, v234, v235
	v_lshrrev_b32_e32 v244, 1, v243
	global_store_dwordx4 v244, v[224:227], s[18:19]
; __device__ __forceinline__ f32x4 sig4(f32x4 v) { return (f32x4){sigmoidf_(v[0]), sigmoidf_(v[1]), sigmoidf_(v[2]), sigmoidf_(v[3])}; }
; __device__ __forceinline__ void unpack8(u32x4 w, f32x4& a, f32x4& b) { a = (f32x4){bf_lo(w.x), bf_hi(w.x), bf_lo(w.y), bf_hi(w.y)}; b = (f32x4){bf_lo(w.z), bf_hi(w.z), bf_lo(w.w), bf_hi(w.w)}; }
; __device__ __forceinline__ u32x4 pack8(f32x4 a, f32x4 b) { u32x4 w; w.x = cvt_pk_bf16(a[0], a[1]); w.y = cvt_pk_bf16(a[2], a[3]); w.z = cvt_pk_bf16(b[0], b[1]); w.w = cvt_pk_bf16(b[2], b[3]); return w; }
;     __device__ __forceinline__ void operator()(AccRef acc, const Unit& u, int wr, int wc, int fr, int fq) const {
;     ...
;                 u32x4 pw[4]; f32x4 yv[4][2]; f32x2 st[4];
; #pragma unroll
;                 for (int m = mh; m < mh + 2; ++m) { const int row = row0 + ai * 128 + m * 16; const size_t ro = (size_t)row * DM + c0 + bj * 128;
;                     pw[m] = *(const u32x4*)(PLEB + ro); yv[m][0] = *(const f32x4*)(X + ro); yv[m][1] = *(const f32x4*)(X + ro + 4); st[m] = *(const f32x2*)(stats + 2 * row); }
; #pragma unroll
;                 for (int m = mh; m < mh + 2; ++m) { const int row = row0 + ai * 128 + m * 16; const size_t ro = (size_t)row * DM + c0 + bj * 128;
;                     const float mu = st[m].x * (1.f / DM), var = st[m].y * (1.f / DM) - mu * mu, r = 1.f / sqrtf(var + LN_EPS);
;                     f32x4 p0, p1; unpack8(pw[m], p0, p1);
;                     const f32x4 x0 = (yv[m][0] - mu) * r * g0 + b0, x1 = (yv[m][1] - mu) * r * g1 + b1;
;                     const f32x4 o0 = x0 + sig4((acc[ai][bj][m][0] - mu * cg0) * r + cb0) * p0, o1 = x1 + sig4((acc[ai][bj][m][1] - mu * cg1) * r + cb1) * p1;
;                     *(f32x4*)(X + ro) = o0; *(f32x4*)(X + ro + 4) = o1; if (XB) *(u32x4*)(XB + ro) = pack8(o0, o1); }
;                 asm volatile("" ::: "memory");
.Leg_noxb_8:
	v_add_u32_e32 v243, 0x60200, v242
	global_load_dwordx4 v[228:231], v243, s[12:13]
	global_load_dwordx4 v[232:235], v243, s[12:13] offset:16
	v_lshrrev_b32_e32 v244, 1, v243
	global_load_dwordx4 v[224:227], v244, s[20:21]
	v_lshrrev_b32_e32 v244, 10, v243
	v_and_b32_e32 v244, -8, v244
	global_load_dwordx2 v[236:237], v244, s[22:23]
	s_waitcnt vmcnt(12)
	v_mul_f32_e32 v168, 0x3a000000, v208
	v_mul_f32_e32 v171, 0x3a000000, v209
	v_fma_f32 v170, -v168, v168, v171
	v_add_f32_e32 v170, 0x3727c5ac, v170
	v_cmp_gt_f32_e32 vcc, s33, v170
	v_mul_f32_e32 v171, 0x4f800000, v170
	s_nop 0
	v_cndmask_b32_e32 v170, v170, v171, vcc
	v_sqrt_f32_e32 v171, v170
	v_lshlrev_b32_e32 v160, 16, v196
	v_and_b32_e32 v161, 0xffff0000, v196
	v_lshlrev_b32_e32 v162, 16, v197
	v_and_b32_e32 v163, 0xffff0000, v197
	v_lshlrev_b32_e32 v164, 16, v198
	v_and_b32_e32 v165, 0xffff0000, v198
	v_lshlrev_b32_e32 v166, 16, v199
	v_and_b32_e32 v167, 0xffff0000, v199
	v_add_u32_e32 v238, -1, v171
	v_fma_f32 v239, -v238, v171, v170
	v_cmp_ge_f32_e64 s[8:9], 0, v239
	v_add_u32_e32 v239, 1, v171
	s_nop 0
	v_cndmask_b32_e64 v238, v171, v238, s[8:9]
	v_fma_f32 v171, -v239, v171, v170
	v_cmp_lt_f32_e64 s[8:9], 0, v171
	s_nop 1
	v_cndmask_b32_e64 v171, v238, v239, s[8:9]
	v_mul_f32_e32 v238, 0x37800000, v171
	v_cndmask_b32_e32 v171, v171, v238, vcc
	v_cmp_class_f32_e32 vcc, v170, v249
	s_nop 1
	v_cndmask_b32_e32 v170, v171, v170, vcc
	v_div_scale_f32 v171, s[4:5], v170, v170, 1.0
	v_rcp_f32_e32 v238, v171
	s_nop 0
	v_fma_f32 v239, -v171, v238, 1.0
	v_fmac_f32_e32 v238, v239, v238
	v_div_scale_f32 v239, vcc, 1.0, v170, 1.0
	v_mul_f32_e32 v240, v239, v238
	v_fma_f32 v241, -v171, v240, v239
	v_fmac_f32_e32 v240, v241, v238
	v_fma_f32 v171, -v171, v240, v239
	v_div_fmas_f32 v171, v171, v238, v240
	v_div_fixup_f32 v169, v171, v170, 1.0
	v_fma_f32 v52, -v144, v168, v52
	v_fma_f32 v53, -v145, v168, v53
	v_fma_f32 v54, -v146, v168, v54
	v_fma_f32 v55, -v147, v168, v55
	v_fma_f32 v48, -v148, v168, v48
	v_fma_f32 v49, -v149, v168, v49
	v_fma_f32 v50, -v150, v168, v50
	v_fma_f32 v51, -v151, v168, v51
	v_sub_f32_e32 v200, v200, v168
	v_sub_f32_e32 v201, v201, v168
	v_sub_f32_e32 v202, v202, v168
	v_sub_f32_e32 v203, v203, v168
	v_sub_f32_e32 v204, v204, v168
	v_sub_f32_e32 v205, v205, v168
	v_sub_f32_e32 v206, v206, v168
	v_sub_f32_e32 v207, v207, v168
	v_fma_f32 v52, v52, v169, v152
	v_fma_f32 v53, v53, v169, v153
	v_fma_f32 v54, v54, v169, v154
	v_fma_f32 v55, v55, v169, v155
	v_fma_f32 v48, v48, v169, v156
	v_fma_f32 v49, v49, v169, v157
	v_fma_f32 v50, v50, v169, v158
	v_fma_f32 v51, v51, v169, v159
	v_mul_f32_e32 v200, v200, v169
	v_mul_f32_e32 v201, v201, v169
	v_mul_f32_e32 v202, v202, v169
	v_mul_f32_e32 v203, v203, v169
	v_mul_f32_e32 v204, v204, v169
	v_mul_f32_e32 v205, v205, v169
	v_mul_f32_e32 v206, v206, v169
	v_mul_f32_e32 v207, v207, v169
	v_mul_f32_e32 v52, 0xbfb8aa3b, v52
	v_mul_f32_e32 v53, 0xbfb8aa3b, v53
	v_mul_f32_e32 v54, 0xbfb8aa3b, v54
	v_mul_f32_e32 v55, 0xbfb8aa3b, v55
	v_mul_f32_e32 v48, 0xbfb8aa3b, v48
	v_mul_f32_e32 v49, 0xbfb8aa3b, v49
	v_mul_f32_e32 v50, 0xbfb8aa3b, v50
	v_mul_f32_e32 v51, 0xbfb8aa3b, v51
	v_fma_f32 v200, v128, v200, v136
	v_fma_f32 v201, v129, v201, v137
	v_fma_f32 v202, v130, v202, v138
	v_fma_f32 v203, v131, v203, v139
	v_fma_f32 v204, v132, v204, v140
	v_fma_f32 v205, v133, v205, v141
	v_fma_f32 v206, v134, v206, v142
	v_fma_f32 v207, v135, v207, v143
	v_exp_f32_e32 v52, v52
	v_exp_f32_e32 v53, v53
	v_exp_f32_e32 v54, v54
	v_exp_f32_e32 v55, v55
	v_exp_f32_e32 v48, v48
	v_exp_f32_e32 v49, v49
	v_exp_f32_e32 v50, v50
	v_exp_f32_e32 v51, v51
	v_add_f32_e32 v52, 1.0, v52
	v_add_f32_e32 v53, 1.0, v53
	v_add_f32_e32 v54, 1.0, v54
	v_add_f32_e32 v55, 1.0, v55
	v_add_f32_e32 v48, 1.0, v48
	v_add_f32_e32 v49, 1.0, v49
	v_add_f32_e32 v50, 1.0, v50
	v_add_f32_e32 v51, 1.0, v51
	v_rcp_f32_e32 v52, v52
	v_rcp_f32_e32 v53, v53
	v_rcp_f32_e32 v54, v54
	v_rcp_f32_e32 v55, v55
	v_rcp_f32_e32 v48, v48
	v_rcp_f32_e32 v49, v49
	v_rcp_f32_e32 v50, v50
	v_rcp_f32_e32 v51, v51
	v_fma_f32 v200, v52, v160, v200
	v_fma_f32 v201, v53, v161, v201
	v_fma_f32 v202, v54, v162, v202
	v_fma_f32 v203, v55, v163, v203
	v_fma_f32 v204, v48, v164, v204
	v_fma_f32 v205, v49, v165, v205
	v_fma_f32 v206, v50, v166, v206
	v_fma_f32 v207, v51, v167, v207
	v_add_u32_e32 v243, 0x20200, v242
	global_store_dwordx4 v243, v[200:203], s[12:13]
	global_store_dwordx4 v243, v[204:207], s[12:13] offset:16
	s_and_b64 s[4:5], exec, s[16:17]
	s_cbranch_scc0 .Leg_noxb_9
	v_cvt_pk_bf16_f32 v196, v200, v201
	v_cvt_pk_bf16_f32 v197, v202, v203
	v_cvt_pk_bf16_f32 v198, v204, v205
	v_cvt_pk_bf16_f32 v199, v206, v207
	v_lshrrev_b32_e32 v244, 1, v243
	global_store_dwordx4 v244, v[196:199], s[18:19]
; __device__ __forceinline__ f32x4 sig4(f32x4 v) { return (f32x4){sigmoidf_(v[0]), sigmoidf_(v[1]), sigmoidf_(v[2]), sigmoidf_(v[3])}; }
; __device__ __forceinline__ void unpack8(u32x4 w, f32x4& a, f32x4& b) { a = (f32x4){bf_lo(w.x), bf_hi(w.x), bf_lo(w.y), bf_hi(w.y)}; b = (f32x4){bf_lo(w.z), bf_hi(w.z), bf_lo(w.w), bf_hi(w.w)}; }
; __device__ __forceinline__ u32x4 pack8(f32x4 a, f32x4 b) { u32x4 w; w.x = cvt_pk_bf16(a[0], a[1]); w.y = cvt_pk_bf16(a[2], a[3]); w.z = cvt_pk_bf16(b[0], b[1]); w.w = cvt_pk_bf16(b[2], b[3]); return w; }
;     __device__ __forceinline__ void operator()(AccRef acc, const Unit& u, int wr, int wc, int fr, int fq) const {
;     ...
;                 u32x4 pw[4]; f32x4 yv[4][2]; f32x2 st[4];
; #pragma unroll
;                 for (int m = mh; m < mh + 2; ++m) { const int row = row0 + ai * 128 + m * 16; const size_t ro = (size_t)row * DM + c0 + bj * 128;
;                     pw[m] = *(const u32x4*)(PLEB + ro); yv[m][0] = *(const f32x4*)(X + ro); yv[m][1] = *(const f32x4*)(X + ro + 4); st[m] = *(const f32x2*)(stats + 2 * row); }
; #pragma unroll
;                 for (int m = mh; m < mh + 2; ++m) { const int row = row0 + ai * 128 + m * 16; const size_t ro = (size_t)row * DM + c0 + bj * 128;
;                     const float mu = st[m].x * (1.f / DM), var = st[m].y * (1.f / DM) - mu * mu, r = 1.f / sqrtf(var + LN_EPS);
;                     f32x4 p0, p1; unpack8(pw[m], p0, p1);
;                     const f32x4 x0 = (yv[m][0] - mu) * r * g0 + b0, x1 = (yv[m][1] - mu) * r * g1 + b1;
;                     const f32x4 o0 = x0 + sig4((acc[ai][bj][m][0] - mu * cg0) * r + cb0) * p0, o1 = x1 + sig4((acc[ai][bj][m][1] - mu * cg1) * r + cb1) * p1;
;                     *(f32x4*)(X + ro) = o0; *(f32x4*)(X + ro + 4) = o1; if (XB) *(u32x4*)(XB + ro) = pack8(o0, o1); }
;                 asm volatile("" ::: "memory");
.Leg_noxb_9:
	v_add_u32_e32 v243, 0x100200, v242
	global_load_dwordx4 v[200:203], v243, s[12:13]
	global_load_dwordx4 v[204:207], v243, s[12:13] offset:16
	v_lshrrev_b32_e32 v244, 1, v243
	global_load_dwordx4 v[196:199], v244, s[20:21]
	v_lshrrev_b32_e32 v244, 10, v243
	v_and_b32_e32 v244, -8, v244
	global_load_dwordx2 v[208:209], v244, s[22:23]
	s_waitcnt vmcnt(12)
	v_mul_f32_e32 v168, 0x3a000000, v222
	v_mul_f32_e32 v171, 0x3a000000, v223
	v_fma_f32 v170, -v168, v168, v171
	v_add_f32_e32 v170, 0x3727c5ac, v170
	v_cmp_gt_f32_e32 vcc, s33, v170
	v_mul_f32_e32 v171, 0x4f800000, v170
	s_nop 0
	v_cndmask_b32_e32 v170, v170, v171, vcc
	v_sqrt_f32_e32 v171, v170
	v_lshlrev_b32_e32 v160, 16, v210
	v_and_b32_e32 v161, 0xffff0000, v210
	v_lshlrev_b32_e32 v162, 16, v211
	v_and_b32_e32 v163, 0xffff0000, v211
	v_lshlrev_b32_e32 v164, 16, v212
	v_and_b32_e32 v165, 0xffff0000, v212
	v_lshlrev_b32_e32 v166, 16, v213
	v_and_b32_e32 v167, 0xffff0000, v213
	v_add_u32_e32 v238, -1, v171
	v_fma_f32 v239, -v238, v171, v170
	v_cmp_ge_f32_e64 s[8:9], 0, v239
	v_add_u32_e32 v239, 1, v171
	s_nop 0
	v_cndmask_b32_e64 v238, v171, v238, s[8:9]
	v_fma_f32 v171, -v239, v171, v170
	v_cmp_lt_f32_e64 s[8:9], 0, v171
	s_nop 1
	v_cndmask_b32_e64 v171, v238, v239, s[8:9]
	v_mul_f32_e32 v238, 0x37800000, v171
	v_cndmask_b32_e32 v171, v171, v238, vcc
	v_cmp_class_f32_e32 vcc, v170, v249
	s_nop 1
	v_cndmask_b32_e32 v170, v171, v170, vcc
	v_div_scale_f32 v171, s[4:5], v170, v170, 1.0
	v_rcp_f32_e32 v238, v171
	s_nop 0
	v_fma_f32 v239, -v171, v238, 1.0
	v_fmac_f32_e32 v238, v239, v238
	v_div_scale_f32 v239, vcc, 1.0, v170, 1.0
	v_mul_f32_e32 v240, v239, v238
	v_fma_f32 v241, -v171, v240, v239
	v_fmac_f32_e32 v240, v241, v238
	v_fma_f32 v171, -v171, v240, v239
	v_div_fmas_f32 v171, v171, v238, v240
	v_div_fixup_f32 v169, v171, v170, 1.0
	v_fma_f32 v44, -v144, v168, v44
	v_fma_f32 v45, -v145, v168, v45
	v_fma_f32 v46, -v146, v168, v46
	v_fma_f32 v47, -v147, v168, v47
	v_fma_f32 v40, -v148, v168, v40
	v_fma_f32 v41, -v149, v168, v41
	v_fma_f32 v42, -v150, v168, v42
	v_fma_f32 v43, -v151, v168, v43
	v_sub_f32_e32 v214, v214, v168
	v_sub_f32_e32 v215, v215, v168
	v_sub_f32_e32 v216, v216, v168
	v_sub_f32_e32 v217, v217, v168
	v_sub_f32_e32 v218, v218, v168
	v_sub_f32_e32 v219, v219, v168
	v_sub_f32_e32 v220, v220, v168
	v_sub_f32_e32 v221, v221, v168
	v_fma_f32 v44, v44, v169, v152
	v_fma_f32 v45, v45, v169, v153
	v_fma_f32 v46, v46, v169, v154
	v_fma_f32 v47, v47, v169, v155
	v_fma_f32 v40, v40, v169, v156
	v_fma_f32 v41, v41, v169, v157
	v_fma_f32 v42, v42, v169, v158
	v_fma_f32 v43, v43, v169, v159
	v_mul_f32_e32 v214, v214, v169
	v_mul_f32_e32 v215, v215, v169
	v_mul_f32_e32 v216, v216, v169
	v_mul_f32_e32 v217, v217, v169
	v_mul_f32_e32 v218, v218, v169
	v_mul_f32_e32 v219, v219, v169
	v_mul_f32_e32 v220, v220, v169
	v_mul_f32_e32 v221, v221, v169
	v_mul_f32_e32 v44, 0xbfb8aa3b, v44
	v_mul_f32_e32 v45, 0xbfb8aa3b, v45
	v_mul_f32_e32 v46, 0xbfb8aa3b, v46
	v_mul_f32_e32 v47, 0xbfb8aa3b, v47
	v_mul_f32_e32 v40, 0xbfb8aa3b, v40
	v_mul_f32_e32 v41, 0xbfb8aa3b, v41
	v_mul_f32_e32 v42, 0xbfb8aa3b, v42
	v_mul_f32_e32 v43, 0xbfb8aa3b, v43
	v_fma_f32 v214, v128, v214, v136
	v_fma_f32 v215, v129, v215, v137
	v_fma_f32 v216, v130, v216, v138
	v_fma_f32 v217, v131, v217, v139
	v_fma_f32 v218, v132, v218, v140
	v_fma_f32 v219, v133, v219, v141
	v_fma_f32 v220, v134, v220, v142
	v_fma_f32 v221, v135, v221, v143
	v_exp_f32_e32 v44, v44
	v_exp_f32_e32 v45, v45
	v_exp_f32_e32 v46, v46
	v_exp_f32_e32 v47, v47
	v_exp_f32_e32 v40, v40
	v_exp_f32_e32 v41, v41
	v_exp_f32_e32 v42, v42
	v_exp_f32_e32 v43, v43
	v_add_f32_e32 v44, 1.0, v44
	v_add_f32_e32 v45, 1.0, v45
	v_add_f32_e32 v46, 1.0, v46
	v_add_f32_e32 v47, 1.0, v47
	v_add_f32_e32 v40, 1.0, v40
	v_add_f32_e32 v41, 1.0, v41
	v_add_f32_e32 v42, 1.0, v42
	v_add_f32_e32 v43, 1.0, v43
	v_rcp_f32_e32 v44, v44
	v_rcp_f32_e32 v45, v45
	v_rcp_f32_e32 v46, v46
	v_rcp_f32_e32 v47, v47
	v_rcp_f32_e32 v40, v40
	v_rcp_f32_e32 v41, v41
	v_rcp_f32_e32 v42, v42
	v_rcp_f32_e32 v43, v43
	v_fma_f32 v214, v44, v160, v214
	v_fma_f32 v215, v45, v161, v215
	v_fma_f32 v216, v46, v162, v216
	v_fma_f32 v217, v47, v163, v217
	v_fma_f32 v218, v40, v164, v218
	v_fma_f32 v219, v41, v165, v219
	v_fma_f32 v220, v42, v166, v220
	v_fma_f32 v221, v43, v167, v221
	v_add_u32_e32 v243, 0x40200, v242
	global_store_dwordx4 v243, v[214:217], s[12:13]
	global_store_dwordx4 v243, v[218:221], s[12:13] offset:16
	s_and_b64 s[4:5], exec, s[16:17]
	s_cbranch_scc0 .Leg_noxb_10
	v_cvt_pk_bf16_f32 v210, v214, v215
	v_cvt_pk_bf16_f32 v211, v216, v217
	v_cvt_pk_bf16_f32 v212, v218, v219
	v_cvt_pk_bf16_f32 v213, v220, v221
	v_lshrrev_b32_e32 v244, 1, v243
	global_store_dwordx4 v244, v[210:213], s[18:19]
; __device__ __forceinline__ f32x4 sig4(f32x4 v) { return (f32x4){sigmoidf_(v[0]), sigmoidf_(v[1]), sigmoidf_(v[2]), sigmoidf_(v[3])}; }
; __device__ __forceinline__ void unpack8(u32x4 w, f32x4& a, f32x4& b) { a = (f32x4){bf_lo(w.x), bf_hi(w.x), bf_lo(w.y), bf_hi(w.y)}; b = (f32x4){bf_lo(w.z), bf_hi(w.z), bf_lo(w.w), bf_hi(w.w)}; }
; __device__ __forceinline__ u32x4 pack8(f32x4 a, f32x4 b) { u32x4 w; w.x = cvt_pk_bf16(a[0], a[1]); w.y = cvt_pk_bf16(a[2], a[3]); w.z = cvt_pk_bf16(b[0], b[1]); w.w = cvt_pk_bf16(b[2], b[3]); return w; }
;     __device__ __forceinline__ void operator()(AccRef acc, const Unit& u, int wr, int wc, int fr, int fq) const {
;     ...
;                 u32x4 pw[4]; f32x4 yv[4][2]; f32x2 st[4];
; #pragma unroll
;                 for (int m = mh; m < mh + 2; ++m) { const int row = row0 + ai * 128 + m * 16; const size_t ro = (size_t)row * DM + c0 + bj * 128;
;                     pw[m] = *(const u32x4*)(PLEB + ro); yv[m][0] = *(const f32x4*)(X + ro); yv[m][1] = *(const f32x4*)(X + ro + 4); st[m] = *(const f32x2*)(stats + 2 * row); }
; #pragma unroll
;                 for (int m = mh; m < mh + 2; ++m) { const int row = row0 + ai * 128 + m * 16; const size_t ro = (size_t)row * DM + c0 + bj * 128;
;                     const float mu = st[m].x * (1.f / DM), var = st[m].y * (1.f / DM) - mu * mu, r = 1.f / sqrtf(var + LN_EPS);
;                     f32x4 p0, p1; unpack8(pw[m], p0, p1);
;                     const f32x4 x0 = (yv[m][0] - mu) * r * g0 + b0, x1 = (yv[m][1] - mu) * r * g1 + b1;
;                     const f32x4 o0 = x0 + sig4((acc[ai][bj][m][0] - mu * cg0) * r + cb0) * p0, o1 = x1 + sig4((acc[ai][bj][m][1] - mu * cg1) * r + cb1) * p1;
;                     *(f32x4*)(X + ro) = o0; *(f32x4*)(X + ro + 4) = o1; if (XB) *(u32x4*)(XB + ro) = pack8(o0, o1); }
;                 asm volatile("" ::: "memory");
.Leg_noxb_10:
	v_add_u32_e32 v243, 0x120200, v242
	global_load_dwordx4 v[214:217], v243, s[12:13]
	global_load_dwordx4 v[218:221], v243, s[12:13] offset:16
	v_lshrrev_b32_e32 v244, 1, v243
	global_load_dwordx4 v[210:213], v244, s[20:21]
	v_lshrrev_b32_e32 v244, 10, v243
	v_and_b32_e32 v244, -8, v244
	global_load_dwordx2 v[222:223], v244, s[22:23]
	s_waitcnt vmcnt(12)
	v_mul_f32_e32 v168, 0x3a000000, v236
	v_mul_f32_e32 v171, 0x3a000000, v237
	v_fma_f32 v170, -v168, v168, v171
	v_add_f32_e32 v170, 0x3727c5ac, v170
	v_cmp_gt_f32_e32 vcc, s33, v170
	v_mul_f32_e32 v171, 0x4f800000, v170
	s_nop 0
	v_cndmask_b32_e32 v170, v170, v171, vcc
	v_sqrt_f32_e32 v171, v170
	v_lshlrev_b32_e32 v160, 16, v224
	v_and_b32_e32 v161, 0xffff0000, v224
	v_lshlrev_b32_e32 v162, 16, v225
	v_and_b32_e32 v163, 0xffff0000, v225
	v_lshlrev_b32_e32 v164, 16, v226
	v_and_b32_e32 v165, 0xffff0000, v226
	v_lshlrev_b32_e32 v166, 16, v227
	v_and_b32_e32 v167, 0xffff0000, v227
	v_add_u32_e32 v238, -1, v171
	v_fma_f32 v239, -v238, v171, v170
	v_cmp_ge_f32_e64 s[8:9], 0, v239
	v_add_u32_e32 v239, 1, v171
	s_nop 0
	v_cndmask_b32_e64 v238, v171, v238, s[8:9]
	v_fma_f32 v171, -v239, v171, v170
	v_cmp_lt_f32_e64 s[8:9], 0, v171
	s_nop 1
	v_cndmask_b32_e64 v171, v238, v239, s[8:9]
	v_mul_f32_e32 v238, 0x37800000, v171
	v_cndmask_b32_e32 v171, v171, v238, vcc
	v_cmp_class_f32_e32 vcc, v170, v249
	s_nop 1
	v_cndmask_b32_e32 v170, v171, v170, vcc
	v_div_scale_f32 v171, s[4:5], v170, v170, 1.0
	v_rcp_f32_e32 v238, v171
	s_nop 0
	v_fma_f32 v239, -v171, v238, 1.0
	v_fmac_f32_e32 v238, v239, v238
	v_div_scale_f32 v239, vcc, 1.0, v170, 1.0
	v_mul_f32_e32 v240, v239, v238
	v_fma_f32 v241, -v171, v240, v239
	v_fmac_f32_e32 v240, v241, v238
	v_fma_f32 v171, -v171, v240, v239
	v_div_fmas_f32 v171, v171, v238, v240
	v_div_fixup_f32 v169, v171, v170, 1.0
	v_fma_f32 v36, -v144, v168, v36
	v_fma_f32 v37, -v145, v168, v37
	v_fma_f32 v38, -v146, v168, v38
	v_fma_f32 v39, -v147, v168, v39
	v_fma_f32 v32, -v148, v168, v32
	v_fma_f32 v33, -v149, v168, v33
	v_fma_f32 v34, -v150, v168, v34
	v_fma_f32 v35, -v151, v168, v35
	v_sub_f32_e32 v228, v228, v168
	v_sub_f32_e32 v229, v229, v168
	v_sub_f32_e32 v230, v230, v168
	v_sub_f32_e32 v231, v231, v168
	v_sub_f32_e32 v232, v232, v168
	v_sub_f32_e32 v233, v233, v168
	v_sub_f32_e32 v234, v234, v168
	v_sub_f32_e32 v235, v235, v168
	v_fma_f32 v36, v36, v169, v152
	v_fma_f32 v37, v37, v169, v153
	v_fma_f32 v38, v38, v169, v154
	v_fma_f32 v39, v39, v169, v155
	v_fma_f32 v32, v32, v169, v156
	v_fma_f32 v33, v33, v169, v157
	v_fma_f32 v34, v34, v169, v158
	v_fma_f32 v35, v35, v169, v159
	v_mul_f32_e32 v228, v228, v169
	v_mul_f32_e32 v229, v229, v169
	v_mul_f32_e32 v230, v230, v169
	v_mul_f32_e32 v231, v231, v169
	v_mul_f32_e32 v232, v232, v169
	v_mul_f32_e32 v233, v233, v169
	v_mul_f32_e32 v234, v234, v169
	v_mul_f32_e32 v235, v235, v169
	v_mul_f32_e32 v36, 0xbfb8aa3b, v36
	v_mul_f32_e32 v37, 0xbfb8aa3b, v37
	v_mul_f32_e32 v38, 0xbfb8aa3b, v38
	v_mul_f32_e32 v39, 0xbfb8aa3b, v39
	v_mul_f32_e32 v32, 0xbfb8aa3b, v32
	v_mul_f32_e32 v33, 0xbfb8aa3b, v33
	v_mul_f32_e32 v34, 0xbfb8aa3b, v34
	v_mul_f32_e32 v35, 0xbfb8aa3b, v35
	v_fma_f32 v228, v128, v228, v136
	v_fma_f32 v229, v129, v229, v137
	v_fma_f32 v230, v130, v230, v138
	v_fma_f32 v231, v131, v231, v139
	v_fma_f32 v232, v132, v232, v140
	v_fma_f32 v233, v133, v233, v141
	v_fma_f32 v234, v134, v234, v142
	v_fma_f32 v235, v135, v235, v143
	v_exp_f32_e32 v36, v36
	v_exp_f32_e32 v37, v37
	v_exp_f32_e32 v38, v38
	v_exp_f32_e32 v39, v39
	v_exp_f32_e32 v32, v32
	v_exp_f32_e32 v33, v33
	v_exp_f32_e32 v34, v34
	v_exp_f32_e32 v35, v35
	v_add_f32_e32 v36, 1.0, v36
	v_add_f32_e32 v37, 1.0, v37
	v_add_f32_e32 v38, 1.0, v38
	v_add_f32_e32 v39, 1.0, v39
	v_add_f32_e32 v32, 1.0, v32
	v_add_f32_e32 v33, 1.0, v33
	v_add_f32_e32 v34, 1.0, v34
	v_add_f32_e32 v35, 1.0, v35
	v_rcp_f32_e32 v36, v36
	v_rcp_f32_e32 v37, v37
	v_rcp_f32_e32 v38, v38
	v_rcp_f32_e32 v39, v39
	v_rcp_f32_e32 v32, v32
	v_rcp_f32_e32 v33, v33
	v_rcp_f32_e32 v34, v34
	v_rcp_f32_e32 v35, v35
	v_fma_f32 v228, v36, v160, v228
	v_fma_f32 v229, v37, v161, v229
	v_fma_f32 v230, v38, v162, v230
	v_fma_f32 v231, v39, v163, v231
	v_fma_f32 v232, v32, v164, v232
	v_fma_f32 v233, v33, v165, v233
	v_fma_f32 v234, v34, v166, v234
	v_fma_f32 v235, v35, v167, v235
	v_add_u32_e32 v243, 0x60200, v242
	global_store_dwordx4 v243, v[228:231], s[12:13]
	global_store_dwordx4 v243, v[232:235], s[12:13] offset:16
	s_and_b64 s[4:5], exec, s[16:17]
	s_cbranch_scc0 .Leg_noxb_11
	v_cvt_pk_bf16_f32 v224, v228, v229
	v_cvt_pk_bf16_f32 v225, v230, v231
	v_cvt_pk_bf16_f32 v226, v232, v233
	v_cvt_pk_bf16_f32 v227, v234, v235
	v_lshrrev_b32_e32 v244, 1, v243
	global_store_dwordx4 v244, v[224:227], s[18:19]
; __device__ __forceinline__ f32x4 sig4(f32x4 v) { return (f32x4){sigmoidf_(v[0]), sigmoidf_(v[1]), sigmoidf_(v[2]), sigmoidf_(v[3])}; }
; __device__ __forceinline__ void unpack8(u32x4 w, f32x4& a, f32x4& b) { a = (f32x4){bf_lo(w.x), bf_hi(w.x), bf_lo(w.y), bf_hi(w.y)}; b = (f32x4){bf_lo(w.z), bf_hi(w.z), bf_lo(w.w), bf_hi(w.w)}; }
; __device__ __forceinline__ u32x4 pack8(f32x4 a, f32x4 b) { u32x4 w; w.x = cvt_pk_bf16(a[0], a[1]); w.y = cvt_pk_bf16(a[2], a[3]); w.z = cvt_pk_bf16(b[0], b[1]); w.w = cvt_pk_bf16(b[2], b[3]); return w; }
;     __device__ __forceinline__ void operator()(AccRef acc, const Unit& u, int wr, int wc, int fr, int fq) const {
;     ...
;                 u32x4 pw[4]; f32x4 yv[4][2]; f32x2 st[4];
; #pragma unroll
;                 for (int m = mh; m < mh + 2; ++m) { const int row = row0 + ai * 128 + m * 16; const size_t ro = (size_t)row * DM + c0 + bj * 128;
;                     pw[m] = *(const u32x4*)(PLEB + ro); yv[m][0] = *(const f32x4*)(X + ro); yv[m][1] = *(const f32x4*)(X + ro + 4); st[m] = *(const f32x2*)(stats + 2 * row); }
; #pragma unroll
;                 for (int m = mh; m < mh + 2; ++m) { const int row = row0 + ai * 128 + m * 16; const size_t ro = (size_t)row * DM + c0 + bj * 128;
;                     const float mu = st[m].x * (1.f / DM), var = st[m].y * (1.f / DM) - mu * mu, r = 1.f / sqrtf(var + LN_EPS);
;                     f32x4 p0, p1; unpack8(pw[m], p0, p1);
;                     const f32x4 x0 = (yv[m][0] - mu) * r * g0 + b0, x1 = (yv[m][1] - mu) * r * g1 + b1;
;                     const f32x4 o0 = x0 + sig4((acc[ai][bj][m][0] - mu * cg0) * r + cb0) * p0, o1 = x1 + sig4((acc[ai][bj][m][1] - mu * cg1) * r + cb1) * p1;
;                     *(f32x4*)(X + ro) = o0; *(f32x4*)(X + ro + 4) = o1; if (XB) *(u32x4*)(XB + ro) = pack8(o0, o1); }
;                 asm volatile("" ::: "memory");
.Leg_noxb_11:
	v_add_u32_e32 v243, 0x140200, v242
	global_load_dwordx4 v[228:231], v243, s[12:13]
	global_load_dwordx4 v[232:235], v243, s[12:13] offset:16
	v_lshrrev_b32_e32 v244, 1, v243
	global_load_dwordx4 v[224:227], v244, s[20:21]
	v_lshrrev_b32_e32 v244, 10, v243
	v_and_b32_e32 v244, -8, v244
	global_load_dwordx2 v[236:237], v244, s[22:23]
	s_waitcnt vmcnt(12)
	v_mul_f32_e32 v168, 0x3a000000, v208
	v_mul_f32_e32 v171, 0x3a000000, v209
	v_fma_f32 v170, -v168, v168, v171
	v_add_f32_e32 v170, 0x3727c5ac, v170
	v_cmp_gt_f32_e32 vcc, s33, v170
	v_mul_f32_e32 v171, 0x4f800000, v170
	s_nop 0
	v_cndmask_b32_e32 v170, v170, v171, vcc
	v_sqrt_f32_e32 v171, v170
	v_lshlrev_b32_e32 v160, 16, v196
	v_and_b32_e32 v161, 0xffff0000, v196
	v_lshlrev_b32_e32 v162, 16, v197
	v_and_b32_e32 v163, 0xffff0000, v197
	v_lshlrev_b32_e32 v164, 16, v198
	v_and_b32_e32 v165, 0xffff0000, v198
	v_lshlrev_b32_e32 v166, 16, v199
	v_and_b32_e32 v167, 0xffff0000, v199
	v_add_u32_e32 v238, -1, v171
	v_fma_f32 v239, -v238, v171, v170
	v_cmp_ge_f32_e64 s[8:9], 0, v239
	v_add_u32_e32 v239, 1, v171
	s_nop 0
	v_cndmask_b32_e64 v238, v171, v238, s[8:9]
	v_fma_f32 v171, -v239, v171, v170
	v_cmp_lt_f32_e64 s[8:9], 0, v171
	s_nop 1
	v_cndmask_b32_e64 v171, v238, v239, s[8:9]
	v_mul_f32_e32 v238, 0x37800000, v171
	v_cndmask_b32_e32 v171, v171, v238, vcc
	v_cmp_class_f32_e32 vcc, v170, v249
	s_nop 1
	v_cndmask_b32_e32 v170, v171, v170, vcc
	v_div_scale_f32 v171, s[4:5], v170, v170, 1.0
	v_rcp_f32_e32 v238, v171
	s_nop 0
	v_fma_f32 v239, -v171, v238, 1.0
	v_fmac_f32_e32 v238, v239, v238
	v_div_scale_f32 v239, vcc, 1.0, v170, 1.0
	v_mul_f32_e32 v240, v239, v238
	v_fma_f32 v241, -v171, v240, v239
	v_fmac_f32_e32 v240, v241, v238
	v_fma_f32 v171, -v171, v240, v239
	v_div_fmas_f32 v171, v171, v238, v240
	v_div_fixup_f32 v169, v171, v170, 1.0
	v_fma_f32 v28, -v144, v168, v28
	v_fma_f32 v29, -v145, v168, v29
	v_fma_f32 v30, -v146, v168, v30
	v_fma_f32 v31, -v147, v168, v31
	v_fma_f32 v24, -v148, v168, v24
	v_fma_f32 v25, -v149, v168, v25
	v_fma_f32 v26, -v150, v168, v26
	v_fma_f32 v27, -v151, v168, v27
	v_sub_f32_e32 v200, v200, v168
	v_sub_f32_e32 v201, v201, v168
	v_sub_f32_e32 v202, v202, v168
	v_sub_f32_e32 v203, v203, v168
	v_sub_f32_e32 v204, v204, v168
	v_sub_f32_e32 v205, v205, v168
	v_sub_f32_e32 v206, v206, v168
	v_sub_f32_e32 v207, v207, v168
	v_fma_f32 v28, v28, v169, v152
	v_fma_f32 v29, v29, v169, v153
	v_fma_f32 v30, v30, v169, v154
	v_fma_f32 v31, v31, v169, v155
	v_fma_f32 v24, v24, v169, v156
	v_fma_f32 v25, v25, v169, v157
	v_fma_f32 v26, v26, v169, v158
	v_fma_f32 v27, v27, v169, v159
	v_mul_f32_e32 v200, v200, v169
	v_mul_f32_e32 v201, v201, v169
	v_mul_f32_e32 v202, v202, v169
	v_mul_f32_e32 v203, v203, v169
	v_mul_f32_e32 v204, v204, v169
	v_mul_f32_e32 v205, v205, v169
	v_mul_f32_e32 v206, v206, v169
	v_mul_f32_e32 v207, v207, v169
	v_mul_f32_e32 v28, 0xbfb8aa3b, v28
	v_mul_f32_e32 v29, 0xbfb8aa3b, v29
	v_mul_f32_e32 v30, 0xbfb8aa3b, v30
	v_mul_f32_e32 v31, 0xbfb8aa3b, v31
	v_mul_f32_e32 v24, 0xbfb8aa3b, v24
	v_mul_f32_e32 v25, 0xbfb8aa3b, v25
	v_mul_f32_e32 v26, 0xbfb8aa3b, v26
	v_mul_f32_e32 v27, 0xbfb8aa3b, v27
	v_fma_f32 v200, v128, v200, v136
	v_fma_f32 v201, v129, v201, v137
	v_fma_f32 v202, v130, v202, v138
	v_fma_f32 v203, v131, v203, v139
	v_fma_f32 v204, v132, v204, v140
	v_fma_f32 v205, v133, v205, v141
	v_fma_f32 v206, v134, v206, v142
	v_fma_f32 v207, v135, v207, v143
	v_exp_f32_e32 v28, v28
	v_exp_f32_e32 v29, v29
	v_exp_f32_e32 v30, v30
	v_exp_f32_e32 v31, v31
	v_exp_f32_e32 v24, v24
	v_exp_f32_e32 v25, v25
	v_exp_f32_e32 v26, v26
	v_exp_f32_e32 v27, v27
	v_add_f32_e32 v28, 1.0, v28
	v_add_f32_e32 v29, 1.0, v29
	v_add_f32_e32 v30, 1.0, v30
	v_add_f32_e32 v31, 1.0, v31
	v_add_f32_e32 v24, 1.0, v24
	v_add_f32_e32 v25, 1.0, v25
	v_add_f32_e32 v26, 1.0, v26
	v_add_f32_e32 v27, 1.0, v27
	v_rcp_f32_e32 v28, v28
	v_rcp_f32_e32 v29, v29
	v_rcp_f32_e32 v30, v30
	v_rcp_f32_e32 v31, v31
	v_rcp_f32_e32 v24, v24
	v_rcp_f32_e32 v25, v25
	v_rcp_f32_e32 v26, v26
	v_rcp_f32_e32 v27, v27
	v_fma_f32 v200, v28, v160, v200
	v_fma_f32 v201, v29, v161, v201
	v_fma_f32 v202, v30, v162, v202
	v_fma_f32 v203, v31, v163, v203
	v_fma_f32 v204, v24, v164, v204
	v_fma_f32 v205, v25, v165, v205
	v_fma_f32 v206, v26, v166, v206
	v_fma_f32 v207, v27, v167, v207
	v_add_u32_e32 v243, 0x100200, v242
	global_store_dwordx4 v243, v[200:203], s[12:13]
	global_store_dwordx4 v243, v[204:207], s[12:13] offset:16
	s_and_b64 s[4:5], exec, s[16:17]
	s_cbranch_scc0 .Leg_noxb_12
	v_cvt_pk_bf16_f32 v196, v200, v201
	v_cvt_pk_bf16_f32 v197, v202, v203
	v_cvt_pk_bf16_f32 v198, v204, v205
	v_cvt_pk_bf16_f32 v199, v206, v207
	v_lshrrev_b32_e32 v244, 1, v243
	global_store_dwordx4 v244, v[196:199], s[18:19]
; __device__ __forceinline__ f32x4 sig4(f32x4 v) { return (f32x4){sigmoidf_(v[0]), sigmoidf_(v[1]), sigmoidf_(v[2]), sigmoidf_(v[3])}; }
; __device__ __forceinline__ void unpack8(u32x4 w, f32x4& a, f32x4& b) { a = (f32x4){bf_lo(w.x), bf_hi(w.x), bf_lo(w.y), bf_hi(w.y)}; b = (f32x4){bf_lo(w.z), bf_hi(w.z), bf_lo(w.w), bf_hi(w.w)}; }
; __device__ __forceinline__ u32x4 pack8(f32x4 a, f32x4 b) { u32x4 w; w.x = cvt_pk_bf16(a[0], a[1]); w.y = cvt_pk_bf16(a[2], a[3]); w.z = cvt_pk_bf16(b[0], b[1]); w.w = cvt_pk_bf16(b[2], b[3]); return w; }
;     __device__ __forceinline__ void operator()(AccRef acc, const Unit& u, int wr, int wc, int fr, int fq) const {
;     ...
;                 u32x4 pw[4]; f32x4 yv[4][2]; f32x2 st[4];
; #pragma unroll
;                 for (int m = mh; m < mh + 2; ++m) { const int row = row0 + ai * 128 + m * 16; const size_t ro = (size_t)row * DM + c0 + bj * 128;
;                     pw[m] = *(const u32x4*)(PLEB + ro); yv[m][0] = *(const f32x4*)(X + ro); yv[m][1] = *(const f32x4*)(X + ro + 4); st[m] = *(const f32x2*)(stats + 2 * row); }
; #pragma unroll
;                 for (int m = mh; m < mh + 2; ++m) { const int row = row0 + ai * 128 + m * 16; const size_t ro = (size_t)row * DM + c0 + bj * 128;
;                     const float mu = st[m].x * (1.f / DM), var = st[m].y * (1.f / DM) - mu * mu, r = 1.f / sqrtf(var + LN_EPS);
;                     f32x4 p0, p1; unpack8(pw[m], p0, p1);
;                     const f32x4 x0 = (yv[m][0] - mu) * r * g0 + b0, x1 = (yv[m][1] - mu) * r * g1 + b1;
;                     const f32x4 o0 = x0 + sig4((acc[ai][bj][m][0] - mu * cg0) * r + cb0) * p0, o1 = x1 + sig4((acc[ai][bj][m][1] - mu * cg1) * r + cb1) * p1;
;                     *(f32x4*)(X + ro) = o0; *(f32x4*)(X + ro + 4) = o1; if (XB) *(u32x4*)(XB + ro) = pack8(o0, o1); }
;                 asm volatile("" ::: "memory");
.Leg_noxb_12:
	v_add_u32_e32 v243, 0x160200, v242
	global_load_dwordx4 v[200:203], v243, s[12:13]
	global_load_dwordx4 v[204:207], v243, s[12:13] offset:16
	v_lshrrev_b32_e32 v244, 1, v243
	global_load_dwordx4 v[196:199], v244, s[20:21]
	v_lshrrev_b32_e32 v244, 10, v243
	v_and_b32_e32 v244, -8, v244
	global_load_dwordx2 v[208:209], v244, s[22:23]
	s_waitcnt vmcnt(12)
	v_mul_f32_e32 v168, 0x3a000000, v222
	v_mul_f32_e32 v171, 0x3a000000, v223
	v_fma_f32 v170, -v168, v168, v171
	v_add_f32_e32 v170, 0x3727c5ac, v170
	v_cmp_gt_f32_e32 vcc, s33, v170
	v_mul_f32_e32 v171, 0x4f800000, v170
	s_nop 0
	v_cndmask_b32_e32 v170, v170, v171, vcc
	v_sqrt_f32_e32 v171, v170
	v_lshlrev_b32_e32 v160, 16, v210
	v_and_b32_e32 v161, 0xffff0000, v210
	v_lshlrev_b32_e32 v162, 16, v211
	v_and_b32_e32 v163, 0xffff0000, v211
	v_lshlrev_b32_e32 v164, 16, v212
	v_and_b32_e32 v165, 0xffff0000, v212
	v_lshlrev_b32_e32 v166, 16, v213
	v_and_b32_e32 v167, 0xffff0000, v213
	v_add_u32_e32 v238, -1, v171
	v_fma_f32 v239, -v238, v171, v170
	v_cmp_ge_f32_e64 s[8:9], 0, v239
	v_add_u32_e32 v239, 1, v171
	s_nop 0
	v_cndmask_b32_e64 v238, v171, v238, s[8:9]
	v_fma_f32 v171, -v239, v171, v170
	v_cmp_lt_f32_e64 s[8:9], 0, v171
	s_nop 1
	v_cndmask_b32_e64 v171, v238, v239, s[8:9]
	v_mul_f32_e32 v238, 0x37800000, v171
	v_cndmask_b32_e32 v171, v171, v238, vcc
	v_cmp_class_f32_e32 vcc, v170, v249
	s_nop 1
	v_cndmask_b32_e32 v170, v171, v170, vcc
	v_div_scale_f32 v171, s[4:5], v170, v170, 1.0
	v_rcp_f32_e32 v238, v171
	s_nop 0
	v_fma_f32 v239, -v171, v238, 1.0
	v_fmac_f32_e32 v238, v239, v238
	v_div_scale_f32 v239, vcc, 1.0, v170, 1.0
	v_mul_f32_e32 v240, v239, v238
	v_fma_f32 v241, -v171, v240, v239
	v_fmac_f32_e32 v240, v241, v238
	v_fma_f32 v171, -v171, v240, v239
	v_div_fmas_f32 v171, v171, v238, v240
	v_div_fixup_f32 v169, v171, v170, 1.0
	v_fma_f32 v20, -v144, v168, v20
	v_fma_f32 v21, -v145, v168, v21
	v_fma_f32 v22, -v146, v168, v22
	v_fma_f32 v23, -v147, v168, v23
	v_fma_f32 v16, -v148, v168, v16
	v_fma_f32 v17, -v149, v168, v17
	v_fma_f32 v18, -v150, v168, v18
	v_fma_f32 v19, -v151, v168, v19
	v_sub_f32_e32 v214, v214, v168
	v_sub_f32_e32 v215, v215, v168
	v_sub_f32_e32 v216, v216, v168
	v_sub_f32_e32 v217, v217, v168
	v_sub_f32_e32 v218, v218, v168
	v_sub_f32_e32 v219, v219, v168
	v_sub_f32_e32 v220, v220, v168
	v_sub_f32_e32 v221, v221, v168
	v_fma_f32 v20, v20, v169, v152
	v_fma_f32 v21, v21, v169, v153
	v_fma_f32 v22, v22, v169, v154
	v_fma_f32 v23, v23, v169, v155
	v_fma_f32 v16, v16, v169, v156
	v_fma_f32 v17, v17, v169, v157
	v_fma_f32 v18, v18, v169, v158
	v_fma_f32 v19, v19, v169, v159
	v_mul_f32_e32 v214, v214, v169
	v_mul_f32_e32 v215, v215, v169
	v_mul_f32_e32 v216, v216, v169
	v_mul_f32_e32 v217, v217, v169
	v_mul_f32_e32 v218, v218, v169
	v_mul_f32_e32 v219, v219, v169
	v_mul_f32_e32 v220, v220, v169
	v_mul_f32_e32 v221, v221, v169
	v_mul_f32_e32 v20, 0xbfb8aa3b, v20
	v_mul_f32_e32 v21, 0xbfb8aa3b, v21
	v_mul_f32_e32 v22, 0xbfb8aa3b, v22
	v_mul_f32_e32 v23, 0xbfb8aa3b, v23
	v_mul_f32_e32 v16, 0xbfb8aa3b, v16
	v_mul_f32_e32 v17, 0xbfb8aa3b, v17
	v_mul_f32_e32 v18, 0xbfb8aa3b, v18
	v_mul_f32_e32 v19, 0xbfb8aa3b, v19
	v_fma_f32 v214, v128, v214, v136
	v_fma_f32 v215, v129, v215, v137
	v_fma_f32 v216, v130, v216, v138
	v_fma_f32 v217, v131, v217, v139
	v_fma_f32 v218, v132, v218, v140
	v_fma_f32 v219, v133, v219, v141
	v_fma_f32 v220, v134, v220, v142
	v_fma_f32 v221, v135, v221, v143
	v_exp_f32_e32 v20, v20
	v_exp_f32_e32 v21, v21
	v_exp_f32_e32 v22, v22
	v_exp_f32_e32 v23, v23
	v_exp_f32_e32 v16, v16
	v_exp_f32_e32 v17, v17
	v_exp_f32_e32 v18, v18
	v_exp_f32_e32 v19, v19
	v_add_f32_e32 v20, 1.0, v20
	v_add_f32_e32 v21, 1.0, v21
	v_add_f32_e32 v22, 1.0, v22
	v_add_f32_e32 v23, 1.0, v23
	v_add_f32_e32 v16, 1.0, v16
	v_add_f32_e32 v17, 1.0, v17
	v_add_f32_e32 v18, 1.0, v18
	v_add_f32_e32 v19, 1.0, v19
	v_rcp_f32_e32 v20, v20
	v_rcp_f32_e32 v21, v21
	v_rcp_f32_e32 v22, v22
	v_rcp_f32_e32 v23, v23
	v_rcp_f32_e32 v16, v16
	v_rcp_f32_e32 v17, v17
	v_rcp_f32_e32 v18, v18
	v_rcp_f32_e32 v19, v19
	v_fma_f32 v214, v20, v160, v214
	v_fma_f32 v215, v21, v161, v215
	v_fma_f32 v216, v22, v162, v216
	v_fma_f32 v217, v23, v163, v217
	v_fma_f32 v218, v16, v164, v218
	v_fma_f32 v219, v17, v165, v219
	v_fma_f32 v220, v18, v166, v220
	v_fma_f32 v221, v19, v167, v221
	v_add_u32_e32 v243, 0x120200, v242
	global_store_dwordx4 v243, v[214:217], s[12:13]
	global_store_dwordx4 v243, v[218:221], s[12:13] offset:16
	s_and_b64 s[4:5], exec, s[16:17]
	s_cbranch_scc0 .Leg_noxb_13
	v_cvt_pk_bf16_f32 v210, v214, v215
	v_cvt_pk_bf16_f32 v211, v216, v217
	v_cvt_pk_bf16_f32 v212, v218, v219
	v_cvt_pk_bf16_f32 v213, v220, v221
	v_lshrrev_b32_e32 v244, 1, v243
	global_store_dwordx4 v244, v[210:213], s[18:19]
; __device__ __forceinline__ f32x4 sig4(f32x4 v) { return (f32x4){sigmoidf_(v[0]), sigmoidf_(v[1]), sigmoidf_(v[2]), sigmoidf_(v[3])}; }
; __device__ __forceinline__ void unpack8(u32x4 w, f32x4& a, f32x4& b) { a = (f32x4){bf_lo(w.x), bf_hi(w.x), bf_lo(w.y), bf_hi(w.y)}; b = (f32x4){bf_lo(w.z), bf_hi(w.z), bf_lo(w.w), bf_hi(w.w)}; }
; __device__ __forceinline__ u32x4 pack8(f32x4 a, f32x4 b) { u32x4 w; w.x = cvt_pk_bf16(a[0], a[1]); w.y = cvt_pk_bf16(a[2], a[3]); w.z = cvt_pk_bf16(b[0], b[1]); w.w = cvt_pk_bf16(b[2], b[3]); return w; }
;     __device__ __forceinline__ void operator()(AccRef acc, const Unit& u, int wr, int wc, int fr, int fq) const {
;     ...
;                 u32x4 pw[4]; f32x4 yv[4][2]; f32x2 st[4];
; #pragma unroll
;                 for (int m = mh; m < mh + 2; ++m) { const int row = row0 + ai * 128 + m * 16; const size_t ro = (size_t)row * DM + c0 + bj * 128;
;                     pw[m] = *(const u32x4*)(PLEB + ro); yv[m][0] = *(const f32x4*)(X + ro); yv[m][1] = *(const f32x4*)(X + ro + 4); st[m] = *(const f32x2*)(stats + 2 * row); }
; #pragma unroll
;                 for (int m = mh; m < mh + 2; ++m) { const int row = row0 + ai * 128 + m * 16; const size_t ro = (size_t)row * DM + c0 + bj * 128;
;                     const float mu = st[m].x * (1.f / DM), var = st[m].y * (1.f / DM) - mu * mu, r = 1.f / sqrtf(var + LN_EPS);
;                     f32x4 p0, p1; unpack8(pw[m], p0, p1);
;                     const f32x4 x0 = (yv[m][0] - mu) * r * g0 + b0, x1 = (yv[m][1] - mu) * r * g1 + b1;
;                     const f32x4 o0 = x0 + sig4((acc[ai][bj][m][0] - mu * cg0) * r + cb0) * p0, o1 = x1 + sig4((acc[ai][bj][m][1] - mu * cg1) * r + cb1) * p1;
;                     *(f32x4*)(X + ro) = o0; *(f32x4*)(X + ro + 4) = o1; if (XB) *(u32x4*)(XB + ro) = pack8(o0, o1); }
;                 asm volatile("" ::: "memory");
.Leg_noxb_13:
	s_waitcnt vmcnt(8)
	v_mul_f32_e32 v168, 0x3a000000, v236
	v_mul_f32_e32 v171, 0x3a000000, v237
	v_fma_f32 v170, -v168, v168, v171
	v_add_f32_e32 v170, 0x3727c5ac, v170
	v_cmp_gt_f32_e32 vcc, s33, v170
	v_mul_f32_e32 v171, 0x4f800000, v170
	s_nop 0
	v_cndmask_b32_e32 v170, v170, v171, vcc
	v_sqrt_f32_e32 v171, v170
	v_lshlrev_b32_e32 v160, 16, v224
	v_and_b32_e32 v161, 0xffff0000, v224
	v_lshlrev_b32_e32 v162, 16, v225
	v_and_b32_e32 v163, 0xffff0000, v225
	v_lshlrev_b32_e32 v164, 16, v226
	v_and_b32_e32 v165, 0xffff0000, v226
	v_lshlrev_b32_e32 v166, 16, v227
	v_and_b32_e32 v167, 0xffff0000, v227
	v_add_u32_e32 v238, -1, v171
	v_fma_f32 v239, -v238, v171, v170
	v_cmp_ge_f32_e64 s[8:9], 0, v239
	v_add_u32_e32 v239, 1, v171
	s_nop 0
	v_cndmask_b32_e64 v238, v171, v238, s[8:9]
	v_fma_f32 v171, -v239, v171, v170
	v_cmp_lt_f32_e64 s[8:9], 0, v171
	s_nop 1
	v_cndmask_b32_e64 v171, v238, v239, s[8:9]
	v_mul_f32_e32 v238, 0x37800000, v171
	v_cndmask_b32_e32 v171, v171, v238, vcc
	v_cmp_class_f32_e32 vcc, v170, v249
	s_nop 1
	v_cndmask_b32_e32 v170, v171, v170, vcc
	v_div_scale_f32 v171, s[4:5], v170, v170, 1.0
	v_rcp_f32_e32 v238, v171
	s_nop 0
	v_fma_f32 v239, -v171, v238, 1.0
	v_fmac_f32_e32 v238, v239, v238
	v_div_scale_f32 v239, vcc, 1.0, v170, 1.0
	v_mul_f32_e32 v240, v239, v238
	v_fma_f32 v241, -v171, v240, v239
	v_fmac_f32_e32 v240, v241, v238
	v_fma_f32 v171, -v171, v240, v239
	v_div_fmas_f32 v171, v171, v238, v240
	v_div_fixup_f32 v169, v171, v170, 1.0
	v_fma_f32 v12, -v144, v168, v12
	v_fma_f32 v13, -v145, v168, v13
	v_fma_f32 v14, -v146, v168, v14
	v_fma_f32 v15, -v147, v168, v15
	v_fma_f32 v8, -v148, v168, v8
	v_fma_f32 v9, -v149, v168, v9
	v_fma_f32 v10, -v150, v168, v10
	v_fma_f32 v11, -v151, v168, v11
	v_sub_f32_e32 v228, v228, v168
	v_sub_f32_e32 v229, v229, v168
	v_sub_f32_e32 v230, v230, v168
	v_sub_f32_e32 v231, v231, v168
	v_sub_f32_e32 v232, v232, v168
	v_sub_f32_e32 v233, v233, v168
	v_sub_f32_e32 v234, v234, v168
	v_sub_f32_e32 v235, v235, v168
	v_fma_f32 v12, v12, v169, v152
	v_fma_f32 v13, v13, v169, v153
	v_fma_f32 v14, v14, v169, v154
	v_fma_f32 v15, v15, v169, v155
	v_fma_f32 v8, v8, v169, v156
	v_fma_f32 v9, v9, v169, v157
	v_fma_f32 v10, v10, v169, v158
	v_fma_f32 v11, v11, v169, v159
	v_mul_f32_e32 v228, v228, v169
	v_mul_f32_e32 v229, v229, v169
	v_mul_f32_e32 v230, v230, v169
	v_mul_f32_e32 v231, v231, v169
	v_mul_f32_e32 v232, v232, v169
	v_mul_f32_e32 v233, v233, v169
	v_mul_f32_e32 v234, v234, v169
	v_mul_f32_e32 v235, v235, v169
	v_mul_f32_e32 v12, 0xbfb8aa3b, v12
	v_mul_f32_e32 v13, 0xbfb8aa3b, v13
	v_mul_f32_e32 v14, 0xbfb8aa3b, v14
	v_mul_f32_e32 v15, 0xbfb8aa3b, v15
	v_mul_f32_e32 v8, 0xbfb8aa3b, v8
	v_mul_f32_e32 v9, 0xbfb8aa3b, v9
	v_mul_f32_e32 v10, 0xbfb8aa3b, v10
	v_mul_f32_e32 v11, 0xbfb8aa3b, v11
	v_fma_f32 v228, v128, v228, v136
	v_fma_f32 v229, v129, v229, v137
	v_fma_f32 v230, v130, v230, v138
	v_fma_f32 v231, v131, v231, v139
	v_fma_f32 v232, v132, v232, v140
	v_fma_f32 v233, v133, v233, v141
	v_fma_f32 v234, v134, v234, v142
	v_fma_f32 v235, v135, v235, v143
	v_exp_f32_e32 v12, v12
	v_exp_f32_e32 v13, v13
	v_exp_f32_e32 v14, v14
	v_exp_f32_e32 v15, v15
	v_exp_f32_e32 v8, v8
	v_exp_f32_e32 v9, v9
	v_exp_f32_e32 v10, v10
	v_exp_f32_e32 v11, v11
	v_add_f32_e32 v12, 1.0, v12
	v_add_f32_e32 v13, 1.0, v13
	v_add_f32_e32 v14, 1.0, v14
	v_add_f32_e32 v15, 1.0, v15
	v_add_f32_e32 v8, 1.0, v8
	v_add_f32_e32 v9, 1.0, v9
	v_add_f32_e32 v10, 1.0, v10
	v_add_f32_e32 v11, 1.0, v11
	v_rcp_f32_e32 v12, v12
	v_rcp_f32_e32 v13, v13
	v_rcp_f32_e32 v14, v14
	v_rcp_f32_e32 v15, v15
	v_rcp_f32_e32 v8, v8
	v_rcp_f32_e32 v9, v9
	v_rcp_f32_e32 v10, v10
	v_rcp_f32_e32 v11, v11
	v_fma_f32 v228, v12, v160, v228
	v_fma_f32 v229, v13, v161, v229
	v_fma_f32 v230, v14, v162, v230
	v_fma_f32 v231, v15, v163, v231
	v_fma_f32 v232, v8, v164, v232
	v_fma_f32 v233, v9, v165, v233
	v_fma_f32 v234, v10, v166, v234
	v_fma_f32 v235, v11, v167, v235
	v_add_u32_e32 v243, 0x140200, v242
	global_store_dwordx4 v243, v[228:231], s[12:13]
	global_store_dwordx4 v243, v[232:235], s[12:13] offset:16
	s_and_b64 s[4:5], exec, s[16:17]
	s_cbranch_scc0 .Leg_noxb_14
	v_cvt_pk_bf16_f32 v224, v228, v229
	v_cvt_pk_bf16_f32 v225, v230, v231
	v_cvt_pk_bf16_f32 v226, v232, v233
	v_cvt_pk_bf16_f32 v227, v234, v235
	v_lshrrev_b32_e32 v244, 1, v243
	global_store_dwordx4 v244, v[224:227], s[18:19]
; __device__ __forceinline__ f32x4 sig4(f32x4 v) { return (f32x4){sigmoidf_(v[0]), sigmoidf_(v[1]), sigmoidf_(v[2]), sigmoidf_(v[3])}; }
; __device__ __forceinline__ void unpack8(u32x4 w, f32x4& a, f32x4& b) { a = (f32x4){bf_lo(w.x), bf_hi(w.x), bf_lo(w.y), bf_hi(w.y)}; b = (f32x4){bf_lo(w.z), bf_hi(w.z), bf_lo(w.w), bf_hi(w.w)}; }
; __device__ __forceinline__ u32x4 pack8(f32x4 a, f32x4 b) { u32x4 w; w.x = cvt_pk_bf16(a[0], a[1]); w.y = cvt_pk_bf16(a[2], a[3]); w.z = cvt_pk_bf16(b[0], b[1]); w.w = cvt_pk_bf16(b[2], b[3]); return w; }
; #define PG8_WAIT_V(n) asm volatile("s_waitcnt vmcnt(" #n ")" ::: "memory")
; #define PG8_BAR __builtin_amdgcn_s_barrier()
; template <class Epi>
; __device__ __forceinline__ void gemm_phase(LAS unsigned char* lds, const Gemm g, const StaticOrder& S, const Epi& E, const int tid) {
;     ...
;     PG8_WAIT_V(0);
;     if (wr == 0) PG8_BAR;
;     PG8_BAR;
;     __device__ __forceinline__ void operator()(AccRef acc, const Unit& u, int wr, int wc, int fr, int fq) const {
;     ...
;                 u32x4 pw[4]; f32x4 yv[4][2]; f32x2 st[4];
; #pragma unroll
;                 for (int m = mh; m < mh + 2; ++m) { const int row = row0 + ai * 128 + m * 16; const size_t ro = (size_t)row * DM + c0 + bj * 128;
;                     pw[m] = *(const u32x4*)(PLEB + ro); yv[m][0] = *(const f32x4*)(X + ro); yv[m][1] = *(const f32x4*)(X + ro + 4); st[m] = *(const f32x2*)(stats + 2 * row); }
; #pragma unroll
;                 for (int m = mh; m < mh + 2; ++m) { const int row = row0 + ai * 128 + m * 16; const size_t ro = (size_t)row * DM + c0 + bj * 128;
;                     const float mu = st[m].x * (1.f / DM), var = st[m].y * (1.f / DM) - mu * mu, r = 1.f / sqrtf(var + LN_EPS);
;                     f32x4 p0, p1; unpack8(pw[m], p0, p1);
;                     const f32x4 x0 = (yv[m][0] - mu) * r * g0 + b0, x1 = (yv[m][1] - mu) * r * g1 + b1;
;                     const f32x4 o0 = x0 + sig4((acc[ai][bj][m][0] - mu * cg0) * r + cb0) * p0, o1 = x1 + sig4((acc[ai][bj][m][1] - mu * cg1) * r + cb1) * p1;
;                     *(f32x4*)(X + ro) = o0; *(f32x4*)(X + ro + 4) = o1; if (XB) *(u32x4*)(XB + ro) = pack8(o0, o1); }
;                 asm volatile("" ::: "memory");
.Leg_noxb_14:
	s_waitcnt vmcnt(4)
	v_mul_f32_e32 v168, 0x3a000000, v208
	v_mul_f32_e32 v171, 0x3a000000, v209
	v_fma_f32 v170, -v168, v168, v171
	v_add_f32_e32 v170, 0x3727c5ac, v170
	v_cmp_gt_f32_e32 vcc, s33, v170
	v_mul_f32_e32 v171, 0x4f800000, v170
	s_nop 0
	v_cndmask_b32_e32 v170, v170, v171, vcc
	v_sqrt_f32_e32 v171, v170
	v_lshlrev_b32_e32 v160, 16, v196
	v_and_b32_e32 v161, 0xffff0000, v196
	v_lshlrev_b32_e32 v162, 16, v197
	v_and_b32_e32 v163, 0xffff0000, v197
	v_lshlrev_b32_e32 v164, 16, v198
	v_and_b32_e32 v165, 0xffff0000, v198
	v_lshlrev_b32_e32 v166, 16, v199
	v_and_b32_e32 v167, 0xffff0000, v199
	v_add_u32_e32 v238, -1, v171
	v_fma_f32 v239, -v238, v171, v170
	v_cmp_ge_f32_e64 s[8:9], 0, v239
	v_add_u32_e32 v239, 1, v171
	s_nop 0
	v_cndmask_b32_e64 v238, v171, v238, s[8:9]
	v_fma_f32 v171, -v239, v171, v170
	v_cmp_lt_f32_e64 s[8:9], 0, v171
	s_nop 1
	v_cndmask_b32_e64 v171, v238, v239, s[8:9]
	v_mul_f32_e32 v238, 0x37800000, v171
	v_cndmask_b32_e32 v171, v171, v238, vcc
	v_cmp_class_f32_e32 vcc, v170, v249
	s_nop 1
	v_cndmask_b32_e32 v170, v171, v170, vcc
	v_div_scale_f32 v171, s[4:5], v170, v170, 1.0
	v_rcp_f32_e32 v238, v171
	s_nop 0
	v_fma_f32 v239, -v171, v238, 1.0
	v_fmac_f32_e32 v238, v239, v238
	v_div_scale_f32 v239, vcc, 1.0, v170, 1.0
	v_mul_f32_e32 v240, v239, v238
	v_fma_f32 v241, -v171, v240, v239
	v_fmac_f32_e32 v240, v241, v238
	v_fma_f32 v171, -v171, v240, v239
	v_div_fmas_f32 v171, v171, v238, v240
	v_div_fixup_f32 v169, v171, v170, 1.0
	v_fma_f32 v4, -v144, v168, v4
	v_fma_f32 v5, -v145, v168, v5
	v_fma_f32 v6, -v146, v168, v6
	v_fma_f32 v7, -v147, v168, v7
	v_fma_f32 v0, -v148, v168, v0
	v_fma_f32 v1, -v149, v168, v1
	v_fma_f32 v2, -v150, v168, v2
	v_fma_f32 v3, -v151, v168, v3
	v_sub_f32_e32 v200, v200, v168
	v_sub_f32_e32 v201, v201, v168
	v_sub_f32_e32 v202, v202, v168
	v_sub_f32_e32 v203, v203, v168
	v_sub_f32_e32 v204, v204, v168
	v_sub_f32_e32 v205, v205, v168
	v_sub_f32_e32 v206, v206, v168
	v_sub_f32_e32 v207, v207, v168
	v_fma_f32 v4, v4, v169, v152
	v_fma_f32 v5, v5, v169, v153
	v_fma_f32 v6, v6, v169, v154
	v_fma_f32 v7, v7, v169, v155
	v_fma_f32 v0, v0, v169, v156
	v_fma_f32 v1, v1, v169, v157
	v_fma_f32 v2, v2, v169, v158
	v_fma_f32 v3, v3, v169, v159
	v_mul_f32_e32 v200, v200, v169
	v_mul_f32_e32 v201, v201, v169
	v_mul_f32_e32 v202, v202, v169
	v_mul_f32_e32 v203, v203, v169
	v_mul_f32_e32 v204, v204, v169
	v_mul_f32_e32 v205, v205, v169
	v_mul_f32_e32 v206, v206, v169
	v_mul_f32_e32 v207, v207, v169
	v_mul_f32_e32 v4, 0xbfb8aa3b, v4
	v_mul_f32_e32 v5, 0xbfb8aa3b, v5
	v_mul_f32_e32 v6, 0xbfb8aa3b, v6
	v_mul_f32_e32 v7, 0xbfb8aa3b, v7
	v_mul_f32_e32 v0, 0xbfb8aa3b, v0
	v_mul_f32_e32 v1, 0xbfb8aa3b, v1
	v_mul_f32_e32 v2, 0xbfb8aa3b, v2
	v_mul_f32_e32 v3, 0xbfb8aa3b, v3
	v_fma_f32 v200, v128, v200, v136
	v_fma_f32 v201, v129, v201, v137
	v_fma_f32 v202, v130, v202, v138
	v_fma_f32 v203, v131, v203, v139
	v_fma_f32 v204, v132, v204, v140
	v_fma_f32 v205, v133, v205, v141
	v_fma_f32 v206, v134, v206, v142
	v_fma_f32 v207, v135, v207, v143
	v_exp_f32_e32 v4, v4
	v_exp_f32_e32 v5, v5
	v_exp_f32_e32 v6, v6
	v_exp_f32_e32 v7, v7
	v_exp_f32_e32 v0, v0
	v_exp_f32_e32 v1, v1
	v_exp_f32_e32 v2, v2
	v_exp_f32_e32 v3, v3
	v_add_f32_e32 v4, 1.0, v4
	v_add_f32_e32 v5, 1.0, v5
	v_add_f32_e32 v6, 1.0, v6
	v_add_f32_e32 v7, 1.0, v7
	v_add_f32_e32 v0, 1.0, v0
	v_add_f32_e32 v1, 1.0, v1
	v_add_f32_e32 v2, 1.0, v2
	v_add_f32_e32 v3, 1.0, v3
	v_rcp_f32_e32 v4, v4
	v_rcp_f32_e32 v5, v5
	v_rcp_f32_e32 v6, v6
	v_rcp_f32_e32 v7, v7
	v_rcp_f32_e32 v0, v0
	v_rcp_f32_e32 v1, v1
	v_rcp_f32_e32 v2, v2
	v_rcp_f32_e32 v3, v3
	v_fma_f32 v200, v4, v160, v200
	v_fma_f32 v201, v5, v161, v201
	v_fma_f32 v202, v6, v162, v202
	v_fma_f32 v203, v7, v163, v203
	v_fma_f32 v204, v0, v164, v204
	v_fma_f32 v205, v1, v165, v205
	v_fma_f32 v206, v2, v166, v206
	v_fma_f32 v207, v3, v167, v207
	v_add_u32_e32 v243, 0x160200, v242
	global_store_dwordx4 v243, v[200:203], s[12:13]
	global_store_dwordx4 v243, v[204:207], s[12:13] offset:16
	s_and_b64 s[4:5], exec, s[16:17]
	s_cbranch_scc0 .Leg_noxb_15
	v_cvt_pk_bf16_f32 v196, v200, v201
	v_cvt_pk_bf16_f32 v197, v202, v203
	v_cvt_pk_bf16_f32 v198, v204, v205
	v_cvt_pk_bf16_f32 v199, v206, v207
	v_lshrrev_b32_e32 v244, 1, v243
	global_store_dwordx4 v244, v[196:199], s[18:19]
.Leg_noxb_15:
	s_branch .LBB0_882
.LBB0_923:
	s_waitcnt vmcnt(0)
	s_cmpk_gt_u32 s2, 0xff
	s_cbranch_scc1 .LBB0_925
	s_barrier

; __device__ __forceinline__ unsigned xb_add(unsigned* p, unsigned v) { return __hip_atomic_fetch_add(p, v, __ATOMIC_RELAXED, __HIP_MEMORY_SCOPE_AGENT); }
; __device__ __forceinline__ void xcd_barrier(const XcdBarrier& b) {
;     asm volatile("s_waitcnt vmcnt(0)" ::: "memory");
;     __syncthreads();
;     if (threadIdx.x == 0) {
;         unsigned long long bar_ = (unsigned long long)b.bar; unsigned bx = b.x;
;         asm volatile("" : "+s"(bar_), "+s"(bx));
;         unsigned* bar = (unsigned*)bar_;
;         __builtin_amdgcn_s_waitcnt(0);
;         unsigned nloc = b.st[0], nx = b.st[1];
;         if (nloc == 0u) { xcd_barrier_complete(bar, bx, nloc, nx); b.st[0] = nloc; b.st[1] = nx; }
;         const unsigned old = xb_add(&bar[XB_XSUB(bx)], 1u);
;         const unsigned gen = old / nloc;
;         if (old + 1u == (gen + 1u) * nloc) {
;             __builtin_amdgcn_fence(__ATOMIC_RELEASE, "agent");
;             asm volatile("s_waitcnt vmcnt(0)" ::: "memory");
;             const unsigned og = xb_add(&bar[XB_TOP], 1u);
;             const unsigned tg = og / nx;
;             if (og + 1u == (tg + 1u) * nx) xb_add(&bar[XB_TOPGEN], 1u);
.LBB0_926:
	s_and_b64 vcc, exec, s[16:17]
	s_cbranch_vccz .LBB0_199
	s_waitcnt vmcnt(0)
	s_waitcnt lgkmcnt(0)
	s_barrier
	s_mov_b64 s[38:39], exec
	v_readlane_b32 s2, v253, 5
	v_readlane_b32 s3, v253, 6
	s_and_b64 s[2:3], s[38:39], s[2:3]
	s_mov_b64 exec, s[2:3]
	s_cbranch_execz .LBB0_198
	s_add_i32 s98, s98, 1
	v_mov_b32_e32 v0, 0x20fa0
	ds_read_b64 v[2:3], v0
	v_readlane_b32 s10, v253, 2
	v_readlane_b32 s11, v253, 3
	v_readlane_b32 s12, v253, 4
	s_lshl_b32 s12, s12, 6
	s_add_i32 s12, s12, 0x3600
	s_add_u32 s14, s10, s12
	s_addc_u32 s15, s11, 0
	s_add_u32 s10, s10, 0x3b00
	s_addc_u32 s11, s11, 0
	v_mov_b64_e32 v[4:5], s[14:15]
	v_mov_b32_e32 v8, 1
	flat_atomic_add v6, v[4:5], v8 sc0
	s_waitcnt vmcnt(0) lgkmcnt(0)
	v_readfirstlane_b32 s12, v6
	v_readfirstlane_b32 s13, v2
	v_readfirstlane_b32 s14, v3
	s_mul_i32 s13, s13, s98
	s_mul_i32 s14, s14, s98
	s_add_i32 s12, s12, 1
	v_mov_b64_e32 v[4:5], s[10:11]
	s_cmp_lg_u32 s12, s13
	s_cbranch_scc1 .Lgb_poll_8
	buffer_wbl2 sc1
	s_waitcnt vmcnt(0) lgkmcnt(0)
	flat_atomic_add v7, v[4:5], v8 sc0
	s_waitcnt vmcnt(0) lgkmcnt(0)

; __device__ __forceinline__ unsigned xb_ld(unsigned* p)              { return __hip_atomic_load(p, __ATOMIC_RELAXED, __HIP_MEMORY_SCOPE_AGENT); }
; __device__ __forceinline__ unsigned xb_add(unsigned* p, unsigned v) { return __hip_atomic_fetch_add(p, v, __ATOMIC_RELAXED, __HIP_MEMORY_SCOPE_AGENT); }
; #define XB_SPIN(cond, bar) do { unsigned _sp = 0; while (cond) { __builtin_amdgcn_s_sleep(1); \
;     if ((++_sp & 255u) == 0u) { if (xb_ld(&(bar)[XB_TMO])) break; if (_sp > XB_SPIN_CAP) { atomicAdd(&(bar)[XB_TMO], 1u); break; } } } } while (0)
; __device__ __forceinline__ void xcd_barrier(const XcdBarrier& b) {
;     ...
;             else XB_SPIN(xb_ld(&bar[XB_TOPGEN]) == tg, bar);
;             __builtin_amdgcn_fence(__ATOMIC_ACQUIRE, "agent");
;             xb_add(&bar[XB_XGEN(bx)], 1u);
;             asm volatile("s_waitcnt vmcnt(0)" ::: "memory");
;         } else {
;             XB_SPIN(xb_ld(&bar[XB_XGEN(bx)]) == gen, bar);
;             __builtin_amdgcn_fence(__ATOMIC_ACQUIRE, "agent");
;             asm volatile("s_waitcnt vmcnt(0)" ::: "memory");
;         }
;     }
;     __syncthreads();
.Lgb_done_8:
	buffer_inv sc1
	s_waitcnt vmcnt(0)
	s_branch .LBB0_198

; __global__ void __launch_bounds__(512, 2) fwd_megakernel(Params p_) {
	.amdhsa_kernel _Z14fwd_megakernel6Params
		.amdhsa_group_segment_fixed_size 0
		.amdhsa_private_segment_fixed_size 0
		.amdhsa_kernarg_size 480
		.amdhsa_user_sgpr_count 2
		.amdhsa_user_sgpr_dispatch_ptr 0
		.amdhsa_user_sgpr_queue_ptr 0
		.amdhsa_user_sgpr_kernarg_segment_ptr 1
		.amdhsa_user_sgpr_dispatch_id 0
		.amdhsa_user_sgpr_kernarg_preload_length 0
		.amdhsa_user_sgpr_kernarg_preload_offset 0
		.amdhsa_user_sgpr_private_segment_size 0
		.amdhsa_uses_dynamic_stack 0
		.amdhsa_enable_private_segment 0
		.amdhsa_system_sgpr_workgroup_id_x 1
		.amdhsa_system_sgpr_workgroup_id_y 0
		.amdhsa_system_sgpr_workgroup_id_z 0
		.amdhsa_system_sgpr_workgroup_info 0
		.amdhsa_system_vgpr_workitem_id 2
		.amdhsa_next_free_vgpr 256
		.amdhsa_next_free_sgpr 100
		.amdhsa_accum_offset 256
		.amdhsa_reserve_vcc 1
		.amdhsa_float_round_mode_32 0
		.amdhsa_float_round_mode_16_64 0
		.amdhsa_float_denorm_mode_32 3
		.amdhsa_float_denorm_mode_16_64 3
		.amdhsa_dx10_clamp 1
		.amdhsa_ieee_mode 1
		.amdhsa_fp16_overflow 0
		.amdhsa_tg_split 0
		.amdhsa_exception_fp_ieee_invalid_op 0
		.amdhsa_exception_fp_denorm_src 0
		.amdhsa_exception_fp_ieee_div_zero 0
		.amdhsa_exception_fp_ieee_overflow 0
		.amdhsa_exception_fp_ieee_underflow 0
		.amdhsa_exception_fp_ieee_inexact 0
		.amdhsa_exception_int_div_zero 0
	.end_amdhsa_kernel

; __global__ void __launch_bounds__(512, 2) fwd_megakernel(Params p_) {
amdhsa.kernels:
  - .agpr_count:     0
    .args:
      - .offset:         0
        .size:           224
        .value_kind:     by_value
      - .offset:         224
        .size:           4
        .value_kind:     hidden_block_count_x
      - .offset:         228
        .size:           4
        .value_kind:     hidden_block_count_y
      - .offset:         232
        .size:           4
        .value_kind:     hidden_block_count_z
      - .offset:         236
        .size:           2
        .value_kind:     hidden_group_size_x
      - .offset:         238
        .size:           2
        .value_kind:     hidden_group_size_y
      - .offset:         240
        .size:           2
        .value_kind:     hidden_group_size_z
      - .offset:         242
        .size:           2
        .value_kind:     hidden_remainder_x
      - .offset:         244
        .size:           2
        .value_kind:     hidden_remainder_y
      - .offset:         246
        .size:           2
        .value_kind:     hidden_remainder_z
      - .offset:         264
        .size:           8
        .value_kind:     hidden_global_offset_x
      - .offset:         272
        .size:           8
        .value_kind:     hidden_global_offset_y
      - .offset:         280
        .size:           8
        .value_kind:     hidden_global_offset_z
      - .offset:         288
        .size:           2
        .value_kind:     hidden_grid_dims
      - .offset:         312
        .size:           8
        .value_kind:     hidden_multigrid_sync_arg
      - .offset:         344
        .size:           4
        .value_kind:     hidden_dynamic_lds_size
    .group_segment_fixed_size: 0
    .kernarg_segment_align: 8
    .kernarg_segment_size: 480
    .language:       OpenCL C
    .language_version:
      - 2
      - 0
    .max_flat_workgroup_size: 512
    .name:           _Z14fwd_megakernel6Params
    .private_segment_fixed_size: 0
    .sgpr_count:     106
    .sgpr_spill_count: 171
    .symbol:         _Z14fwd_megakernel6Params.kd
    .uniform_work_group_size: 1
    .uses_dynamic_stack: false
    .vgpr_count:     256
    .vgpr_spill_count: 0
    .wavefront_size: 64
